# packed producers padded only for op_sel_hi[0]=1: commutative src0/src1 swapped (op_sel_hi[0] becomes 0) and the s_nop pad dropped, 77 sites
# speedup vs baseline: 1.0107x; 1.0107x over previous
.LBB0_277:
	s_andn2_saveexec_b64 s[10:11], s[10:11]
	s_cbranch_execz .LBB0_270
	v_pk_add_f32 v[114:115], v[90:91], v[118:119]
	v_pk_add_f32 v[90:91], v[90:91], v[118:119] neg_lo:[0,1] neg_hi:[0,1]
	v_mul_f32_e32 v42, 0.5, v114
	v_pk_fma_f32 v[116:117], v[70:71], 0, v[70:71] op_sel:[0,0,1] op_sel_hi:[1,0,0] neg_lo:[1,0,0]
	v_mov_b32_e32 v114, v90
	v_pk_mul_f32 v[114:115], v[114:115], s[74:75]
	s_mov_b32 s78, s63
	v_pk_mul_f32 v[118:119], v[116:117], v[114:115] op_sel:[0,1] op_sel_hi:[1,0]
	v_pk_mul_f32 v[114:115], v[116:117], v[114:115]
	s_mov_b32 s79, s50
	v_sub_f32_e32 v90, v114, v115
	v_fma_mixlo_f16 v97, v91, s75, v90
	v_fma_f32 v90, v91, 0.5, -v90
	v_cvt_f16_f32_sdwa v105, -v90 dst_sel:WORD_1 dst_unused:UNUSED_PAD src0_sel:DWORD
	v_pk_add_f32 v[90:91], v[118:119], v[118:119] op_sel:[0,1] op_sel_hi:[0,1]
	s_waitcnt vmcnt(0)
	v_pk_add_f32 v[114:115], v[42:43], v[90:91]
	v_pk_add_f32 v[90:91], v[42:43], v[90:91] op_sel_hi:[0,1] neg_lo:[0,1] neg_hi:[0,1]
	v_cvt_pk_f16_f32 v42, v114, v91
	v_lshlrev_b32_e32 v90, 16, v97
	v_or_b32_sdwa v91, v105, v42 dst_sel:DWORD dst_unused:UNUSED_PAD src0_sel:DWORD src1_sel:WORD_1
	v_or_b32_sdwa v90, v90, v42 dst_sel:DWORD dst_unused:UNUSED_PAD src0_sel:DWORD src1_sel:WORD_0
	global_store_dwordx2 v[44:45], v[90:91], off
	v_pk_add_f32 v[90:91], v[86:87], v[112:113]
	v_pk_add_f32 v[86:87], v[86:87], v[112:113] neg_lo:[0,1] neg_hi:[0,1]
	v_mul_f32_e32 v42, 0.5, v90
	v_mov_b32_e32 v90, v71
	v_mov_b32_e32 v112, v71
	v_mov_b32_e32 v113, v70
	v_pk_fma_f32 v[114:115], v[70:71], 0, v[112:113] op_sel_hi:[1,0,1] neg_lo:[0,0,1] neg_hi:[0,0,1]
	v_pk_fma_f32 v[116:117], v[70:71], 0, v[90:91] op_sel_hi:[1,0,1]
	v_mov_b32_e32 v90, v86
	v_pk_mov_b32 v[114:115], v[114:115], v[116:117] op_sel:[1,0]
	v_pk_mul_f32 v[90:91], v[90:91], s[74:75]
	s_mov_b32 s51, s63
	v_pk_mul_f32 v[116:117], v[114:115], v[90:91] op_sel:[0,1] op_sel_hi:[1,0]
	v_pk_mul_f32 v[90:91], v[114:115], v[90:91]
	v_pk_add_f32 v[114:115], v[80:81], v[110:111]
	v_sub_f32_e32 v86, v90, v91
	v_fma_mixlo_f16 v97, v87, s75, v86
	v_fma_f32 v86, v87, 0.5, -v86
	v_cvt_f16_f32_sdwa v105, -v86 dst_sel:WORD_1 dst_unused:UNUSED_PAD src0_sel:DWORD
	v_pk_add_f32 v[86:87], v[116:117], v[116:117] op_sel:[0,1] op_sel_hi:[0,1]
	v_pk_add_f32 v[90:91], v[42:43], v[86:87]
	v_pk_add_f32 v[86:87], v[42:43], v[86:87] op_sel_hi:[0,1] neg_lo:[0,1] neg_hi:[0,1]
	v_cvt_pk_f16_f32 v42, v90, v87
	v_lshlrev_b32_e32 v86, 16, v97
	v_add_co_u32_e32 v90, vcc, s31, v44
	v_or_b32_sdwa v87, v105, v42 dst_sel:DWORD dst_unused:UNUSED_PAD src0_sel:DWORD src1_sel:WORD_1
	v_or_b32_sdwa v86, v86, v42 dst_sel:DWORD dst_unused:UNUSED_PAD src0_sel:DWORD src1_sel:WORD_0
	v_addc_co_u32_e32 v91, vcc, 0, v45, vcc
	global_store_dwordx2 v[90:91], v[86:87], off offset:-4096
	v_pk_mul_f32 v[86:87], v[112:113], s[68:69]
	v_pk_add_f32 v[80:81], v[80:81], v[110:111] neg_lo:[0,1] neg_hi:[0,1]
	v_mul_f32_e32 v42, 0.5, v114
	v_pk_add_f32 v[110:111], v[40:41], v[86:87] op_sel:[0,1] op_sel_hi:[0,1] neg_lo:[0,1] neg_hi:[0,1]
	v_pk_fma_f32 v[116:117], v[112:113], s[68:69], v[40:41] op_sel_hi:[1,1,0]
	v_mov_b32_e32 v114, v80
	v_mov_b32_e32 v111, v117
	v_pk_mul_f32 v[114:115], v[114:115], s[74:75]
	v_mov_b32_e32 v105, v78
	v_pk_mul_f32 v[116:117], v[110:111], v[114:115] op_sel:[0,1] op_sel_hi:[1,0]
	v_pk_mul_f32 v[114:115], v[110:111], v[114:115]
	s_mov_b32 s45, s41
	v_sub_f32_e32 v40, v114, v115
	v_fma_mixlo_f16 v97, v81, s75, v40
	v_fma_f32 v40, v81, 0.5, -v40
	v_cvt_f16_f32_sdwa v40, -v40 dst_sel:WORD_1 dst_unused:UNUSED_PAD src0_sel:DWORD
	v_pk_add_f32 v[80:81], v[116:117], v[116:117] op_sel:[0,1] op_sel_hi:[0,1]
	v_pk_add_f32 v[114:115], v[42:43], v[80:81]
	v_pk_add_f32 v[80:81], v[42:43], v[80:81] op_sel_hi:[0,1] neg_lo:[0,1] neg_hi:[0,1]
	v_cvt_pk_f16_f32 v42, v114, v81
	v_lshlrev_b32_e32 v80, 16, v97
	v_or_b32_sdwa v81, v40, v42 dst_sel:DWORD dst_unused:UNUSED_PAD src0_sel:DWORD src1_sel:WORD_1
	v_or_b32_sdwa v80, v80, v42 dst_sel:DWORD dst_unused:UNUSED_PAD src0_sel:DWORD src1_sel:WORD_0
	global_store_dwordx2 v[90:91], v[80:81], off
	v_pk_fma_f32 v[80:81], v[112:113], s[68:69], v[86:87] op_sel:[0,0,1] op_sel_hi:[1,1,0] neg_lo:[0,0,1] neg_hi:[0,0,1]
	v_pk_add_f32 v[86:87], v[84:85], v[108:109]
	v_pk_add_f32 v[84:85], v[84:85], v[108:109] neg_lo:[0,1] neg_hi:[0,1]
	v_mul_f32_e32 v40, 0.5, v86
	v_mov_b32_e32 v86, v84
	v_pk_mul_f32 v[86:87], v[86:87], s[74:75]
	v_mov_b32_e32 v81, v110
	v_mov_b32_e32 v111, v80
	v_pk_mul_f32 v[80:81], v[80:81], v[86:87]
	v_pk_mul_f32 v[90:91], v[110:111], v[86:87]
	v_sub_f32_e32 v42, v80, v81
	v_fma_mixlo_f16 v86, v85, s75, v42
	v_fma_f32 v42, v85, 0.5, -v42
	v_cvt_f16_f32_sdwa v42, -v42 dst_sel:WORD_1 dst_unused:UNUSED_PAD src0_sel:DWORD
	v_pk_add_f32 v[80:81], v[90:91], v[90:91] op_sel:[1,0] op_sel_hi:[1,0]
	s_mov_b32 s80, s41
	v_pk_add_f32 v[84:85], v[40:41], v[80:81]
	v_pk_add_f32 v[80:81], v[40:41], v[80:81] op_sel_hi:[0,1] neg_lo:[0,1] neg_hi:[0,1]
	v_cvt_pk_f16_f32 v40, v84, v81
	v_lshlrev_b32_e32 v80, 16, v86
	v_add_co_u32_e32 v84, vcc, s30, v44
	v_or_b32_sdwa v81, v42, v40 dst_sel:DWORD dst_unused:UNUSED_PAD src0_sel:DWORD src1_sel:WORD_1
	v_or_b32_sdwa v80, v80, v40 dst_sel:DWORD dst_unused:UNUSED_PAD src0_sel:DWORD src1_sel:WORD_0
	v_addc_co_u32_e32 v85, vcc, 0, v45, vcc
	global_store_dwordx2 v[84:85], v[80:81], off offset:-4096
	v_mov_b32_e32 v40, v71
	v_pk_mul_f32 v[70:71], v[70:71], s[78:79] op_sel_hi:[0,1]
	v_pk_add_f32 v[80:81], v[76:77], v[106:107]
	v_pk_add_f32 v[76:77], v[76:77], v[106:107] neg_lo:[0,1] neg_hi:[0,1]
	v_mul_f32_e32 v42, 0.5, v80
	v_pk_fma_f32 v[86:87], v[40:41], s[50:51], v[70:71] op_sel_hi:[0,1,1] neg_lo:[0,0,1] neg_hi:[0,0,1]
	v_pk_fma_f32 v[90:91], v[40:41], s[50:51], v[70:71] op_sel_hi:[0,1,1]
	v_mov_b32_e32 v80, v76
	v_mov_b32_e32 v106, v86
	v_mov_b32_e32 v107, v91
	v_pk_mul_f32 v[80:81], v[80:81], s[74:75]
	s_mov_b32 s81, s44
	v_pk_mul_f32 v[108:109], v[106:107], v[80:81] op_sel:[0,1] op_sel_hi:[1,0]
	v_pk_mul_f32 v[80:81], v[106:107], v[80:81]
	s_mov_b32 s65, s67
	v_sub_f32_e32 v40, v80, v81
	v_fma_mixlo_f16 v97, v77, s75, v40
	v_fma_f32 v40, v77, 0.5, -v40
	v_cvt_f16_f32_sdwa v40, -v40 dst_sel:WORD_1 dst_unused:UNUSED_PAD src0_sel:DWORD
	v_pk_add_f32 v[76:77], v[108:109], v[108:109] op_sel:[0,1] op_sel_hi:[0,1]
	v_pk_add_f32 v[80:81], v[42:43], v[76:77]
	v_pk_add_f32 v[76:77], v[42:43], v[76:77] op_sel_hi:[0,1] neg_lo:[0,1] neg_hi:[0,1]
	v_cvt_pk_f16_f32 v42, v80, v77
	v_lshlrev_b32_e32 v76, 16, v97
	v_or_b32_sdwa v77, v40, v42 dst_sel:DWORD dst_unused:UNUSED_PAD src0_sel:DWORD src1_sel:WORD_1
	v_or_b32_sdwa v76, v76, v42 dst_sel:DWORD dst_unused:UNUSED_PAD src0_sel:DWORD src1_sel:WORD_0
	global_store_dwordx2 v[84:85], v[76:77], off
	v_pk_add_f32 v[76:77], v[78:79], v[102:103]
	v_sub_f32_e32 v97, v79, v103
	v_pk_mov_b32 v[78:79], v[70:71], v[102:103] op_sel:[1,0]
	v_mul_f32_e32 v40, 0.5, v77
	v_pk_add_f32 v[78:79], v[104:105], v[78:79] neg_lo:[0,1] neg_hi:[0,1]
	v_mul_f32_e32 v42, 0.5, v76
	v_pk_mul_f32 v[80:81], v[78:79], v[40:41]
	s_mov_b32 s82, s69
	v_mul_f32_e32 v71, v78, v81
	v_fma_f32 v40, -v86, v40, v71
	v_fma_mixlo_f16 v71, v97, s75, v40
	v_fma_f32 v40, v97, 0.5, -v40
	v_cvt_f16_f32_sdwa v40, -v40 dst_sel:WORD_1 dst_unused:UNUSED_PAD src0_sel:DWORD
	v_pk_fma_f32 v[84:85], v[86:87], v[80:81], v[80:81] op_sel:[0,1,0] op_sel_hi:[1,0,1]
	v_lshlrev_b32_e32 v71, 16, v71
	v_pk_add_f32 v[78:79], v[42:43], v[84:85]
	v_fma_f32 v42, v76, 0.5, -v84
	v_cvt_pk_f16_f32 v42, v78, v42
	v_add_co_u32_e32 v78, vcc, s33, v44
	v_or_b32_sdwa v77, v40, v42 dst_sel:DWORD dst_unused:UNUSED_PAD src0_sel:DWORD src1_sel:WORD_1
	v_or_b32_sdwa v76, v71, v42 dst_sel:DWORD dst_unused:UNUSED_PAD src0_sel:DWORD src1_sel:WORD_0
	v_addc_co_u32_e32 v79, vcc, 0, v45, vcc
	global_store_dwordx2 v[78:79], v[76:77], off offset:-4096
	v_pk_add_f32 v[76:77], v[100:101], v[82:83]
	v_pk_add_f32 v[80:81], v[82:83], v[100:101] neg_lo:[0,1] neg_hi:[0,1]
	v_mul_f32_e32 v40, 0.5, v76
	v_mov_b32_e32 v76, v80
	v_pk_mov_b32 v[82:83], v[86:87], v[90:91] op_sel:[1,0]
	v_pk_mul_f32 v[76:77], v[76:77], s[74:75]
	v_mov_b32_e32 v97, v88
	v_pk_mul_f32 v[84:85], v[82:83], v[76:77] op_sel:[0,1] op_sel_hi:[1,0]
	v_pk_mul_f32 v[76:77], v[82:83], v[76:77]
	s_nop 0
	v_sub_f32_e32 v42, v76, v77
	v_fma_mixlo_f16 v71, v81, s75, v42
	v_fma_f32 v42, v81, 0.5, -v42
	v_cvt_f16_f32_sdwa v42, -v42 dst_sel:WORD_1 dst_unused:UNUSED_PAD src0_sel:DWORD
	v_pk_add_f32 v[76:77], v[84:85], v[84:85] op_sel:[0,1] op_sel_hi:[0,1]
	v_pk_add_f32 v[80:81], v[40:41], v[76:77]
	v_pk_add_f32 v[76:77], v[40:41], v[76:77] op_sel_hi:[0,1] neg_lo:[0,1] neg_hi:[0,1]
	v_cvt_pk_f16_f32 v40, v80, v77
	v_lshlrev_b32_e32 v71, 16, v71
	v_or_b32_sdwa v77, v42, v40 dst_sel:DWORD dst_unused:UNUSED_PAD src0_sel:DWORD src1_sel:WORD_1
	v_or_b32_sdwa v76, v71, v40 dst_sel:DWORD dst_unused:UNUSED_PAD src0_sel:DWORD src1_sel:WORD_0
	global_store_dwordx2 v[78:79], v[76:77], off
	v_pk_add_f32 v[76:77], v[92:93], v[88:89]
	v_mov_b32_e32 v71, v92
	v_mul_f32_e32 v40, 0.5, v77
	v_pk_add_f32 v[70:71], v[96:97], v[70:71] neg_lo:[0,1] neg_hi:[0,1]
	v_sub_f32_e32 v84, v89, v93
	v_pk_mul_f32 v[78:79], v[70:71], v[40:41]
	v_mul_f32_e32 v42, 0.5, v76
	v_mul_f32_e32 v70, v70, v79
	v_fma_f32 v40, -v87, v40, v70
	v_fma_mixlo_f16 v77, v84, s75, v40
	v_fma_f32 v40, v84, 0.5, -v40
	v_cvt_f16_f32_sdwa v40, -v40 dst_sel:WORD_1 dst_unused:UNUSED_PAD src0_sel:DWORD
	v_pk_fma_f32 v[80:81], v[82:83], v[78:79], v[78:79] op_sel:[0,1,0] op_sel_hi:[1,0,1]
	s_nop 0
	v_pk_add_f32 v[70:71], v[42:43], v[80:81]
	v_fma_f32 v42, v76, 0.5, -v80
	v_cvt_pk_f16_f32 v42, v70, v42
	v_lshlrev_b32_e32 v70, 16, v77
	v_or_b32_sdwa v71, v40, v42 dst_sel:DWORD dst_unused:UNUSED_PAD src0_sel:DWORD src1_sel:WORD_1
	v_sub_f32_e32 v40, v98, v99
	v_or_b32_sdwa v70, v70, v42 dst_sel:DWORD dst_unused:UNUSED_PAD src0_sel:DWORD src1_sel:WORD_0
	v_add_co_u32_e32 v76, vcc, s34, v44
	v_cvt_f16_f32_sdwa v42, -v95 dst_sel:WORD_1 dst_unused:UNUSED_PAD src0_sel:DWORD
	v_cvt_f16_f32_sdwa v40, v40 dst_sel:WORD_1 dst_unused:UNUSED_PAD src0_sel:DWORD
	v_addc_co_u32_e32 v77, vcc, 0, v45, vcc
	global_store_dwordx2 v[76:77], v[70:71], off offset:-4096
	v_pk_add_f32 v[70:71], v[98:99], v[98:99] op_sel:[0,1] op_sel_hi:[1,0]
	s_nop 0
	v_cvt_pk_f16_f32 v70, v70, v94
	v_or_b32_sdwa v71, v42, v70 dst_sel:DWORD dst_unused:UNUSED_PAD src0_sel:DWORD src1_sel:WORD_1
	v_or_b32_sdwa v70, v40, v70 dst_sel:DWORD dst_unused:UNUSED_PAD src0_sel:DWORD src1_sel:WORD_0
	global_store_dwordx2 v[76:77], v[70:71], off
	v_pk_add_f32 v[70:71], v[64:65], v[52:53]
	v_pk_add_f32 v[52:53], v[64:65], v[52:53] neg_lo:[0,1] neg_hi:[0,1]
	v_mul_f32_e32 v40, 0.5, v70
	v_mov_b32_e32 v70, v52
	v_pk_mul_f32 v[64:65], v[70:71], s[74:75]
	s_nop 0
	v_pk_mul_f32 v[70:71], v[64:65], s[44:45]
	v_pk_mul_f32 v[64:65], v[64:65], s[80:81]
	s_mov_b32 s80, s67
	v_sub_f32_e32 v42, v64, v65
	v_fma_mixlo_f16 v76, v53, s75, v42
	v_fma_f32 v42, v53, 0.5, -v42
	v_cvt_f16_f32_sdwa v42, -v42 dst_sel:WORD_1 dst_unused:UNUSED_PAD src0_sel:DWORD
	v_pk_add_f32 v[52:53], v[70:71], v[70:71] op_sel:[1,0] op_sel_hi:[1,0]
	s_mov_b32 s81, s64
	v_pk_add_f32 v[64:65], v[40:41], v[52:53]
	v_pk_add_f32 v[52:53], v[40:41], v[52:53] op_sel_hi:[0,1] neg_lo:[0,1] neg_hi:[0,1]
	v_cvt_pk_f16_f32 v40, v64, v53
	v_lshlrev_b32_e32 v52, 16, v76
	v_add_co_u32_e32 v64, vcc, s35, v44
	v_or_b32_sdwa v53, v42, v40 dst_sel:DWORD dst_unused:UNUSED_PAD src0_sel:DWORD src1_sel:WORD_1
	v_or_b32_sdwa v52, v52, v40 dst_sel:DWORD dst_unused:UNUSED_PAD src0_sel:DWORD src1_sel:WORD_0
	v_addc_co_u32_e32 v65, vcc, 0, v45, vcc
	global_store_dwordx2 v[64:65], v[52:53], off offset:-4096
	v_pk_add_f32 v[52:53], v[72:73], v[66:67]
	v_pk_add_f32 v[66:67], v[72:73], v[66:67] neg_lo:[0,1] neg_hi:[0,1]
	v_mul_f32_e32 v40, 0.5, v52
	v_mov_b32_e32 v52, v66
	v_pk_mul_f32 v[52:53], v[52:53], s[74:75]
	s_nop 0
	v_pk_mul_f32 v[70:71], v[52:53], s[78:79]
	v_pk_mul_f32 v[52:53], v[52:53], s[50:51]
	s_nop 0
	v_sub_f32_e32 v42, v52, v53
	v_fma_mixlo_f16 v72, v67, s75, v42
	v_fma_f32 v42, v67, 0.5, -v42
	v_cvt_f16_f32_sdwa v42, -v42 dst_sel:WORD_1 dst_unused:UNUSED_PAD src0_sel:DWORD
	v_pk_add_f32 v[52:53], v[70:71], v[70:71] op_sel:[1,0] op_sel_hi:[1,0]
	s_nop 0
	v_pk_add_f32 v[66:67], v[40:41], v[52:53]
	v_pk_add_f32 v[52:53], v[40:41], v[52:53] op_sel_hi:[0,1] neg_lo:[0,1] neg_hi:[0,1]
	v_cvt_pk_f16_f32 v40, v66, v53
	v_lshlrev_b32_e32 v52, 16, v72
	v_or_b32_sdwa v53, v42, v40 dst_sel:DWORD dst_unused:UNUSED_PAD src0_sel:DWORD src1_sel:WORD_1
	v_or_b32_sdwa v52, v52, v40 dst_sel:DWORD dst_unused:UNUSED_PAD src0_sel:DWORD src1_sel:WORD_0
	global_store_dwordx2 v[64:65], v[52:53], off
	v_pk_add_f32 v[52:53], v[54:55], v[58:59]
	v_pk_add_f32 v[54:55], v[54:55], v[58:59] neg_lo:[0,1] neg_hi:[0,1]
	v_mul_f32_e32 v40, 0.5, v52
	v_mov_b32_e32 v52, v54
	v_pk_mul_f32 v[52:53], v[52:53], s[74:75]
	s_nop 0
	v_pk_mul_f32 v[58:59], v[52:53], s[80:81]
	v_pk_mul_f32 v[52:53], v[52:53], s[64:65]
	s_nop 0
	v_sub_f32_e32 v42, v52, v53
	v_fma_mixlo_f16 v64, v55, s75, v42
	v_fma_f32 v42, v55, 0.5, -v42
	v_cvt_f16_f32_sdwa v42, -v42 dst_sel:WORD_1 dst_unused:UNUSED_PAD src0_sel:DWORD
	v_pk_add_f32 v[52:53], v[58:59], v[58:59] op_sel:[1,0] op_sel_hi:[1,0]
	v_pk_add_f32 v[58:59], v[74:75], v[68:69] neg_lo:[0,1] neg_hi:[0,1]
	v_pk_add_f32 v[54:55], v[40:41], v[52:53]
	v_pk_add_f32 v[52:53], v[40:41], v[52:53] op_sel_hi:[0,1] neg_lo:[0,1] neg_hi:[0,1]
	v_cvt_pk_f16_f32 v40, v54, v53
	v_lshlrev_b32_e32 v52, 16, v64
	v_add_co_u32_e32 v54, vcc, s39, v44
	v_or_b32_sdwa v53, v42, v40 dst_sel:DWORD dst_unused:UNUSED_PAD src0_sel:DWORD src1_sel:WORD_1
	v_or_b32_sdwa v52, v52, v40 dst_sel:DWORD dst_unused:UNUSED_PAD src0_sel:DWORD src1_sel:WORD_0
	v_addc_co_u32_e32 v55, vcc, 0, v45, vcc
	global_store_dwordx2 v[54:55], v[52:53], off offset:-4096
	v_pk_add_f32 v[52:53], v[74:75], v[68:69]
	s_nop 0
	v_mul_f32_e32 v40, 0.5, v52
	v_mov_b32_e32 v52, v58
	v_pk_mul_f32 v[52:53], v[52:53], s[74:75]
	s_nop 0
	v_pk_mul_f32 v[52:53], s[82:83], v[52:53] op_sel_hi:[0,1]
	v_sub_f32_e32 v42, v52, v53
	v_fma_mixlo_f16 v64, v59, s75, v42
	v_fma_f32 v42, v59, 0.5, -v42
	v_cvt_f16_f32_sdwa v42, -v42 dst_sel:WORD_1 dst_unused:UNUSED_PAD src0_sel:DWORD
	v_pk_add_f32 v[52:53], v[52:53], v[52:53] op_sel:[1,0] op_sel_hi:[1,0]
	s_nop 0
	v_pk_add_f32 v[58:59], v[40:41], v[52:53]
	v_pk_add_f32 v[52:53], v[40:41], v[52:53] op_sel_hi:[0,1] neg_lo:[0,1] neg_hi:[0,1]
	v_cvt_pk_f16_f32 v40, v58, v53
	v_lshlrev_b32_e32 v52, 16, v64
	v_or_b32_sdwa v53, v42, v40 dst_sel:DWORD dst_unused:UNUSED_PAD src0_sel:DWORD src1_sel:WORD_1
	v_or_b32_sdwa v52, v52, v40 dst_sel:DWORD dst_unused:UNUSED_PAD src0_sel:DWORD src1_sel:WORD_0
	global_store_dwordx2 v[54:55], v[52:53], off
	v_pk_add_f32 v[52:53], v[56:57], v[48:49]
	v_pk_add_f32 v[48:49], v[56:57], v[48:49] neg_lo:[0,1] neg_hi:[0,1]
	v_mul_f32_e32 v40, 0.5, v52
	v_mov_b32_e32 v52, v48
	v_pk_mul_f32 v[52:53], v[52:53], s[74:75]
	s_nop 0
	v_pk_mul_f32 v[54:55], v[52:53], s[64:65]
	v_pk_mul_f32 v[52:53], v[52:53], s[80:81]
	s_nop 0
	v_sub_f32_e32 v42, v52, v53
	v_fma_mixlo_f16 v56, v49, s75, v42
	v_fma_f32 v42, v49, 0.5, -v42
	v_cvt_f16_f32_sdwa v42, -v42 dst_sel:WORD_1 dst_unused:UNUSED_PAD src0_sel:DWORD
	v_pk_add_f32 v[48:49], v[54:55], v[54:55] op_sel:[1,0] op_sel_hi:[1,0]
	v_pk_add_f32 v[54:55], v[60:61], v[62:63] neg_lo:[0,1] neg_hi:[0,1]
	v_pk_add_f32 v[52:53], v[40:41], v[48:49]
	v_pk_add_f32 v[48:49], v[40:41], v[48:49] op_sel_hi:[0,1] neg_lo:[0,1] neg_hi:[0,1]
	v_cvt_pk_f16_f32 v40, v52, v49
	v_lshlrev_b32_e32 v48, 16, v56
	v_add_co_u32_e32 v52, vcc, s43, v44
	v_or_b32_sdwa v49, v42, v40 dst_sel:DWORD dst_unused:UNUSED_PAD src0_sel:DWORD src1_sel:WORD_1
	v_or_b32_sdwa v48, v48, v40 dst_sel:DWORD dst_unused:UNUSED_PAD src0_sel:DWORD src1_sel:WORD_0
	v_addc_co_u32_e32 v53, vcc, 0, v45, vcc
	global_store_dwordx2 v[52:53], v[48:49], off offset:-4096
	v_pk_add_f32 v[48:49], v[62:63], v[60:61]
	s_nop 0
	v_mul_f32_e32 v40, 0.5, v48
	v_mov_b32_e32 v48, v54
	v_pk_mul_f32 v[48:49], v[48:49], s[74:75]
	s_nop 0
	v_pk_mul_f32 v[56:57], v[48:49], s[50:51]
	v_pk_mul_f32 v[48:49], v[48:49], s[78:79]
	s_mov_b32 s78, s41
	v_sub_f32_e32 v42, v48, v49
	v_pk_add_f32 v[48:49], v[56:57], v[56:57] op_sel:[1,0] op_sel_hi:[1,0]
	v_fma_mixlo_f16 v58, v55, s75, v42
	v_fma_f32 v42, v55, 0.5, -v42
	v_pk_add_f32 v[54:55], v[40:41], v[48:49]
	v_pk_add_f32 v[48:49], v[40:41], v[48:49] op_sel_hi:[0,1] neg_lo:[0,1] neg_hi:[0,1]
	v_cvt_pk_f16_f32 v40, v54, v49
	v_pk_add_f32 v[48:49], v[46:47], v[50:51]
	v_pk_add_f32 v[46:47], v[46:47], v[50:51] neg_lo:[0,1] neg_hi:[0,1]
	v_mov_b32_e32 v50, v48
	v_mov_b32_e32 v51, v47
	v_mov_b32_e32 v47, v49
	v_pk_mul_f32 v[46:47], v[46:47], s[74:75]
	v_cvt_f16_f32_sdwa v42, -v42 dst_sel:WORD_1 dst_unused:UNUSED_PAD src0_sel:DWORD
	v_pk_mul_f32 v[48:49], v[46:47], s[44:45] op_sel_hi:[1,0]
	v_lshlrev_b32_e32 v56, 16, v58
	v_pk_fma_f32 v[54:55], v[46:47], s[78:79], v[48:49] op_sel:[0,0,1] op_sel_hi:[1,0,0] neg_hi:[1,0,0]
	s_nop 0
	s_nop 0
	s_nop 0
	v_pk_fma_f32 v[46:47], v[50:51], 0.5, v[54:55] op_sel_hi:[1,0,1]
	v_pk_fma_f32 v[116:117], v[50:51], 0.5, v[54:55] op_sel_hi:[1,0,1] neg_lo:[0,0,1] neg_hi:[0,0,1]
	v_cvt_f16_f32_e32 v48, v46
	v_cvt_f16_f32_sdwa v49, v47 dst_sel:WORD_1 dst_unused:UNUSED_PAD src0_sel:DWORD
	v_or_b32_sdwa v47, v42, v40 dst_sel:DWORD dst_unused:UNUSED_PAD src0_sel:DWORD src1_sel:WORD_1
	v_or_b32_sdwa v46, v56, v40 dst_sel:DWORD dst_unused:UNUSED_PAD src0_sel:DWORD src1_sel:WORD_0
	global_store_dwordx2 v[52:53], v[46:47], off
	v_or_b32_e32 v114, v49, v48
	s_branch .LBB0_270

.LBB0_428:
	s_ashr_i32 s17, s16, 31
	s_lshl_b64 s[6:7], s[16:17], 2
	s_add_u32 s6, s48, s6
	s_addc_u32 s7, s49, s7
	global_load_dwordx2 v[40:41], v151, s[6:7]
	s_waitcnt vmcnt(0)
	v_cvt_f32_f16_e32 v36, v10
	v_cvt_f32_f16_sdwa v42, v10 dst_sel:DWORD dst_unused:UNUSED_PAD src0_sel:WORD_1
	v_cvt_f32_f16_e32 v43, v11
	v_cvt_f32_f16_e32 v45, v12
	v_cvt_f32_f16_sdwa v46, v12 dst_sel:DWORD dst_unused:UNUSED_PAD src0_sel:WORD_1
	v_cvt_f32_f16_e32 v47, v13
	v_cvt_f32_f16_sdwa v12, v13 dst_sel:DWORD dst_unused:UNUSED_PAD src0_sel:WORD_1
	v_cvt_f32_f16_e32 v13, v30
	v_cvt_f32_f16_sdwa v50, v26 dst_sel:DWORD dst_unused:UNUSED_PAD src0_sel:WORD_1
	v_cvt_f32_f16_e32 v51, v27
	v_cvt_f32_f16_sdwa v44, v11 dst_sel:DWORD dst_unused:UNUSED_PAD src0_sel:WORD_1
	v_cvt_f32_f16_sdwa v48, v30 dst_sel:DWORD dst_unused:UNUSED_PAD src0_sel:WORD_1
	v_cvt_f32_f16_e32 v49, v31
	v_cvt_f32_f16_sdwa v30, v31 dst_sel:DWORD dst_unused:UNUSED_PAD src0_sel:WORD_1
	v_cvt_f32_f16_e32 v31, v32
	v_cvt_f32_f16_sdwa v11, v33 dst_sel:DWORD dst_unused:UNUSED_PAD src0_sel:WORD_1
	v_cvt_f32_f16_sdwa v32, v32 dst_sel:DWORD dst_unused:UNUSED_PAD src0_sel:WORD_1
	v_cvt_f32_f16_e32 v33, v33
	v_cvt_f32_f16_sdwa v26, v27 dst_sel:DWORD dst_unused:UNUSED_PAD src0_sel:WORD_1
	v_cvt_f32_f16_e32 v27, v28
	v_cvt_f32_f16_sdwa v52, v28 dst_sel:DWORD dst_unused:UNUSED_PAD src0_sel:WORD_1
	v_cvt_f32_f16_e32 v53, v29
	v_cvt_f32_f16_e32 v28, v22
	v_cvt_f32_f16_sdwa v54, v22 dst_sel:DWORD dst_unused:UNUSED_PAD src0_sel:WORD_1
	v_cvt_f32_f16_e32 v55, v23
	v_cvt_f32_f16_sdwa v22, v23 dst_sel:DWORD dst_unused:UNUSED_PAD src0_sel:WORD_1
	v_cvt_f32_f16_e32 v23, v24
	v_cvt_f32_f16_sdwa v56, v24 dst_sel:DWORD dst_unused:UNUSED_PAD src0_sel:WORD_1
	v_cvt_f32_f16_e32 v57, v25
	v_cvt_f32_f16_sdwa v29, v29 dst_sel:DWORD dst_unused:UNUSED_PAD src0_sel:WORD_1
	v_cvt_f32_f16_sdwa v25, v25 dst_sel:DWORD dst_unused:UNUSED_PAD src0_sel:WORD_1
	v_cvt_f32_f16_e32 v24, v38
	v_cvt_f32_f16_sdwa v60, v19 dst_sel:DWORD dst_unused:UNUSED_PAD src0_sel:WORD_1
	v_cvt_f32_f16_e32 v61, v20
	v_cvt_f32_f16_e32 v38, v18
	v_cvt_f32_f16_e32 v59, v19
	v_mul_f32_e32 v19, 0x3b800000, v36
	v_pk_mul_f32 v[42:43], v[42:43], s[24:25] op_sel_hi:[1,0]
	v_pk_mul_f32 v[12:13], v[12:13], s[24:25] op_sel_hi:[1,0]
	v_pk_mul_f32 v[50:51], v[50:51], s[24:25] op_sel_hi:[1,0]
	v_pk_mul_f32 v[44:45], v[44:45], s[24:25] op_sel_hi:[1,0]
	v_pk_mul_f32 v[46:47], v[46:47], s[24:25] op_sel_hi:[1,0]
	v_pk_mul_f32 v[48:49], v[48:49], s[24:25] op_sel_hi:[1,0]
	v_pk_mul_f32 v[30:31], v[30:31], s[24:25] op_sel_hi:[1,0]
	v_mul_f32_e32 v11, 0x3b800000, v11
	v_pk_mul_f32 v[32:33], v[32:33], s[24:25] op_sel_hi:[1,0]
	v_pk_mul_f32 v[26:27], v[26:27], s[24:25] op_sel_hi:[1,0]
	v_pk_mul_f32 v[52:53], v[52:53], s[24:25] op_sel_hi:[1,0]
	v_pk_mul_f32 v[54:55], v[54:55], s[24:25] op_sel_hi:[1,0]
	v_pk_mul_f32 v[22:23], v[22:23], s[24:25] op_sel_hi:[1,0]
	v_pk_mul_f32 v[56:57], v[56:57], s[24:25] op_sel_hi:[1,0]
	ds_write2_b32 v131, v42, v43 offset0:1 offset1:2
	ds_write2_b32 v131, v44, v45 offset0:3 offset1:4
	ds_write2_b32 v131, v46, v47 offset0:5 offset1:6
	ds_write2_b32 v131, v12, v13 offset0:7 offset1:8
	ds_write2_b32 v131, v48, v49 offset0:9 offset1:10
	ds_write2_b32 v131, v30, v31 offset0:11 offset1:12
	ds_write2_b32 v131, v32, v33 offset0:13 offset1:14
	v_pk_mov_b32 v[12:13], v[50:51], v[50:51] op_sel:[1,0]
	v_pk_mul_f32 v[28:29], v[28:29], s[24:25] op_sel_hi:[1,0]
	v_pk_mul_f32 v[24:25], v[24:25], s[24:25] op_sel_hi:[1,0]
	v_pk_mov_b32 v[26:27], v[26:27], v[26:27] op_sel:[1,0]
	v_pk_mov_b32 v[30:31], v[52:53], v[52:53] op_sel:[1,0]
	v_pk_mov_b32 v[32:33], v[54:55], v[54:55] op_sel:[1,0]
	v_pk_mov_b32 v[22:23], v[22:23], v[22:23] op_sel:[1,0]
	v_pk_mov_b32 v[42:43], v[56:57], v[56:57] op_sel:[1,0]
	v_cvt_f32_f16_sdwa v58, v18 dst_sel:DWORD dst_unused:UNUSED_PAD src0_sel:WORD_1
	v_mul_f32_e32 v36, 0x3b800000, v38
	s_mov_b32 s6, s65
	v_pk_mul_f32 v[58:59], v[58:59], s[24:25] op_sel_hi:[1,0]
	v_fma_mix_f32 v10, v10, s24, v40 op_sel_hi:[1,0,0]
	s_nop 0
	v_cndmask_b32_e64 v10, v19, v10, s[4:5]
	ds_write2_b32 v131, v10, v11 offset1:15
	ds_write_b64 v132, v[12:13] offset:32824
	ds_write_b64 v133, v[26:27] offset:32824
	ds_write_b64 v134, v[30:31] offset:32824
	ds_write_b64 v135, v[28:29] offset:32824
	ds_write_b64 v136, v[32:33] offset:32824
	ds_write_b64 v137, v[22:23] offset:32824
	ds_write_b64 v138, v[42:43] offset:32824
	ds_write_b64 v139, v[24:25] offset:32824
	v_cvt_f32_f16_sdwa v10, v20 dst_sel:DWORD dst_unused:UNUSED_PAD src0_sel:WORD_1
	v_cvt_f32_f16_e32 v11, v21
	v_pk_mul_f32 v[12:13], v[60:61], s[24:25] op_sel_hi:[1,0]
	v_fma_mix_f32 v18, v18, s24, v41 op_sel_hi:[1,0,0]
	ds_write2_b32 v140, v12, v13 offset0:3 offset1:4
	v_cvt_f32_f16_sdwa v12, v21 dst_sel:DWORD dst_unused:UNUSED_PAD src0_sel:WORD_1
	v_cvt_f32_f16_e32 v13, v14
	v_cndmask_b32_e64 v36, v36, v18, s[4:5]
	v_cvt_f32_f16_sdwa v18, v14 dst_sel:DWORD dst_unused:UNUSED_PAD src0_sel:WORD_1
	v_cvt_f32_f16_e32 v19, v15
	v_pk_mul_f32 v[10:11], v[10:11], s[24:25] op_sel_hi:[1,0]
	ds_write2_b32 v140, v10, v11 offset0:5 offset1:6
	v_pk_mul_f32 v[10:11], v[12:13], s[24:25] op_sel_hi:[1,0]
	ds_write2_b32 v140, v10, v11 offset0:7 offset1:8
	v_pk_mul_f32 v[10:11], v[18:19], s[24:25] op_sel_hi:[1,0]
	ds_write2_b32 v140, v10, v11 offset0:9 offset1:10
	v_cvt_f32_f16_sdwa v10, v15 dst_sel:DWORD dst_unused:UNUSED_PAD src0_sel:WORD_1
	v_cvt_f32_f16_e32 v11, v16
	v_cvt_f32_f16_sdwa v12, v16 dst_sel:DWORD dst_unused:UNUSED_PAD src0_sel:WORD_1
	v_cvt_f32_f16_e32 v13, v17
	v_cvt_f32_f16_sdwa v14, v17 dst_sel:DWORD dst_unused:UNUSED_PAD src0_sel:WORD_1
	v_pk_mul_f32 v[10:11], v[10:11], s[24:25] op_sel_hi:[1,0]
	ds_write2_b32 v140, v10, v11 offset0:11 offset1:12
	v_pk_mul_f32 v[10:11], v[12:13], s[24:25] op_sel_hi:[1,0]
	ds_write2_b32 v140, v10, v11 offset0:13 offset1:14
	v_cvt_f32_f16_sdwa v10, v6 dst_sel:DWORD dst_unused:UNUSED_PAD src0_sel:WORD_1
	v_cvt_f32_f16_e32 v11, v7
	v_cvt_f32_f16_sdwa v6, v7 dst_sel:DWORD dst_unused:UNUSED_PAD src0_sel:WORD_1
	v_cvt_f32_f16_e32 v7, v8
	v_mul_f32_e32 v14, 0x3b800000, v14
	v_pk_mul_f32 v[10:11], v[10:11], s[24:25] op_sel_hi:[1,0]
	ds_write2_b32 v140, v58, v59 offset0:1 offset1:2
	v_pk_mov_b32 v[10:11], v[10:11], v[10:11] op_sel:[1,0]
	ds_write2_b32 v140, v36, v14 offset1:15
	ds_write_b64 v141, v[10:11] offset:32824
	v_cvt_f32_f16_sdwa v10, v8 dst_sel:DWORD dst_unused:UNUSED_PAD src0_sel:WORD_1
	v_cvt_f32_f16_e32 v11, v9
	v_pk_mul_f32 v[6:7], v[6:7], s[24:25] op_sel_hi:[1,0]
	s_nop 0
	v_pk_mov_b32 v[6:7], v[6:7], v[6:7] op_sel:[1,0]
	ds_write_b64 v142, v[6:7] offset:32824
	v_cvt_f32_f16_sdwa v7, v9 dst_sel:DWORD dst_unused:UNUSED_PAD src0_sel:WORD_1
	v_pk_mul_f32 v[8:9], v[10:11], s[24:25] op_sel_hi:[1,0]
	v_cvt_f32_f16_e32 v6, v2
	v_pk_mov_b32 v[8:9], v[8:9], v[8:9] op_sel:[1,0]
	ds_write_b64 v143, v[8:9] offset:32824
	v_cvt_f32_f16_sdwa v8, v2 dst_sel:DWORD dst_unused:UNUSED_PAD src0_sel:WORD_1
	v_cvt_f32_f16_e32 v9, v3
	v_cvt_f32_f16_sdwa v2, v3 dst_sel:DWORD dst_unused:UNUSED_PAD src0_sel:WORD_1
	v_cvt_f32_f16_e32 v3, v4
	v_pk_mul_f32 v[6:7], v[6:7], s[24:25] op_sel_hi:[1,0]
	ds_write_b64 v144, v[6:7] offset:32824
	v_pk_mul_f32 v[6:7], v[8:9], s[24:25] op_sel_hi:[1,0]
	v_pk_mul_f32 v[2:3], v[2:3], s[24:25] op_sel_hi:[1,0]
	v_pk_mov_b32 v[6:7], v[6:7], v[6:7] op_sel:[1,0]
	ds_write_b64 v145, v[6:7] offset:32824
	v_pk_mov_b32 v[2:3], v[2:3], v[2:3] op_sel:[1,0]
	v_cvt_f32_f16_sdwa v6, v4 dst_sel:DWORD dst_unused:UNUSED_PAD src0_sel:WORD_1
	v_cvt_f32_f16_e32 v7, v5
	ds_write_b64 v148, v[2:3] offset:32824
	v_cvt_f32_f16_sdwa v3, v5 dst_sel:DWORD dst_unused:UNUSED_PAD src0_sel:WORD_1
	v_cvt_f32_f16_e32 v2, v39
	v_pk_mul_f32 v[4:5], v[6:7], s[24:25] op_sel_hi:[1,0]
	v_pk_mul_f32 v[2:3], v[2:3], s[24:25] op_sel_hi:[1,0]
	v_pk_mov_b32 v[4:5], v[4:5], v[4:5] op_sel:[1,0]
	ds_write_b64 v149, v[4:5] offset:32824
	ds_write_b64 v150, v[2:3] offset:32824
	v_mov_b32_e32 v2, v130
	s_waitcnt lgkmcnt(0)
	s_barrier
	s_nop 0
	v_and_b32_e32 v3, 0xff, v2
	v_lshlrev_b32_e32 v4, 5, v2
	v_and_or_b32 v3, v4, s29, v3
	v_ashrrev_i32_e32 v4, 5, v3
	v_lshlrev_b32_e32 v3, 3, v3
	v_lshlrev_b32_e32 v6, 3, v4
	v_add3_u32 v36, 0, v3, v6
	ds_read_b64 v[154:155], v36
	ds_read_b64 v[156:157], v36 offset:2112
	ds_read_b64 v[158:159], v36 offset:4224
	ds_read_b64 v[160:161], v36 offset:6336
	ds_read_b64 v[162:163], v36 offset:8448
	ds_read_b64 v[164:165], v36 offset:10560
	ds_read_b64 v[166:167], v36 offset:12672
	ds_read_b64 v[168:169], v36 offset:14784
	ds_read_b64 v[170:171], v36 offset:16896
	ds_read_b64 v[172:173], v36 offset:19008
	ds_read_b64 v[174:175], v36 offset:21120
	ds_read_b64 v[176:177], v36 offset:23232
	ds_read_b64 v[178:179], v36 offset:25344
	ds_read_b64 v[180:181], v36 offset:27456
	ds_read_b64 v[182:183], v36 offset:29568
	ds_read_b64 v[184:185], v36 offset:31680
	ds_read_b64 v[186:187], v36 offset:33792
	ds_read_b64 v[188:189], v36 offset:35904
	ds_read_b64 v[190:191], v36 offset:38016
	ds_read_b64 v[192:193], v36 offset:40128
	ds_read_b64 v[194:195], v36 offset:42240
	ds_read_b64 v[196:197], v36 offset:44352
	ds_read_b64 v[198:199], v36 offset:46464
	ds_read_b64 v[204:205], v36 offset:48576
	ds_read_b64 v[206:207], v36 offset:50688
	ds_read_b64 v[208:209], v36 offset:52800
	ds_read_b64 v[210:211], v36 offset:54912
	ds_read_b64 v[212:213], v36 offset:57024
	ds_read_b64 v[214:215], v36 offset:59136
	ds_read_b64 v[216:217], v36 offset:61248
	ds_read_b64 v[218:219], v36 offset:63360
	ds_read_b64 v[220:221], v36 offset:65472
	s_waitcnt lgkmcnt(14)
	v_pk_add_f32 v[222:223], v[154:155], v[186:187]
	v_pk_add_f32 v[154:155], v[154:155], v[186:187] neg_lo:[0,1] neg_hi:[0,1]
	v_pk_add_f32 v[186:187], v[156:157], v[188:189]
	v_pk_add_f32 v[156:157], v[156:157], v[188:189] neg_lo:[0,1] neg_hi:[0,1]
	v_cvt_f32_ubyte0_e32 v2, v2
	v_pk_mul_f32 v[188:189], v[156:157], s[40:41]
	v_mul_f32_e32 v5, 0x39000000, v2
	v_pk_fma_f32 v[156:157], v[156:157], s[36:37], v[188:189] op_sel:[0,0,1] op_sel_hi:[1,0,0]
	s_waitcnt lgkmcnt(13)
	v_pk_add_f32 v[188:189], v[158:159], v[190:191]
	v_pk_add_f32 v[158:159], v[158:159], v[190:191] neg_lo:[0,1] neg_hi:[0,1]
	v_sin_f32_e32 v2, v5
	v_pk_mul_f32 v[190:191], v[158:159], s[44:45]
	v_cos_f32_e32 v4, v5
	v_pk_fma_f32 v[158:159], v[158:159], s[42:43], v[190:191] op_sel:[0,0,1] op_sel_hi:[1,0,0]
	s_waitcnt lgkmcnt(12)
	v_pk_add_f32 v[190:191], v[160:161], v[192:193]
	v_pk_add_f32 v[160:161], v[160:161], v[192:193] neg_lo:[0,1] neg_hi:[0,1]
	v_xor_b32_e32 v5, 0x80000000, v2
	v_pk_mul_f32 v[192:193], v[160:161], s[62:63]
	v_mov_b32_e32 v3, v5
	v_pk_fma_f32 v[160:161], v[160:161], s[50:51], v[192:193] op_sel:[0,0,1] op_sel_hi:[1,0,0]
	s_waitcnt lgkmcnt(11)
	v_pk_add_f32 v[192:193], v[162:163], v[194:195]
	v_pk_add_f32 v[162:163], v[162:163], v[194:195] neg_lo:[0,1] neg_hi:[0,1]
	v_pk_mul_f32 v[6:7], v[4:5], v[2:3] op_sel:[1,0] op_sel_hi:[0,1]
	v_pk_mul_f32 v[194:195], v[162:163], s[68:69]
	v_pk_fma_f32 v[6:7], v[4:5], v[4:5], v[6:7] op_sel_hi:[1,0,1]
	v_pk_fma_f32 v[162:163], v[162:163], s[64:65], v[194:195] op_sel:[0,0,1] op_sel_hi:[1,0,0]
	s_waitcnt lgkmcnt(10)
	v_pk_add_f32 v[194:195], v[164:165], v[196:197]
	v_pk_add_f32 v[164:165], v[164:165], v[196:197] neg_lo:[0,1] neg_hi:[0,1]
	v_xor_b32_e32 v12, 0x80000000, v7
	v_pk_mul_f32 v[196:197], v[164:165], s[70:71]
	v_mov_b32_e32 v13, v7
	v_pk_fma_f32 v[164:165], v[164:165], s[46:47], v[196:197] op_sel:[0,0,1] op_sel_hi:[1,0,0]
	s_waitcnt lgkmcnt(9)
	v_pk_add_f32 v[196:197], v[166:167], v[198:199]
	v_pk_add_f32 v[166:167], v[166:167], v[198:199] neg_lo:[0,1] neg_hi:[0,1]
	v_pk_mul_f32 v[10:11], v[6:7], v[12:13] op_sel:[1,0] op_sel_hi:[0,1]
	v_pk_mul_f32 v[198:199], v[166:167], s[76:77]
	v_pk_fma_f32 v[10:11], v[6:7], v[6:7], v[10:11] op_sel_hi:[1,0,1]
	v_pk_fma_f32 v[166:167], v[166:167], s[72:73], v[198:199] op_sel:[0,0,1] op_sel_hi:[1,0,0]
	s_waitcnt lgkmcnt(8)
	v_pk_add_f32 v[198:199], v[168:169], v[204:205]
	v_pk_add_f32 v[168:169], v[168:169], v[204:205] neg_lo:[0,1] neg_hi:[0,1]
	v_xor_b32_e32 v14, 0x80000000, v11
	v_pk_mul_f32 v[204:205], v[168:169], s[26:27]
	v_mov_b32_e32 v15, v11
	v_pk_fma_f32 v[168:169], v[168:169], s[38:39], v[204:205] op_sel:[0,0,1] op_sel_hi:[1,0,0]
	s_waitcnt lgkmcnt(7)
	v_pk_add_f32 v[204:205], v[170:171], v[206:207]
	v_pk_add_f32 v[206:207], v[170:171], v[206:207] neg_lo:[0,1] neg_hi:[0,1]
	v_pk_mul_f32 v[26:27], v[10:11], v[14:15] op_sel:[1,0] op_sel_hi:[0,1]
	s_waitcnt lgkmcnt(6)
	v_pk_add_f32 v[170:171], v[172:173], v[208:209]
	v_pk_add_f32 v[172:173], v[172:173], v[208:209] neg_lo:[0,1] neg_hi:[0,1]
	v_pk_fma_f32 v[26:27], v[10:11], v[10:11], v[26:27] op_sel_hi:[1,0,1]
	v_pk_mul_f32 v[208:209], v[172:173], s[26:27]
	v_pk_mul_f32 v[46:47], v[14:15], v[26:27] op_sel:[0,1] op_sel_hi:[1,0]
	v_pk_fma_f32 v[172:173], v[172:173], s[38:39], v[208:209] op_sel:[0,0,1] op_sel_hi:[1,0,0] neg_lo:[1,0,0] neg_hi:[1,0,0]
	s_waitcnt lgkmcnt(5)
	v_pk_add_f32 v[208:209], v[174:175], v[210:211]
	v_pk_add_f32 v[174:175], v[174:175], v[210:211] neg_lo:[0,1] neg_hi:[0,1]
	v_pk_fma_f32 v[46:47], v[10:11], v[26:27], v[46:47] op_sel_hi:[0,1,1]
	v_pk_mul_f32 v[210:211], v[174:175], s[76:77]
	v_pk_mul_f32 v[62:63], v[14:15], v[46:47] op_sel:[0,1] op_sel_hi:[1,0]
	v_pk_fma_f32 v[174:175], v[174:175], s[72:73], v[210:211] op_sel:[0,0,1] op_sel_hi:[1,0,0] neg_lo:[1,0,0] neg_hi:[1,0,0]
	s_waitcnt lgkmcnt(4)
	v_pk_add_f32 v[210:211], v[176:177], v[212:213]
	v_pk_add_f32 v[176:177], v[176:177], v[212:213] neg_lo:[0,1] neg_hi:[0,1]
	v_pk_fma_f32 v[62:63], v[10:11], v[46:47], v[62:63] op_sel_hi:[0,1,1]
	v_pk_mul_f32 v[212:213], v[176:177], s[70:71]
	v_pk_mul_f32 v[78:79], v[14:15], v[62:63] op_sel:[0,1] op_sel_hi:[1,0]
	v_pk_fma_f32 v[176:177], v[176:177], s[46:47], v[212:213] op_sel:[0,0,1] op_sel_hi:[1,0,0] neg_lo:[1,0,0] neg_hi:[1,0,0]
	s_waitcnt lgkmcnt(3)
	v_pk_add_f32 v[212:213], v[178:179], v[214:215]
	v_pk_add_f32 v[178:179], v[178:179], v[214:215] neg_lo:[0,1] neg_hi:[0,1]
	v_pk_fma_f32 v[78:79], v[10:11], v[62:63], v[78:79] op_sel_hi:[0,1,1]
	v_pk_mul_f32 v[214:215], v[178:179], s[68:69]
	v_pk_mul_f32 v[94:95], v[14:15], v[78:79] op_sel:[0,1] op_sel_hi:[1,0]
	v_pk_fma_f32 v[178:179], v[178:179], s[64:65], v[214:215] op_sel:[0,0,1] op_sel_hi:[1,0,0] neg_lo:[1,0,0] neg_hi:[1,0,0]
	s_waitcnt lgkmcnt(2)
	v_pk_add_f32 v[214:215], v[180:181], v[216:217]
	v_pk_add_f32 v[180:181], v[180:181], v[216:217] neg_lo:[0,1] neg_hi:[0,1]
	v_pk_fma_f32 v[94:95], v[10:11], v[78:79], v[94:95] op_sel_hi:[0,1,1]
	v_pk_mul_f32 v[216:217], v[180:181], s[62:63]
	v_pk_mul_f32 v[110:111], v[14:15], v[94:95] op_sel:[0,1] op_sel_hi:[1,0]
	v_pk_fma_f32 v[180:181], v[180:181], s[50:51], v[216:217] op_sel:[0,0,1] op_sel_hi:[1,0,0] neg_lo:[1,0,0] neg_hi:[1,0,0]
	s_waitcnt lgkmcnt(1)
	v_pk_add_f32 v[216:217], v[182:183], v[218:219]
	v_pk_add_f32 v[182:183], v[182:183], v[218:219] neg_lo:[0,1] neg_hi:[0,1]
	v_pk_mul_f32 v[8:9], v[2:3], v[6:7] op_sel:[0,1] op_sel_hi:[1,0]
	v_pk_mul_f32 v[218:219], v[182:183], s[44:45]
	v_pk_fma_f32 v[110:111], v[10:11], v[94:95], v[110:111] op_sel_hi:[0,1,1]
	v_pk_fma_f32 v[182:183], v[182:183], s[42:43], v[218:219] op_sel:[0,0,1] op_sel_hi:[1,0,0] neg_lo:[1,0,0] neg_hi:[1,0,0]
	s_waitcnt lgkmcnt(0)
	v_pk_add_f32 v[218:219], v[184:185], v[220:221]
	v_pk_add_f32 v[184:185], v[184:185], v[220:221] neg_lo:[0,1] neg_hi:[0,1]
	v_pk_fma_f32 v[8:9], v[4:5], v[6:7], v[8:9] op_sel_hi:[0,1,1]
	v_pk_mul_f32 v[220:221], v[184:185], s[40:41]
	v_pk_mul_f32 v[16:17], v[2:3], v[10:11] op_sel:[0,1] op_sel_hi:[1,0]
	v_pk_fma_f32 v[184:185], v[184:185], s[36:37], v[220:221] op_sel:[0,0,1] op_sel_hi:[1,0,0] neg_lo:[1,0,0] neg_hi:[1,0,0]
	v_pk_add_f32 v[220:221], v[222:223], v[204:205]
	v_pk_add_f32 v[204:205], v[222:223], v[204:205] neg_lo:[0,1] neg_hi:[0,1]
	v_pk_add_f32 v[222:223], v[186:187], v[170:171]
	v_pk_add_f32 v[170:171], v[186:187], v[170:171] neg_lo:[0,1] neg_hi:[0,1]
	v_pk_mul_f32 v[30:31], v[2:3], v[26:27] op_sel:[0,1] op_sel_hi:[1,0]
	v_pk_mul_f32 v[186:187], v[170:171], s[44:45]
	v_pk_mul_f32 v[50:51], v[2:3], v[46:47] op_sel:[0,1] op_sel_hi:[1,0]
	v_pk_fma_f32 v[170:171], v[170:171], s[42:43], v[186:187] op_sel:[0,0,1] op_sel_hi:[1,0,0]
	v_pk_add_f32 v[186:187], v[188:189], v[208:209]
	v_pk_add_f32 v[188:189], v[188:189], v[208:209] neg_lo:[0,1] neg_hi:[0,1]
	v_pk_mul_f32 v[66:67], v[2:3], v[62:63] op_sel:[0,1] op_sel_hi:[1,0]
	v_pk_mul_f32 v[208:209], v[188:189], s[68:69]
	v_pk_mul_f32 v[82:83], v[2:3], v[78:79] op_sel:[0,1] op_sel_hi:[1,0]
	v_pk_fma_f32 v[188:189], v[188:189], s[64:65], v[208:209] op_sel:[0,0,1] op_sel_hi:[1,0,0]
	v_pk_add_f32 v[208:209], v[190:191], v[210:211]
	v_pk_add_f32 v[190:191], v[190:191], v[210:211] neg_lo:[0,1] neg_hi:[0,1]
	v_pk_mul_f32 v[98:99], v[2:3], v[94:95] op_sel:[0,1] op_sel_hi:[1,0]
	v_pk_mul_f32 v[210:211], v[190:191], s[76:77]
	v_pk_mul_f32 v[114:115], v[2:3], v[110:111] op_sel:[0,1] op_sel_hi:[1,0]
	v_pk_fma_f32 v[190:191], v[190:191], s[72:73], v[210:211] op_sel:[0,0,1] op_sel_hi:[1,0,0]
	v_pk_add_f32 v[210:211], v[192:193], v[212:213]
	v_pk_add_f32 v[212:213], v[192:193], v[212:213] neg_lo:[0,1] neg_hi:[0,1]
	v_xor_b32_e32 v20, 0x80000000, v9
	v_pk_add_f32 v[192:193], v[194:195], v[214:215]
	v_pk_add_f32 v[194:195], v[194:195], v[214:215] neg_lo:[0,1] neg_hi:[0,1]
	v_mov_b32_e32 v21, v9
	v_pk_mul_f32 v[214:215], v[194:195], s[76:77]
	v_pk_fma_f32 v[16:17], v[4:5], v[10:11], v[16:17] op_sel_hi:[0,1,1]
	v_pk_fma_f32 v[194:195], v[194:195], s[72:73], v[214:215] op_sel:[0,0,1] op_sel_hi:[1,0,0] neg_lo:[1,0,0] neg_hi:[1,0,0]
	v_pk_add_f32 v[214:215], v[196:197], v[216:217]
	v_pk_add_f32 v[196:197], v[196:197], v[216:217] neg_lo:[0,1] neg_hi:[0,1]
	v_pk_mul_f32 v[18:19], v[12:13], v[10:11] op_sel:[0,1] op_sel_hi:[1,0]
	v_pk_mul_f32 v[216:217], v[196:197], s[68:69]
	v_pk_fma_f32 v[30:31], v[4:5], v[26:27], v[30:31] op_sel_hi:[0,1,1]
	v_pk_fma_f32 v[196:197], v[196:197], s[64:65], v[216:217] op_sel:[0,0,1] op_sel_hi:[1,0,0] neg_lo:[1,0,0] neg_hi:[1,0,0]
	v_pk_add_f32 v[216:217], v[198:199], v[218:219]
	v_pk_add_f32 v[198:199], v[198:199], v[218:219] neg_lo:[0,1] neg_hi:[0,1]
	v_pk_mul_f32 v[38:39], v[12:13], v[26:27] op_sel:[0,1] op_sel_hi:[1,0]
	v_pk_mul_f32 v[218:219], v[198:199], s[44:45]
	v_pk_fma_f32 v[50:51], v[4:5], v[46:47], v[50:51] op_sel_hi:[0,1,1]
	v_pk_fma_f32 v[198:199], v[198:199], s[42:43], v[218:219] op_sel:[0,0,1] op_sel_hi:[1,0,0] neg_lo:[1,0,0] neg_hi:[1,0,0]
	v_pk_add_f32 v[218:219], v[154:155], v[206:207] op_sel:[0,1] op_sel_hi:[1,0] neg_hi:[0,1]
	v_pk_add_f32 v[154:155], v[154:155], v[206:207] op_sel:[0,1] op_sel_hi:[1,0] neg_lo:[0,1]
	v_pk_add_f32 v[206:207], v[156:157], v[172:173]
	v_pk_add_f32 v[156:157], v[156:157], v[172:173] neg_lo:[0,1] neg_hi:[0,1]
	v_pk_mul_f32 v[54:55], v[12:13], v[46:47] op_sel:[0,1] op_sel_hi:[1,0]
	v_pk_mul_f32 v[172:173], v[156:157], s[44:45]
	v_pk_fma_f32 v[66:67], v[4:5], v[62:63], v[66:67] op_sel_hi:[0,1,1]
	v_pk_fma_f32 v[156:157], v[156:157], s[42:43], v[172:173] op_sel:[0,0,1] op_sel_hi:[1,0,0]
	v_pk_add_f32 v[172:173], v[158:159], v[174:175]
	v_pk_add_f32 v[158:159], v[158:159], v[174:175] neg_lo:[0,1] neg_hi:[0,1]
	v_pk_mul_f32 v[70:71], v[12:13], v[62:63] op_sel:[0,1] op_sel_hi:[1,0]
	v_pk_mul_f32 v[174:175], v[158:159], s[68:69]
	v_pk_fma_f32 v[82:83], v[4:5], v[78:79], v[82:83] op_sel_hi:[0,1,1]
	v_pk_fma_f32 v[158:159], v[158:159], s[64:65], v[174:175] op_sel:[0,0,1] op_sel_hi:[1,0,0]
	v_pk_add_f32 v[174:175], v[160:161], v[176:177]
	v_pk_add_f32 v[160:161], v[160:161], v[176:177] neg_lo:[0,1] neg_hi:[0,1]
	v_pk_mul_f32 v[86:87], v[12:13], v[78:79] op_sel:[0,1] op_sel_hi:[1,0]
	v_pk_mul_f32 v[176:177], v[160:161], s[76:77]
	v_pk_fma_f32 v[98:99], v[4:5], v[94:95], v[98:99] op_sel_hi:[0,1,1]
	v_pk_fma_f32 v[160:161], v[160:161], s[72:73], v[176:177] op_sel:[0,0,1] op_sel_hi:[1,0,0]
	v_pk_add_f32 v[176:177], v[162:163], v[178:179]
	v_pk_add_f32 v[178:179], v[162:163], v[178:179] neg_lo:[0,1] neg_hi:[0,1]
	v_pk_mul_f32 v[102:103], v[12:13], v[94:95] op_sel:[0,1] op_sel_hi:[1,0]
	v_pk_add_f32 v[162:163], v[164:165], v[180:181]
	v_pk_add_f32 v[164:165], v[164:165], v[180:181] neg_lo:[0,1] neg_hi:[0,1]
	v_pk_fma_f32 v[114:115], v[4:5], v[110:111], v[114:115] op_sel_hi:[0,1,1]
	v_pk_mul_f32 v[180:181], v[164:165], s[76:77]
	v_pk_mul_f32 v[118:119], v[12:13], v[110:111] op_sel:[0,1] op_sel_hi:[1,0]
	v_pk_fma_f32 v[164:165], v[164:165], s[72:73], v[180:181] op_sel:[0,0,1] op_sel_hi:[1,0,0] neg_lo:[1,0,0] neg_hi:[1,0,0]
	v_pk_add_f32 v[180:181], v[166:167], v[182:183]
	v_pk_add_f32 v[166:167], v[166:167], v[182:183] neg_lo:[0,1] neg_hi:[0,1]
	v_pk_fma_f32 v[18:19], v[6:7], v[10:11], v[18:19] op_sel_hi:[0,1,1]
	v_pk_mul_f32 v[182:183], v[166:167], s[68:69]
	v_pk_mul_f32 v[22:23], v[10:11], v[20:21] op_sel:[1,0] op_sel_hi:[0,1]
	v_pk_fma_f32 v[166:167], v[166:167], s[64:65], v[182:183] op_sel:[0,0,1] op_sel_hi:[1,0,0] neg_lo:[1,0,0] neg_hi:[1,0,0]
	v_pk_add_f32 v[182:183], v[168:169], v[184:185]
	v_pk_add_f32 v[168:169], v[168:169], v[184:185] neg_lo:[0,1] neg_hi:[0,1]
	v_pk_fma_f32 v[38:39], v[6:7], v[26:27], v[38:39] op_sel_hi:[0,1,1]
	v_pk_mul_f32 v[184:185], v[168:169], s[44:45]
	v_pk_mul_f32 v[42:43], v[20:21], v[26:27] op_sel:[0,1] op_sel_hi:[1,0]
	v_pk_fma_f32 v[168:169], v[168:169], s[42:43], v[184:185] op_sel:[0,0,1] op_sel_hi:[1,0,0] neg_lo:[1,0,0] neg_hi:[1,0,0]
	v_pk_add_f32 v[184:185], v[220:221], v[210:211]
	v_pk_add_f32 v[210:211], v[220:221], v[210:211] neg_lo:[0,1] neg_hi:[0,1]
	v_pk_add_f32 v[220:221], v[222:223], v[192:193]
	v_pk_add_f32 v[192:193], v[222:223], v[192:193] neg_lo:[0,1] neg_hi:[0,1]
	v_pk_fma_f32 v[54:55], v[6:7], v[46:47], v[54:55] op_sel_hi:[0,1,1]
	v_pk_mul_f32 v[222:223], v[192:193], s[68:69]
	v_pk_mul_f32 v[58:59], v[20:21], v[46:47] op_sel:[0,1] op_sel_hi:[1,0]
	v_pk_fma_f32 v[192:193], v[192:193], s[64:65], v[222:223] op_sel:[0,0,1] op_sel_hi:[1,0,0]
	v_pk_add_f32 v[222:223], v[186:187], v[214:215]
	v_pk_add_f32 v[214:215], v[186:187], v[214:215] neg_lo:[0,1] neg_hi:[0,1]
	v_pk_fma_f32 v[70:71], v[6:7], v[62:63], v[70:71] op_sel_hi:[0,1,1]
	v_pk_add_f32 v[186:187], v[208:209], v[216:217]
	v_pk_add_f32 v[208:209], v[208:209], v[216:217] neg_lo:[0,1] neg_hi:[0,1]
	v_pk_mul_f32 v[74:75], v[20:21], v[62:63] op_sel:[0,1] op_sel_hi:[1,0]
	v_pk_mul_f32 v[216:217], v[208:209], s[68:69]
	v_pk_fma_f32 v[86:87], v[6:7], v[78:79], v[86:87] op_sel_hi:[0,1,1]
	v_pk_fma_f32 v[208:209], v[208:209], s[64:65], v[216:217] op_sel:[0,0,1] op_sel_hi:[1,0,0] neg_lo:[1,0,0] neg_hi:[1,0,0]
	v_pk_add_f32 v[216:217], v[204:205], v[212:213] op_sel:[0,1] op_sel_hi:[1,0] neg_hi:[0,1]
	v_pk_add_f32 v[204:205], v[204:205], v[212:213] op_sel:[0,1] op_sel_hi:[1,0] neg_lo:[0,1]
	v_pk_add_f32 v[212:213], v[170:171], v[194:195]
	v_pk_add_f32 v[170:171], v[170:171], v[194:195] neg_lo:[0,1] neg_hi:[0,1]
	v_pk_mul_f32 v[90:91], v[20:21], v[78:79] op_sel:[0,1] op_sel_hi:[1,0]
	v_pk_mul_f32 v[194:195], v[170:171], s[68:69]
	v_pk_fma_f32 v[102:103], v[6:7], v[94:95], v[102:103] op_sel_hi:[0,1,1]
	v_pk_fma_f32 v[170:171], v[170:171], s[64:65], v[194:195] op_sel:[0,0,1] op_sel_hi:[1,0,0]
	v_pk_add_f32 v[194:195], v[188:189], v[196:197]
	v_pk_add_f32 v[196:197], v[188:189], v[196:197] neg_lo:[0,1] neg_hi:[0,1]
	v_pk_mul_f32 v[106:107], v[20:21], v[94:95] op_sel:[0,1] op_sel_hi:[1,0]
	v_pk_add_f32 v[188:189], v[190:191], v[198:199]
	v_pk_add_f32 v[190:191], v[190:191], v[198:199] neg_lo:[0,1] neg_hi:[0,1]
	v_pk_fma_f32 v[118:119], v[6:7], v[110:111], v[118:119] op_sel_hi:[0,1,1]
	v_pk_mul_f32 v[198:199], v[190:191], s[68:69]
	v_pk_mul_f32 v[122:123], v[20:21], v[110:111] op_sel:[0,1] op_sel_hi:[1,0]
	v_pk_fma_f32 v[190:191], v[190:191], s[64:65], v[198:199] op_sel:[0,0,1] op_sel_hi:[1,0,0] neg_lo:[1,0,0] neg_hi:[1,0,0]
	v_pk_add_f32 v[198:199], v[218:219], v[176:177]
	v_pk_add_f32 v[176:177], v[218:219], v[176:177] neg_lo:[0,1] neg_hi:[0,1]
	v_pk_add_f32 v[218:219], v[206:207], v[162:163]
	v_pk_add_f32 v[162:163], v[206:207], v[162:163] neg_lo:[0,1] neg_hi:[0,1]
	v_xor_b32_e32 v24, 0x80000000, v17
	v_pk_mul_f32 v[206:207], v[162:163], s[68:69]
	v_xor_b32_e32 v28, 0x80000000, v19
	v_pk_fma_f32 v[162:163], v[162:163], s[64:65], v[206:207] op_sel:[0,0,1] op_sel_hi:[1,0,0]
	v_pk_add_f32 v[206:207], v[172:173], v[180:181]
	v_pk_add_f32 v[180:181], v[172:173], v[180:181] neg_lo:[0,1] neg_hi:[0,1]
	v_pk_fma_f32 v[22:23], v[10:11], v[8:9], v[22:23] op_sel_hi:[1,0,1]
	v_pk_add_f32 v[172:173], v[174:175], v[182:183]
	v_pk_add_f32 v[174:175], v[174:175], v[182:183] neg_lo:[0,1] neg_hi:[0,1]
	v_pk_fma_f32 v[42:43], v[8:9], v[26:27], v[42:43] op_sel_hi:[0,1,1]
	v_pk_mul_f32 v[182:183], v[174:175], s[68:69]
	v_pk_fma_f32 v[58:59], v[8:9], v[46:47], v[58:59] op_sel_hi:[0,1,1]
	v_pk_fma_f32 v[174:175], v[174:175], s[64:65], v[182:183] op_sel:[0,0,1] op_sel_hi:[1,0,0] neg_lo:[1,0,0] neg_hi:[1,0,0]
	v_pk_add_f32 v[182:183], v[154:155], v[178:179] op_sel:[0,1] op_sel_hi:[1,0] neg_hi:[0,1]
	v_pk_add_f32 v[154:155], v[154:155], v[178:179] op_sel:[0,1] op_sel_hi:[1,0] neg_lo:[0,1]
	v_pk_add_f32 v[178:179], v[156:157], v[164:165]
	v_pk_add_f32 v[156:157], v[156:157], v[164:165] neg_lo:[0,1] neg_hi:[0,1]
	v_pk_fma_f32 v[74:75], v[8:9], v[62:63], v[74:75] op_sel_hi:[0,1,1]
	v_pk_mul_f32 v[164:165], v[156:157], s[68:69]
	v_pk_fma_f32 v[90:91], v[8:9], v[78:79], v[90:91] op_sel_hi:[0,1,1]
	v_pk_fma_f32 v[156:157], v[156:157], s[64:65], v[164:165] op_sel:[0,0,1] op_sel_hi:[1,0,0]
	v_pk_add_f32 v[164:165], v[158:159], v[166:167]
	v_pk_add_f32 v[166:167], v[158:159], v[166:167] neg_lo:[0,1] neg_hi:[0,1]
	v_pk_fma_f32 v[106:107], v[8:9], v[94:95], v[106:107] op_sel_hi:[0,1,1]
	v_pk_add_f32 v[158:159], v[160:161], v[168:169]
	v_pk_add_f32 v[160:161], v[160:161], v[168:169] neg_lo:[0,1] neg_hi:[0,1]
	v_pk_fma_f32 v[122:123], v[8:9], v[110:111], v[122:123] op_sel_hi:[0,1,1]
	v_pk_mul_f32 v[168:169], v[160:161], s[68:69]
	v_mov_b32_e32 v25, v17
	v_pk_fma_f32 v[160:161], v[160:161], s[64:65], v[168:169] op_sel:[0,0,1] op_sel_hi:[1,0,0] neg_lo:[1,0,0] neg_hi:[1,0,0]
	v_pk_add_f32 v[168:169], v[184:185], v[222:223]
	v_pk_add_f32 v[184:185], v[184:185], v[222:223] neg_lo:[0,1] neg_hi:[0,1]
	v_pk_add_f32 v[222:223], v[220:221], v[186:187]
	v_pk_add_f32 v[220:221], v[220:221], v[186:187] neg_lo:[0,1] neg_hi:[0,1]
	v_mov_b32_e32 v29, v19
	v_pk_add_f32 v[186:187], v[210:211], v[214:215] op_sel:[0,1] op_sel_hi:[1,0] neg_hi:[0,1]
	v_pk_add_f32 v[210:211], v[210:211], v[214:215] op_sel:[0,1] op_sel_hi:[1,0] neg_lo:[0,1]
	v_pk_add_f32 v[214:215], v[192:193], v[208:209]
	v_pk_add_f32 v[208:209], v[192:193], v[208:209] neg_lo:[0,1] neg_hi:[0,1]
	v_xor_b32_e32 v32, 0x80000000, v23
	v_pk_add_f32 v[192:193], v[216:217], v[194:195]
	v_pk_add_f32 v[194:195], v[216:217], v[194:195] neg_lo:[0,1] neg_hi:[0,1]
	v_pk_add_f32 v[216:217], v[212:213], v[188:189]
	v_pk_add_f32 v[212:213], v[212:213], v[188:189] neg_lo:[0,1] neg_hi:[0,1]
	v_xor_b32_e32 v40, 0x80000000, v27
	v_pk_add_f32 v[188:189], v[204:205], v[196:197] op_sel:[0,1] op_sel_hi:[1,0] neg_hi:[0,1]
	v_pk_add_f32 v[196:197], v[204:205], v[196:197] op_sel:[0,1] op_sel_hi:[1,0] neg_lo:[0,1]
	v_pk_add_f32 v[204:205], v[170:171], v[190:191]
	v_pk_add_f32 v[190:191], v[170:171], v[190:191] neg_lo:[0,1] neg_hi:[0,1]
	v_xor_b32_e32 v44, 0x80000000, v31
	v_pk_add_f32 v[170:171], v[198:199], v[206:207]
	v_pk_add_f32 v[198:199], v[198:199], v[206:207] neg_lo:[0,1] neg_hi:[0,1]
	v_pk_add_f32 v[206:207], v[218:219], v[172:173]
	v_pk_add_f32 v[218:219], v[218:219], v[172:173] neg_lo:[0,1] neg_hi:[0,1]
	v_xor_b32_e32 v48, 0x80000000, v39
	v_pk_add_f32 v[172:173], v[176:177], v[180:181] op_sel:[0,1] op_sel_hi:[1,0] neg_hi:[0,1]
	v_pk_add_f32 v[176:177], v[176:177], v[180:181] op_sel:[0,1] op_sel_hi:[1,0] neg_lo:[0,1]
	v_pk_add_f32 v[180:181], v[162:163], v[174:175]
	v_pk_add_f32 v[174:175], v[162:163], v[174:175] neg_lo:[0,1] neg_hi:[0,1]
	v_mov_b32_e32 v33, v23
	v_pk_add_f32 v[162:163], v[182:183], v[164:165]
	v_pk_add_f32 v[164:165], v[182:183], v[164:165] neg_lo:[0,1] neg_hi:[0,1]
	v_pk_add_f32 v[182:183], v[178:179], v[158:159]
	v_pk_add_f32 v[178:179], v[178:179], v[158:159] neg_lo:[0,1] neg_hi:[0,1]
	v_mov_b32_e32 v41, v27
	v_pk_add_f32 v[158:159], v[154:155], v[166:167] op_sel:[0,1] op_sel_hi:[1,0] neg_hi:[0,1]
	v_pk_add_f32 v[154:155], v[154:155], v[166:167] op_sel:[0,1] op_sel_hi:[1,0] neg_lo:[0,1]
	v_pk_add_f32 v[166:167], v[156:157], v[160:161]
	v_pk_add_f32 v[156:157], v[156:157], v[160:161] neg_lo:[0,1] neg_hi:[0,1]
	v_mov_b32_e32 v45, v31
	v_xor_b32_e32 v161, 0x80000000, v156
	v_mov_b32_e32 v160, v157
	v_pk_add_f32 v[156:157], v[168:169], v[222:223]
	v_pk_add_f32 v[168:169], v[168:169], v[222:223] neg_lo:[0,1] neg_hi:[0,1]
	v_pk_add_f32 v[222:223], v[184:185], v[220:221] op_sel:[0,1] op_sel_hi:[1,0] neg_hi:[0,1]
	v_pk_add_f32 v[184:185], v[184:185], v[220:221] op_sel:[0,1] op_sel_hi:[1,0] neg_lo:[0,1]
	v_pk_add_f32 v[220:221], v[186:187], v[214:215]
	v_pk_add_f32 v[186:187], v[186:187], v[214:215] neg_lo:[0,1] neg_hi:[0,1]
	v_pk_add_f32 v[214:215], v[210:211], v[208:209] op_sel:[0,1] op_sel_hi:[1,0] neg_hi:[0,1]
	v_pk_add_f32 v[208:209], v[210:211], v[208:209] op_sel:[0,1] op_sel_hi:[1,0] neg_lo:[0,1]
	v_pk_add_f32 v[210:211], v[192:193], v[216:217]
	v_pk_add_f32 v[192:193], v[192:193], v[216:217] neg_lo:[0,1] neg_hi:[0,1]
	v_pk_add_f32 v[216:217], v[194:195], v[212:213] op_sel:[0,1] op_sel_hi:[1,0] neg_hi:[0,1]
	v_pk_add_f32 v[194:195], v[194:195], v[212:213] op_sel:[0,1] op_sel_hi:[1,0] neg_lo:[0,1]
	v_pk_add_f32 v[212:213], v[188:189], v[204:205]
	v_pk_add_f32 v[188:189], v[188:189], v[204:205] neg_lo:[0,1] neg_hi:[0,1]
	v_pk_add_f32 v[204:205], v[196:197], v[190:191] op_sel:[0,1] op_sel_hi:[1,0] neg_hi:[0,1]
	v_pk_add_f32 v[190:191], v[196:197], v[190:191] op_sel:[0,1] op_sel_hi:[1,0] neg_lo:[0,1]
	v_pk_add_f32 v[196:197], v[170:171], v[206:207]
	v_pk_add_f32 v[170:171], v[170:171], v[206:207] neg_lo:[0,1] neg_hi:[0,1]
	v_pk_mul_f32 v[2:3], v[2:3], v[196:197] op_sel:[0,1] op_sel_hi:[1,0]
	v_pk_add_f32 v[206:207], v[198:199], v[218:219] op_sel:[0,1] op_sel_hi:[1,0] neg_hi:[0,1]
	v_pk_add_f32 v[198:199], v[198:199], v[218:219] op_sel:[0,1] op_sel_hi:[1,0] neg_lo:[0,1]
	v_pk_add_f32 v[218:219], v[172:173], v[180:181]
	v_pk_add_f32 v[172:173], v[172:173], v[180:181] neg_lo:[0,1] neg_hi:[0,1]
	v_pk_add_f32 v[180:181], v[176:177], v[174:175] op_sel:[0,1] op_sel_hi:[1,0] neg_hi:[0,1]
	v_pk_add_f32 v[174:175], v[176:177], v[174:175] op_sel:[0,1] op_sel_hi:[1,0] neg_lo:[0,1]
	v_pk_add_f32 v[176:177], v[162:163], v[182:183]
	v_pk_fma_f32 v[2:3], v[4:5], v[196:197], v[2:3] op_sel_hi:[0,1,1]
	v_pk_mul_f32 v[4:5], v[12:13], v[210:211] op_sel:[0,1] op_sel_hi:[1,0]
	v_mov_b32_e32 v49, v39
	v_pk_fma_f32 v[4:5], v[6:7], v[210:211], v[4:5] op_sel_hi:[0,1,1]
	v_pk_mul_f32 v[6:7], v[20:21], v[176:177] op_sel:[0,1] op_sel_hi:[1,0]
	v_pk_add_f32 v[162:163], v[162:163], v[182:183] neg_lo:[0,1] neg_hi:[0,1]
	v_pk_fma_f32 v[6:7], v[8:9], v[176:177], v[6:7] op_sel_hi:[0,1,1]
	v_pk_mul_f32 v[8:9], v[14:15], v[220:221] op_sel:[0,1] op_sel_hi:[1,0]
	v_pk_add_f32 v[182:183], v[164:165], v[178:179] op_sel:[0,1] op_sel_hi:[1,0] neg_hi:[0,1]
	v_pk_add_f32 v[164:165], v[164:165], v[178:179] op_sel:[0,1] op_sel_hi:[1,0] neg_lo:[0,1]
	v_pk_add_f32 v[178:179], v[158:159], v[166:167]
	v_pk_fma_f32 v[8:9], v[10:11], v[220:221], v[8:9] op_sel_hi:[0,1,1]
	v_pk_mul_f32 v[10:11], v[24:25], v[218:219] op_sel:[0,1] op_sel_hi:[1,0]
	v_pk_mul_f32 v[12:13], v[28:29], v[212:213] op_sel:[0,1] op_sel_hi:[1,0]
	v_xor_b32_e32 v52, 0x80000000, v43
	v_xor_b32_e32 v56, 0x80000000, v47
	v_xor_b32_e32 v60, 0x80000000, v51
	v_xor_b32_e32 v64, 0x80000000, v55
	v_xor_b32_e32 v68, 0x80000000, v59
	v_xor_b32_e32 v72, 0x80000000, v63
	v_xor_b32_e32 v76, 0x80000000, v67
	v_mov_b32_e32 v53, v43
	v_mov_b32_e32 v57, v47
	v_mov_b32_e32 v61, v51
	v_mov_b32_e32 v65, v55
	v_mov_b32_e32 v69, v59
	v_mov_b32_e32 v73, v63
	v_mov_b32_e32 v77, v67
	v_pk_add_f32 v[158:159], v[158:159], v[166:167] neg_lo:[0,1] neg_hi:[0,1]
	v_pk_add_f32 v[166:167], v[154:155], v[160:161]
	v_pk_fma_f32 v[10:11], v[16:17], v[218:219], v[10:11] op_sel_hi:[0,1,1]
	v_pk_fma_f32 v[12:13], v[18:19], v[212:213], v[12:13] op_sel_hi:[0,1,1]
	v_pk_mul_f32 v[14:15], v[32:33], v[178:179] op_sel:[0,1] op_sel_hi:[1,0]
	v_pk_mul_f32 v[16:17], v[40:41], v[222:223] op_sel:[0,1] op_sel_hi:[1,0]
	v_pk_mul_f32 v[18:19], v[44:45], v[206:207] op_sel:[0,1] op_sel_hi:[1,0]
	v_pk_mul_f32 v[20:21], v[48:49], v[216:217] op_sel:[0,1] op_sel_hi:[1,0]
	v_xor_b32_e32 v80, 0x80000000, v71
	v_xor_b32_e32 v84, 0x80000000, v75
	v_xor_b32_e32 v88, 0x80000000, v79
	v_xor_b32_e32 v92, 0x80000000, v83
	v_xor_b32_e32 v96, 0x80000000, v87
	v_xor_b32_e32 v100, 0x80000000, v91
	v_xor_b32_e32 v104, 0x80000000, v95
	v_xor_b32_e32 v108, 0x80000000, v99
	v_xor_b32_e32 v112, 0x80000000, v103
	v_xor_b32_e32 v116, 0x80000000, v107
	v_xor_b32_e32 v120, 0x80000000, v111
	v_xor_b32_e32 v124, 0x80000000, v115
	v_xor_b32_e32 v126, 0x80000000, v119
	v_xor_b32_e32 v128, 0x80000000, v123
	v_mov_b32_e32 v81, v71
	v_mov_b32_e32 v85, v75
	v_mov_b32_e32 v89, v79
	v_mov_b32_e32 v93, v83
	v_mov_b32_e32 v97, v87
	v_mov_b32_e32 v101, v91
	v_mov_b32_e32 v105, v95
	v_mov_b32_e32 v109, v99
	v_mov_b32_e32 v113, v103
	v_mov_b32_e32 v117, v107
	v_mov_b32_e32 v121, v111
	v_mov_b32_e32 v125, v115
	v_mov_b32_e32 v127, v119
	v_mov_b32_e32 v129, v123
	v_pk_add_f32 v[154:155], v[154:155], v[160:161] neg_lo:[0,1] neg_hi:[0,1]
	v_pk_fma_f32 v[14:15], v[22:23], v[178:179], v[14:15] op_sel_hi:[0,1,1]
	v_pk_fma_f32 v[16:17], v[26:27], v[222:223], v[16:17] op_sel_hi:[0,1,1]
	v_pk_fma_f32 v[18:19], v[30:31], v[206:207], v[18:19] op_sel_hi:[0,1,1]
	v_pk_fma_f32 v[20:21], v[38:39], v[216:217], v[20:21] op_sel_hi:[0,1,1]
	v_pk_mul_f32 v[22:23], v[52:53], v[182:183] op_sel:[0,1] op_sel_hi:[1,0]
	v_pk_mul_f32 v[24:25], v[56:57], v[214:215] op_sel:[0,1] op_sel_hi:[1,0]
	v_pk_mul_f32 v[26:27], v[60:61], v[180:181] op_sel:[0,1] op_sel_hi:[1,0]
	v_pk_mul_f32 v[28:29], v[64:65], v[204:205] op_sel:[0,1] op_sel_hi:[1,0]
	v_pk_mul_f32 v[30:31], v[68:69], v[166:167] op_sel:[0,1] op_sel_hi:[1,0]
	v_pk_mul_f32 v[32:33], v[72:73], v[168:169] op_sel:[0,1] op_sel_hi:[1,0]
	v_pk_mul_f32 v[38:39], v[76:77], v[170:171] op_sel:[0,1] op_sel_hi:[1,0]
	v_pk_fma_f32 v[22:23], v[42:43], v[182:183], v[22:23] op_sel_hi:[0,1,1]
	v_pk_fma_f32 v[24:25], v[46:47], v[214:215], v[24:25] op_sel_hi:[0,1,1]
	v_pk_fma_f32 v[26:27], v[50:51], v[180:181], v[26:27] op_sel_hi:[0,1,1]
	v_pk_fma_f32 v[28:29], v[54:55], v[204:205], v[28:29] op_sel_hi:[0,1,1]
	v_pk_fma_f32 v[30:31], v[58:59], v[166:167], v[30:31] op_sel_hi:[0,1,1]
	v_pk_fma_f32 v[32:33], v[62:63], v[168:169], v[32:33] op_sel_hi:[0,1,1]
	v_pk_fma_f32 v[38:39], v[66:67], v[170:171], v[38:39] op_sel_hi:[0,1,1]
	v_pk_mul_f32 v[40:41], v[80:81], v[192:193] op_sel:[0,1] op_sel_hi:[1,0]
	v_pk_mul_f32 v[42:43], v[84:85], v[162:163] op_sel:[0,1] op_sel_hi:[1,0]
	v_pk_mul_f32 v[44:45], v[88:89], v[186:187] op_sel:[0,1] op_sel_hi:[1,0]
	v_pk_mul_f32 v[46:47], v[92:93], v[172:173] op_sel:[0,1] op_sel_hi:[1,0]
	v_pk_mul_f32 v[48:49], v[96:97], v[188:189] op_sel:[0,1] op_sel_hi:[1,0]
	v_pk_mul_f32 v[50:51], v[100:101], v[158:159] op_sel:[0,1] op_sel_hi:[1,0]
	v_pk_mul_f32 v[52:53], v[104:105], v[184:185] op_sel:[0,1] op_sel_hi:[1,0]
	v_pk_mul_f32 v[54:55], v[108:109], v[198:199] op_sel:[0,1] op_sel_hi:[1,0]
	v_pk_mul_f32 v[56:57], v[112:113], v[194:195] op_sel:[0,1] op_sel_hi:[1,0]
	v_pk_mul_f32 v[58:59], v[116:117], v[164:165] op_sel:[0,1] op_sel_hi:[1,0]
	v_pk_mul_f32 v[60:61], v[120:121], v[208:209] op_sel:[0,1] op_sel_hi:[1,0]
	v_pk_mul_f32 v[62:63], v[124:125], v[174:175] op_sel:[0,1] op_sel_hi:[1,0]
	v_pk_mul_f32 v[64:65], v[126:127], v[190:191] op_sel:[0,1] op_sel_hi:[1,0]
	v_pk_mul_f32 v[66:67], v[128:129], v[154:155] op_sel:[0,1] op_sel_hi:[1,0]
	v_pk_fma_f32 v[40:41], v[70:71], v[192:193], v[40:41] op_sel_hi:[0,1,1]
	v_pk_fma_f32 v[42:43], v[74:75], v[162:163], v[42:43] op_sel_hi:[0,1,1]
	v_pk_fma_f32 v[44:45], v[78:79], v[186:187], v[44:45] op_sel_hi:[0,1,1]
	v_pk_fma_f32 v[46:47], v[82:83], v[172:173], v[46:47] op_sel_hi:[0,1,1]
	v_pk_fma_f32 v[48:49], v[86:87], v[188:189], v[48:49] op_sel_hi:[0,1,1]
	v_pk_fma_f32 v[50:51], v[90:91], v[158:159], v[50:51] op_sel_hi:[0,1,1]
	v_pk_fma_f32 v[52:53], v[94:95], v[184:185], v[52:53] op_sel_hi:[0,1,1]
	v_pk_fma_f32 v[54:55], v[98:99], v[198:199], v[54:55] op_sel_hi:[0,1,1]
	v_pk_fma_f32 v[56:57], v[102:103], v[194:195], v[56:57] op_sel_hi:[0,1,1]
	v_pk_fma_f32 v[58:59], v[106:107], v[164:165], v[58:59] op_sel_hi:[0,1,1]
	v_pk_fma_f32 v[60:61], v[110:111], v[208:209], v[60:61] op_sel_hi:[0,1,1]
	v_pk_fma_f32 v[62:63], v[114:115], v[174:175], v[62:63] op_sel_hi:[0,1,1]
	v_pk_fma_f32 v[64:65], v[118:119], v[190:191], v[64:65] op_sel_hi:[0,1,1]
	v_pk_fma_f32 v[66:67], v[122:123], v[154:155], v[66:67] op_sel_hi:[0,1,1]
	ds_write_b64 v36, v[156:157]
	ds_write_b64 v36, v[32:33] offset:2112
	ds_write_b64 v36, v[16:17] offset:4224
	ds_write_b64 v36, v[52:53] offset:6336
	ds_write_b64 v36, v[8:9] offset:8448
	ds_write_b64 v36, v[44:45] offset:10560
	ds_write_b64 v36, v[24:25] offset:12672
	ds_write_b64 v36, v[60:61] offset:14784
	ds_write_b64 v36, v[4:5] offset:16896
	ds_write_b64 v36, v[40:41] offset:19008
	ds_write_b64 v36, v[20:21] offset:21120
	ds_write_b64 v36, v[56:57] offset:23232
	ds_write_b64 v36, v[12:13] offset:25344
	ds_write_b64 v36, v[48:49] offset:27456
	ds_write_b64 v36, v[28:29] offset:29568
	ds_write_b64 v36, v[64:65] offset:31680
	ds_write_b64 v36, v[2:3] offset:33792
	ds_write_b64 v36, v[38:39] offset:35904
	ds_write_b64 v36, v[18:19] offset:38016
	ds_write_b64 v36, v[54:55] offset:40128
	ds_write_b64 v36, v[10:11] offset:42240
	ds_write_b64 v36, v[46:47] offset:44352
	ds_write_b64 v36, v[26:27] offset:46464
	ds_write_b64 v36, v[62:63] offset:48576
	ds_write_b64 v36, v[6:7] offset:50688
	ds_write_b64 v36, v[42:43] offset:52800
	ds_write_b64 v36, v[22:23] offset:54912
	ds_write_b64 v36, v[58:59] offset:57024
	ds_write_b64 v36, v[14:15] offset:59136
	ds_write_b64 v36, v[50:51] offset:61248
	ds_write_b64 v36, v[30:31] offset:63360
	ds_write_b64 v36, v[66:67] offset:65472
	v_mov_b32_e32 v3, v130
	s_waitcnt lgkmcnt(0)
	s_barrier
	s_nop 0
	v_and_b32_e32 v5, 15, v3
	v_cvt_f32_ubyte0_e32 v2, v5
	v_mul_f32_e32 v4, 0x3b800000, v2
	v_sin_f32_e32 v2, v4
	v_cos_f32_e32 v4, v4
	v_lshlrev_b32_e32 v66, 3, v5
	v_lshlrev_b32_e32 v36, 4, v3
	v_xor_b32_e32 v5, 0x80000000, v2
	v_mov_b32_e32 v3, v5
	v_pk_mul_f32 v[6:7], v[4:5], v[2:3] op_sel:[1,0] op_sel_hi:[0,1]
	v_pk_fma_f32 v[6:7], v[4:5], v[4:5], v[6:7] op_sel_hi:[0,1,1]
	v_xor_b32_e32 v12, 0x80000000, v7
	v_mov_b32_e32 v13, v7
	v_pk_mul_f32 v[10:11], v[6:7], v[12:13] op_sel:[1,0] op_sel_hi:[0,1]
	v_pk_fma_f32 v[10:11], v[6:7], v[6:7], v[10:11] op_sel_hi:[1,0,1]
	v_pk_mul_f32 v[8:9], v[2:3], v[6:7] op_sel:[0,1] op_sel_hi:[1,0]
	v_xor_b32_e32 v14, 0x80000000, v11
	v_mov_b32_e32 v15, v11
	v_pk_mul_f32 v[30:31], v[10:11], v[14:15] op_sel:[1,0] op_sel_hi:[0,1]
	v_pk_fma_f32 v[30:31], v[10:11], v[10:11], v[30:31] op_sel_hi:[1,0,1]
	v_pk_mul_f32 v[16:17], v[2:3], v[10:11] op_sel:[0,1] op_sel_hi:[1,0]
	v_pk_mul_f32 v[50:51], v[14:15], v[30:31] op_sel:[0,1] op_sel_hi:[1,0]
	v_pk_mul_f32 v[38:39], v[2:3], v[30:31] op_sel:[0,1] op_sel_hi:[1,0]
	v_pk_fma_f32 v[50:51], v[10:11], v[30:31], v[50:51] op_sel_hi:[0,1,1]
	v_pk_mul_f32 v[54:55], v[2:3], v[50:51] op_sel:[0,1] op_sel_hi:[1,0]
	v_pk_fma_f32 v[8:9], v[4:5], v[6:7], v[8:9] op_sel_hi:[0,1,1]
	v_pk_fma_f32 v[16:17], v[4:5], v[10:11], v[16:17] op_sel_hi:[0,1,1]
	v_pk_fma_f32 v[38:39], v[4:5], v[30:31], v[38:39] op_sel_hi:[0,1,1]
	v_pk_fma_f32 v[54:55], v[4:5], v[50:51], v[54:55] op_sel_hi:[0,1,1]
	v_and_b32_e32 v5, 0xffffff00, v36
	v_lshlrev_b32_e32 v36, 3, v5
	v_add3_u32 v36, 0, v66, v36
	v_ashrrev_i32_e32 v66, 2, v5
	v_add_u32_e32 v108, v36, v66
	ds_read2_b64 v[66:69], v108 offset1:16
	ds_read2_b64 v[70:73], v108 offset0:33 offset1:49
	ds_read2_b64 v[74:77], v108 offset0:66 offset1:82
	ds_read2_b64 v[78:81], v108 offset0:132 offset1:148
	ds_read2_b64 v[82:85], v108 offset0:99 offset1:115
	ds_read2_b64 v[86:89], v108 offset0:165 offset1:181
	ds_read2_b64 v[90:93], v108 offset0:198 offset1:214
	ds_read2_b64 v[94:97], v108 offset0:231 offset1:247
	s_waitcnt lgkmcnt(4)
	v_pk_add_f32 v[98:99], v[66:67], v[78:79]
	v_pk_add_f32 v[66:67], v[66:67], v[78:79] neg_lo:[0,1] neg_hi:[0,1]
	v_pk_add_f32 v[78:79], v[68:69], v[80:81]
	v_pk_add_f32 v[68:69], v[68:69], v[80:81] neg_lo:[0,1] neg_hi:[0,1]
	s_waitcnt lgkmcnt(1)
	v_pk_add_f32 v[100:101], v[76:77], v[92:93]
	v_pk_mul_f32 v[80:81], v[68:69], s[44:45]
	v_pk_add_f32 v[76:77], v[76:77], v[92:93] neg_lo:[0,1] neg_hi:[0,1]
	v_pk_fma_f32 v[68:69], v[68:69], s[42:43], v[80:81] op_sel:[0,0,1] op_sel_hi:[1,0,0]
	v_pk_add_f32 v[80:81], v[70:71], v[86:87]
	v_pk_add_f32 v[70:71], v[70:71], v[86:87] neg_lo:[0,1] neg_hi:[0,1]
	v_pk_mul_f32 v[92:93], v[76:77], s[76:77]
	v_pk_mul_f32 v[86:87], v[70:71], s[68:69]
	v_pk_fma_f32 v[76:77], v[76:77], s[72:73], v[92:93] op_sel:[0,0,1] op_sel_hi:[1,0,0] neg_lo:[1,0,0] neg_hi:[1,0,0]
	v_pk_fma_f32 v[70:71], v[70:71], s[64:65], v[86:87] op_sel:[0,0,1] op_sel_hi:[1,0,0]
	v_pk_add_f32 v[86:87], v[72:73], v[88:89]
	v_pk_add_f32 v[72:73], v[72:73], v[88:89] neg_lo:[0,1] neg_hi:[0,1]
	s_waitcnt lgkmcnt(0)
	v_pk_add_f32 v[92:93], v[82:83], v[94:95]
	v_pk_add_f32 v[82:83], v[82:83], v[94:95] neg_lo:[0,1] neg_hi:[0,1]
	v_pk_mul_f32 v[88:89], v[72:73], s[76:77]
	v_pk_mul_f32 v[94:95], v[82:83], s[68:69]
	v_pk_fma_f32 v[72:73], v[72:73], s[72:73], v[88:89] op_sel:[0,0,1] op_sel_hi:[1,0,0]
	v_pk_add_f32 v[88:89], v[74:75], v[90:91]
	v_pk_add_f32 v[90:91], v[74:75], v[90:91] neg_lo:[0,1] neg_hi:[0,1]
	v_pk_fma_f32 v[82:83], v[82:83], s[64:65], v[94:95] op_sel:[0,0,1] op_sel_hi:[1,0,0] neg_lo:[1,0,0] neg_hi:[1,0,0]
	v_pk_add_f32 v[94:95], v[84:85], v[96:97]
	v_pk_add_f32 v[84:85], v[84:85], v[96:97] neg_lo:[0,1] neg_hi:[0,1]
	s_nop 0
	v_pk_mul_f32 v[96:97], v[84:85], s[44:45]
	s_nop 0
	v_pk_fma_f32 v[84:85], v[84:85], s[42:43], v[96:97] op_sel:[0,0,1] op_sel_hi:[1,0,0] neg_lo:[1,0,0] neg_hi:[1,0,0]
	v_pk_add_f32 v[96:97], v[98:99], v[88:89]
	v_pk_add_f32 v[88:89], v[98:99], v[88:89] neg_lo:[0,1] neg_hi:[0,1]
	v_pk_add_f32 v[98:99], v[78:79], v[100:101]
	v_pk_add_f32 v[78:79], v[78:79], v[100:101] neg_lo:[0,1] neg_hi:[0,1]
	v_pk_add_f32 v[102:103], v[86:87], v[94:95]
	v_pk_add_f32 v[86:87], v[86:87], v[94:95] neg_lo:[0,1] neg_hi:[0,1]
	v_pk_add_f32 v[74:75], v[66:67], v[90:91] op_sel:[0,1] op_sel_hi:[1,0] neg_hi:[0,1]
	v_pk_add_f32 v[66:67], v[66:67], v[90:91] op_sel:[0,1] op_sel_hi:[1,0] neg_lo:[0,1]
	v_pk_add_f32 v[90:91], v[68:69], v[76:77]
	v_pk_add_f32 v[68:69], v[68:69], v[76:77] neg_lo:[0,1] neg_hi:[0,1]
	v_pk_mul_f32 v[100:101], v[78:79], s[68:69]
	v_pk_mul_f32 v[94:95], v[86:87], s[68:69]
	v_pk_mul_f32 v[76:77], v[68:69], s[68:69]
	v_pk_fma_f32 v[78:79], v[78:79], s[64:65], v[100:101] op_sel:[0,0,1] op_sel_hi:[1,0,0]
	v_pk_add_f32 v[100:101], v[80:81], v[92:93]
	v_pk_add_f32 v[92:93], v[80:81], v[92:93] neg_lo:[0,1] neg_hi:[0,1]
	v_pk_fma_f32 v[86:87], v[86:87], s[64:65], v[94:95] op_sel:[0,0,1] op_sel_hi:[1,0,0] neg_lo:[1,0,0] neg_hi:[1,0,0]
	v_pk_fma_f32 v[68:69], v[68:69], s[64:65], v[76:77] op_sel:[0,0,1] op_sel_hi:[1,0,0]
	v_pk_add_f32 v[76:77], v[70:71], v[82:83]
	v_pk_add_f32 v[94:95], v[72:73], v[84:85]
	v_pk_add_f32 v[72:73], v[72:73], v[84:85] neg_lo:[0,1] neg_hi:[0,1]
	v_pk_add_f32 v[70:71], v[70:71], v[82:83] neg_lo:[0,1] neg_hi:[0,1]
	v_pk_mul_f32 v[84:85], v[72:73], s[68:69]
	v_pk_add_f32 v[104:105], v[74:75], v[76:77]
	v_pk_add_f32 v[74:75], v[74:75], v[76:77] neg_lo:[0,1] neg_hi:[0,1]
	v_pk_add_f32 v[76:77], v[90:91], v[94:95]
	v_pk_add_f32 v[94:95], v[90:91], v[94:95] neg_lo:[0,1] neg_hi:[0,1]
	v_xor_b32_e32 v18, 0x80000000, v9
	v_mov_b32_e32 v19, v9
	v_pk_mul_f32 v[22:23], v[12:13], v[10:11] op_sel:[0,1] op_sel_hi:[1,0]
	v_xor_b32_e32 v83, 0x80000000, v70
	v_pk_fma_f32 v[72:73], v[72:73], s[64:65], v[84:85] op_sel:[0,0,1] op_sel_hi:[1,0,0] neg_lo:[1,0,0] neg_hi:[1,0,0]
	v_pk_add_f32 v[80:81], v[88:89], v[92:93] op_sel:[0,1] op_sel_hi:[1,0] neg_hi:[0,1]
	v_pk_add_f32 v[88:89], v[88:89], v[92:93] op_sel:[0,1] op_sel_hi:[1,0] neg_lo:[0,1]
	v_pk_add_f32 v[92:93], v[78:79], v[86:87]
	v_pk_add_f32 v[86:87], v[78:79], v[86:87] neg_lo:[0,1] neg_hi:[0,1]
	v_mov_b32_e32 v82, v71
	v_xor_b32_e32 v20, 0x80000000, v17
	v_mov_b32_e32 v21, v17
	v_pk_fma_f32 v[22:23], v[6:7], v[10:11], v[22:23] op_sel_hi:[0,1,1]
	v_pk_mul_f32 v[26:27], v[10:11], v[18:19] op_sel:[1,0] op_sel_hi:[0,1]
	v_pk_add_f32 v[70:71], v[66:67], v[82:83]
	v_pk_add_f32 v[66:67], v[66:67], v[82:83] neg_lo:[0,1] neg_hi:[0,1]
	v_pk_add_f32 v[82:83], v[68:69], v[72:73]
	v_pk_add_f32 v[72:73], v[68:69], v[72:73] neg_lo:[0,1] neg_hi:[0,1]
	v_pk_add_f32 v[90:91], v[74:75], v[94:95] op_sel:[0,1] op_sel_hi:[1,0] neg_hi:[0,1]
	v_xor_b32_e32 v24, 0x80000000, v23
	v_mov_b32_e32 v25, v23
	v_pk_fma_f32 v[26:27], v[10:11], v[8:9], v[26:27] op_sel_hi:[1,0,1]
	v_pk_add_f32 v[78:79], v[88:89], v[86:87] op_sel:[0,1] op_sel_hi:[1,0] neg_hi:[0,1]
	v_pk_add_f32 v[74:75], v[74:75], v[94:95] op_sel:[0,1] op_sel_hi:[1,0] neg_lo:[0,1]
	v_pk_mul_f32 v[94:95], v[20:21], v[90:91] op_sel:[0,1] op_sel_hi:[1,0]
	v_xor_b32_e32 v28, 0x80000000, v27
	v_mov_b32_e32 v29, v27
	v_pk_add_f32 v[84:85], v[96:97], v[100:101]
	v_pk_add_f32 v[96:97], v[96:97], v[100:101] neg_lo:[0,1] neg_hi:[0,1]
	v_pk_add_f32 v[100:101], v[98:99], v[102:103]
	v_pk_add_f32 v[68:69], v[66:67], v[72:73] op_sel:[0,1] op_sel_hi:[1,0] neg_hi:[0,1]
	v_pk_fma_f32 v[90:91], v[16:17], v[90:91], v[94:95] op_sel_hi:[0,1,1]
	v_pk_mul_f32 v[94:95], v[24:25], v[78:79] op_sel:[0,1] op_sel_hi:[1,0]
	v_xor_b32_e32 v32, 0x80000000, v31
	v_mov_b32_e32 v33, v31
	v_pk_mul_f32 v[42:43], v[12:13], v[30:31] op_sel:[0,1] op_sel_hi:[1,0]
	v_pk_add_f32 v[106:107], v[84:85], v[100:101]
	v_pk_add_f32 v[84:85], v[84:85], v[100:101] neg_lo:[0,1] neg_hi:[0,1]
	v_pk_fma_f32 v[78:79], v[22:23], v[78:79], v[94:95] op_sel_hi:[0,1,1]
	v_pk_mul_f32 v[94:95], v[28:29], v[68:69] op_sel:[0,1] op_sel_hi:[1,0]
	v_xor_b32_e32 v40, 0x80000000, v39
	v_mov_b32_e32 v41, v39
	v_pk_fma_f32 v[42:43], v[6:7], v[30:31], v[42:43] op_sel_hi:[0,1,1]
	v_pk_mul_f32 v[46:47], v[18:19], v[30:31] op_sel:[0,1] op_sel_hi:[1,0]
	v_pk_add_f32 v[86:87], v[88:89], v[86:87] op_sel:[0,1] op_sel_hi:[1,0] neg_lo:[0,1]
	v_pk_add_f32 v[88:89], v[104:105], v[76:77]
	v_pk_add_f32 v[76:77], v[104:105], v[76:77] neg_lo:[0,1] neg_hi:[0,1]
	v_pk_fma_f32 v[68:69], v[26:27], v[68:69], v[94:95] op_sel_hi:[0,1,1]
	v_pk_mul_f32 v[94:95], v[32:33], v[84:85] op_sel:[0,1] op_sel_hi:[1,0]
	v_xor_b32_e32 v44, 0x80000000, v43
	v_mov_b32_e32 v45, v43
	v_pk_fma_f32 v[46:47], v[8:9], v[30:31], v[46:47] op_sel_hi:[0,1,1]
	v_pk_add_f32 v[102:103], v[98:99], v[102:103] neg_lo:[0,1] neg_hi:[0,1]
	v_pk_add_f32 v[100:101], v[80:81], v[92:93]
	v_pk_add_f32 v[80:81], v[80:81], v[92:93] neg_lo:[0,1] neg_hi:[0,1]
	v_pk_fma_f32 v[84:85], v[30:31], v[84:85], v[94:95] op_sel_hi:[0,1,1]
	v_pk_mul_f32 v[94:95], v[40:41], v[76:77] op_sel:[0,1] op_sel_hi:[1,0]
	v_xor_b32_e32 v48, 0x80000000, v47
	v_mov_b32_e32 v49, v47
	v_pk_add_f32 v[92:93], v[70:71], v[82:83]
	v_pk_add_f32 v[70:71], v[70:71], v[82:83] neg_lo:[0,1] neg_hi:[0,1]
	v_pk_fma_f32 v[76:77], v[38:39], v[76:77], v[94:95] op_sel_hi:[0,1,1]
	v_pk_mul_f32 v[94:95], v[44:45], v[80:81] op_sel:[0,1] op_sel_hi:[1,0]
	v_xor_b32_e32 v52, 0x80000000, v51
	v_mov_b32_e32 v53, v51
	v_pk_mul_f32 v[58:59], v[12:13], v[50:51] op_sel:[0,1] op_sel_hi:[1,0]
	v_pk_add_f32 v[98:99], v[96:97], v[102:103] op_sel:[0,1] op_sel_hi:[1,0] neg_hi:[0,1]
	v_pk_add_f32 v[96:97], v[96:97], v[102:103] op_sel:[0,1] op_sel_hi:[1,0] neg_lo:[0,1]
	v_pk_fma_f32 v[80:81], v[42:43], v[80:81], v[94:95] op_sel_hi:[0,1,1]
	v_pk_mul_f32 v[94:95], v[48:49], v[70:71] op_sel:[0,1] op_sel_hi:[1,0]
	v_xor_b32_e32 v56, 0x80000000, v55
	v_mov_b32_e32 v57, v55
	v_pk_fma_f32 v[58:59], v[6:7], v[50:51], v[58:59] op_sel_hi:[0,1,1]
	v_pk_mul_f32 v[62:63], v[18:19], v[50:51] op_sel:[0,1] op_sel_hi:[1,0]
	v_pk_fma_f32 v[70:71], v[46:47], v[70:71], v[94:95] op_sel_hi:[0,1,1]
	v_pk_mul_f32 v[94:95], v[52:53], v[96:97] op_sel:[0,1] op_sel_hi:[1,0]
	v_xor_b32_e32 v60, 0x80000000, v59
	v_mov_b32_e32 v61, v59
	v_pk_fma_f32 v[62:63], v[8:9], v[50:51], v[62:63] op_sel_hi:[0,1,1]
	v_pk_add_f32 v[66:67], v[66:67], v[72:73] op_sel:[0,1] op_sel_hi:[1,0] neg_lo:[0,1]
	v_pk_mul_f32 v[72:73], v[2:3], v[88:89] op_sel:[0,1] op_sel_hi:[1,0]
	v_pk_fma_f32 v[94:95], v[50:51], v[96:97], v[94:95] op_sel_hi:[0,1,1]
	v_pk_mul_f32 v[96:97], v[56:57], v[74:75] op_sel:[0,1] op_sel_hi:[1,0]
	v_xor_b32_e32 v64, 0x80000000, v63
	v_mov_b32_e32 v65, v63
	v_pk_fma_f32 v[72:73], v[4:5], v[88:89], v[72:73] op_sel_hi:[0,1,1]
	v_pk_mul_f32 v[88:89], v[18:19], v[92:93] op_sel:[0,1] op_sel_hi:[1,0]
	v_pk_fma_f32 v[74:75], v[54:55], v[74:75], v[96:97] op_sel_hi:[0,1,1]
	v_pk_mul_f32 v[96:97], v[60:61], v[86:87] op_sel:[0,1] op_sel_hi:[1,0]
	v_add_u32_e32 v5, 0x2000, v5
	v_pk_mul_f32 v[82:83], v[12:13], v[100:101] op_sel:[0,1] op_sel_hi:[1,0]
	v_pk_fma_f32 v[88:89], v[8:9], v[92:93], v[88:89] op_sel_hi:[0,1,1]
	v_pk_mul_f32 v[92:93], v[14:15], v[98:99] op_sel:[0,1] op_sel_hi:[1,0]
	v_pk_fma_f32 v[86:87], v[58:59], v[86:87], v[96:97] op_sel_hi:[0,1,1]
	v_pk_mul_f32 v[96:97], v[64:65], v[66:67] op_sel:[0,1] op_sel_hi:[1,0]
	v_ashrrev_i32_e32 v5, 2, v5
	v_pk_fma_f32 v[82:83], v[6:7], v[100:101], v[82:83] op_sel_hi:[0,1,1]
	v_pk_fma_f32 v[92:93], v[10:11], v[98:99], v[92:93] op_sel_hi:[0,1,1]
	v_pk_fma_f32 v[66:67], v[62:63], v[66:67], v[96:97] op_sel_hi:[0,1,1]
	ds_write2_b64 v108, v[106:107], v[84:85] offset1:16
	ds_write2_b64 v108, v[92:93], v[94:95] offset0:33 offset1:49
	ds_write2_b64 v108, v[82:83], v[80:81] offset0:66 offset1:82
	ds_write2_b64 v108, v[78:79], v[86:87] offset0:99 offset1:115
	ds_write2_b64 v108, v[72:73], v[76:77] offset0:132 offset1:148
	ds_write2_b64 v108, v[90:91], v[74:75] offset0:165 offset1:181
	ds_write2_b64 v108, v[88:89], v[70:71] offset0:198 offset1:214
	ds_write2_b64 v108, v[68:69], v[66:67] offset0:231 offset1:247
	v_add3_u32 v36, v36, v5, s30
	ds_read2_b64 v[66:69], v36 offset1:16
	ds_read2_b64 v[70:73], v36 offset0:33 offset1:49
	ds_read2_b64 v[74:77], v36 offset0:66 offset1:82
	ds_read2_b64 v[78:81], v36 offset0:132 offset1:148
	ds_read2_b64 v[82:85], v36 offset0:99 offset1:115
	ds_read2_b64 v[86:89], v36 offset0:165 offset1:181
	ds_read2_b64 v[90:93], v36 offset0:198 offset1:214
	ds_read2_b64 v[94:97], v36 offset0:231 offset1:247
	s_waitcnt lgkmcnt(4)
	v_pk_add_f32 v[98:99], v[66:67], v[78:79]
	v_pk_add_f32 v[66:67], v[66:67], v[78:79] neg_lo:[0,1] neg_hi:[0,1]
	v_pk_add_f32 v[78:79], v[68:69], v[80:81]
	v_pk_add_f32 v[68:69], v[68:69], v[80:81] neg_lo:[0,1] neg_hi:[0,1]
	s_waitcnt lgkmcnt(1)
	v_pk_add_f32 v[100:101], v[76:77], v[92:93]
	v_pk_mul_f32 v[80:81], v[68:69], s[44:45]
	v_pk_add_f32 v[76:77], v[76:77], v[92:93] neg_lo:[0,1] neg_hi:[0,1]
	v_pk_fma_f32 v[68:69], v[68:69], s[42:43], v[80:81] op_sel:[0,0,1] op_sel_hi:[1,0,0]
	v_pk_add_f32 v[80:81], v[70:71], v[86:87]
	v_pk_add_f32 v[70:71], v[70:71], v[86:87] neg_lo:[0,1] neg_hi:[0,1]
	v_pk_mul_f32 v[92:93], v[76:77], s[76:77]
	v_pk_mul_f32 v[86:87], v[70:71], s[68:69]
	v_pk_fma_f32 v[76:77], v[76:77], s[72:73], v[92:93] op_sel:[0,0,1] op_sel_hi:[1,0,0] neg_lo:[1,0,0] neg_hi:[1,0,0]
	s_waitcnt lgkmcnt(0)
	v_pk_add_f32 v[92:93], v[82:83], v[94:95]
	v_pk_add_f32 v[82:83], v[82:83], v[94:95] neg_lo:[0,1] neg_hi:[0,1]
	v_pk_fma_f32 v[70:71], v[70:71], s[64:65], v[86:87] op_sel:[0,0,1] op_sel_hi:[1,0,0]
	v_pk_add_f32 v[86:87], v[72:73], v[88:89]
	v_pk_add_f32 v[72:73], v[72:73], v[88:89] neg_lo:[0,1] neg_hi:[0,1]
	v_pk_mul_f32 v[94:95], v[82:83], s[68:69]
	v_pk_mul_f32 v[88:89], v[72:73], s[76:77]
	v_pk_fma_f32 v[82:83], v[82:83], s[64:65], v[94:95] op_sel:[0,0,1] op_sel_hi:[1,0,0] neg_lo:[1,0,0] neg_hi:[1,0,0]
	v_pk_add_f32 v[94:95], v[84:85], v[96:97]
	v_pk_add_f32 v[84:85], v[84:85], v[96:97] neg_lo:[0,1] neg_hi:[0,1]
	v_pk_fma_f32 v[72:73], v[72:73], s[72:73], v[88:89] op_sel:[0,0,1] op_sel_hi:[1,0,0]
	v_pk_add_f32 v[88:89], v[74:75], v[90:91]
	v_pk_mul_f32 v[96:97], v[84:85], s[44:45]
	v_pk_add_f32 v[90:91], v[74:75], v[90:91] neg_lo:[0,1] neg_hi:[0,1]
	v_pk_fma_f32 v[84:85], v[84:85], s[42:43], v[96:97] op_sel:[0,0,1] op_sel_hi:[1,0,0] neg_lo:[1,0,0] neg_hi:[1,0,0]
	v_pk_add_f32 v[96:97], v[98:99], v[88:89]
	v_pk_add_f32 v[88:89], v[98:99], v[88:89] neg_lo:[0,1] neg_hi:[0,1]
	v_pk_add_f32 v[98:99], v[78:79], v[100:101]
	v_pk_add_f32 v[78:79], v[78:79], v[100:101] neg_lo:[0,1] neg_hi:[0,1]
	v_pk_add_f32 v[102:103], v[86:87], v[94:95]
	v_pk_add_f32 v[86:87], v[86:87], v[94:95] neg_lo:[0,1] neg_hi:[0,1]
	v_pk_mul_f32 v[100:101], v[78:79], s[68:69]
	v_pk_mul_f32 v[94:95], v[86:87], s[68:69]
	v_pk_fma_f32 v[78:79], v[78:79], s[64:65], v[100:101] op_sel:[0,0,1] op_sel_hi:[1,0,0]
	v_pk_add_f32 v[100:101], v[80:81], v[92:93]
	v_pk_add_f32 v[92:93], v[80:81], v[92:93] neg_lo:[0,1] neg_hi:[0,1]
	v_pk_fma_f32 v[86:87], v[86:87], s[64:65], v[94:95] op_sel:[0,0,1] op_sel_hi:[1,0,0] neg_lo:[1,0,0] neg_hi:[1,0,0]
	v_pk_add_f32 v[74:75], v[66:67], v[90:91] op_sel:[0,1] op_sel_hi:[1,0] neg_hi:[0,1]
	v_pk_add_f32 v[66:67], v[66:67], v[90:91] op_sel:[0,1] op_sel_hi:[1,0] neg_lo:[0,1]
	v_pk_add_f32 v[90:91], v[68:69], v[76:77]
	v_pk_add_f32 v[68:69], v[68:69], v[76:77] neg_lo:[0,1] neg_hi:[0,1]
	v_pk_add_f32 v[94:95], v[72:73], v[84:85]
	v_pk_add_f32 v[72:73], v[72:73], v[84:85] neg_lo:[0,1] neg_hi:[0,1]
	v_pk_mul_f32 v[76:77], v[68:69], s[68:69]
	v_pk_mul_f32 v[84:85], v[72:73], s[68:69]
	v_pk_fma_f32 v[68:69], v[68:69], s[64:65], v[76:77] op_sel:[0,0,1] op_sel_hi:[1,0,0]
	v_pk_add_f32 v[76:77], v[70:71], v[82:83]
	v_pk_fma_f32 v[72:73], v[72:73], s[64:65], v[84:85] op_sel:[0,0,1] op_sel_hi:[1,0,0] neg_lo:[1,0,0] neg_hi:[1,0,0]
	v_pk_add_f32 v[80:81], v[88:89], v[92:93] op_sel:[0,1] op_sel_hi:[1,0] neg_hi:[0,1]
	v_pk_add_f32 v[88:89], v[88:89], v[92:93] op_sel:[0,1] op_sel_hi:[1,0] neg_lo:[0,1]
	v_pk_add_f32 v[92:93], v[78:79], v[86:87]
	v_pk_add_f32 v[86:87], v[78:79], v[86:87] neg_lo:[0,1] neg_hi:[0,1]
	s_add_i32 s65, s65, s28
	v_pk_add_f32 v[82:83], v[70:71], v[82:83] neg_lo:[0,1] neg_hi:[0,1]
	s_nop 0
	v_pk_add_f32 v[104:105], v[74:75], v[76:77]
	v_pk_add_f32 v[74:75], v[74:75], v[76:77] neg_lo:[0,1] neg_hi:[0,1]
	v_pk_add_f32 v[76:77], v[90:91], v[94:95]
	s_cmpk_gt_i32 s65, 0x3ff
	s_nop 0
	v_pk_add_f32 v[84:85], v[96:97], v[100:101]
	v_pk_add_f32 v[96:97], v[96:97], v[100:101] neg_lo:[0,1] neg_hi:[0,1]
	v_pk_add_f32 v[100:101], v[98:99], v[102:103]
	s_nop 0
	v_pk_add_f32 v[78:79], v[88:89], v[86:87] op_sel:[0,1] op_sel_hi:[1,0] neg_hi:[0,1]
	v_pk_add_f32 v[86:87], v[88:89], v[86:87] op_sel:[0,1] op_sel_hi:[1,0] neg_lo:[0,1]
	v_pk_add_f32 v[88:89], v[104:105], v[76:77]
	s_cselect_b64 s[80:81], -1, 0
	s_cmpk_lt_i32 s65, 0x400
	v_pk_add_f32 v[98:99], v[98:99], v[102:103] neg_lo:[0,1] neg_hi:[0,1]
	v_pk_add_f32 v[70:71], v[66:67], v[82:83] op_sel:[0,1] op_sel_hi:[1,0] neg_hi:[0,1]
	v_pk_add_f32 v[66:67], v[66:67], v[82:83] op_sel:[0,1] op_sel_hi:[1,0] neg_lo:[0,1]
	v_pk_add_f32 v[82:83], v[68:69], v[72:73]
	v_pk_add_f32 v[106:107], v[84:85], v[100:101]
	v_pk_add_f32 v[84:85], v[84:85], v[100:101] neg_lo:[0,1] neg_hi:[0,1]
	v_pk_add_f32 v[100:101], v[80:81], v[92:93]
	v_pk_mul_f32 v[2:3], v[2:3], v[88:89] op_sel:[0,1] op_sel_hi:[1,0]
	s_cselect_b32 s6, s65, s6
	v_xor_b32_e32 v103, 0x80000000, v98
	v_pk_add_f32 v[90:91], v[90:91], v[94:95] neg_lo:[0,1] neg_hi:[0,1]
	v_mov_b32_e32 v102, v99
	v_pk_add_f32 v[80:81], v[80:81], v[92:93] neg_lo:[0,1] neg_hi:[0,1]
	v_pk_add_f32 v[92:93], v[70:71], v[82:83]
	v_pk_fma_f32 v[2:3], v[4:5], v[88:89], v[2:3] op_sel_hi:[0,1,1]
	v_pk_mul_f32 v[4:5], v[12:13], v[100:101] op_sel:[0,1] op_sel_hi:[1,0]
	s_lshl_b32 s8, s6, 1
	s_lshl_b32 s6, s6, 2
	v_xor_b32_e32 v95, 0x80000000, v90
	v_pk_add_f32 v[68:69], v[68:69], v[72:73] neg_lo:[0,1] neg_hi:[0,1]
	v_pk_add_f32 v[98:99], v[96:97], v[102:103]
	v_mov_b32_e32 v94, v91
	v_pk_fma_f32 v[4:5], v[6:7], v[100:101], v[4:5] op_sel_hi:[0,1,1]
	v_pk_mul_f32 v[6:7], v[18:19], v[92:93] op_sel:[0,1] op_sel_hi:[1,0]
	s_and_b32 s7, s8, 0x3fe
	s_and_b32 s6, s6, 0xfffff800
	v_xor_b32_e32 v73, 0x80000000, v68
	v_pk_add_f32 v[90:91], v[74:75], v[94:95]
	v_mov_b32_e32 v72, v69
	v_pk_fma_f32 v[6:7], v[8:9], v[92:93], v[6:7] op_sel_hi:[0,1,1]
	v_pk_mul_f32 v[8:9], v[14:15], v[98:99] op_sel:[0,1] op_sel_hi:[1,0]
	s_or_b32 s6, s7, s6
	v_pk_add_f32 v[68:69], v[66:67], v[72:73]
	v_pk_fma_f32 v[8:9], v[10:11], v[98:99], v[8:9] op_sel_hi:[0,1,1]
	v_pk_mul_f32 v[10:11], v[20:21], v[90:91] op_sel:[0,1] op_sel_hi:[1,0]
	s_ashr_i32 s7, s6, 31
	v_pk_add_f32 v[96:97], v[96:97], v[102:103] neg_lo:[0,1] neg_hi:[0,1]
	v_pk_add_f32 v[76:77], v[104:105], v[76:77] neg_lo:[0,1] neg_hi:[0,1]
	v_pk_add_f32 v[74:75], v[74:75], v[94:95] neg_lo:[0,1] neg_hi:[0,1]
	v_pk_add_f32 v[70:71], v[70:71], v[82:83] neg_lo:[0,1] neg_hi:[0,1]
	v_pk_add_f32 v[66:67], v[66:67], v[72:73] neg_lo:[0,1] neg_hi:[0,1]
	v_pk_fma_f32 v[10:11], v[16:17], v[90:91], v[10:11] op_sel_hi:[0,1,1]
	v_pk_mul_f32 v[12:13], v[24:25], v[78:79] op_sel:[0,1] op_sel_hi:[1,0]
	v_pk_mul_f32 v[14:15], v[28:29], v[68:69] op_sel:[0,1] op_sel_hi:[1,0]
	v_pk_mul_f32 v[16:17], v[32:33], v[84:85] op_sel:[0,1] op_sel_hi:[1,0]
	s_lshl_b64 s[82:83], s[6:7], 14
	s_bitset1_b32 s6, 10
	v_pk_fma_f32 v[12:13], v[22:23], v[78:79], v[12:13] op_sel_hi:[0,1,1]
	v_pk_fma_f32 v[14:15], v[26:27], v[68:69], v[14:15] op_sel_hi:[0,1,1]
	v_pk_fma_f32 v[16:17], v[30:31], v[84:85], v[16:17] op_sel_hi:[0,1,1]
	v_pk_mul_f32 v[18:19], v[40:41], v[76:77] op_sel:[0,1] op_sel_hi:[1,0]
	v_pk_mul_f32 v[20:21], v[44:45], v[80:81] op_sel:[0,1] op_sel_hi:[1,0]
	v_pk_mul_f32 v[22:23], v[48:49], v[70:71] op_sel:[0,1] op_sel_hi:[1,0]
	v_pk_mul_f32 v[24:25], v[52:53], v[96:97] op_sel:[0,1] op_sel_hi:[1,0]
	v_pk_mul_f32 v[26:27], v[56:57], v[74:75] op_sel:[0,1] op_sel_hi:[1,0]
	v_pk_mul_f32 v[28:29], v[60:61], v[86:87] op_sel:[0,1] op_sel_hi:[1,0]
	v_pk_mul_f32 v[30:31], v[64:65], v[66:67] op_sel:[0,1] op_sel_hi:[1,0]
	s_ashr_i32 s7, s6, 31
	v_pk_fma_f32 v[18:19], v[38:39], v[76:77], v[18:19] op_sel_hi:[0,1,1]
	v_pk_fma_f32 v[20:21], v[42:43], v[80:81], v[20:21] op_sel_hi:[0,1,1]
	v_pk_fma_f32 v[22:23], v[46:47], v[70:71], v[22:23] op_sel_hi:[0,1,1]
	v_pk_fma_f32 v[24:25], v[50:51], v[96:97], v[24:25] op_sel_hi:[0,1,1]
	v_pk_fma_f32 v[26:27], v[54:55], v[74:75], v[26:27] op_sel_hi:[0,1,1]
	v_pk_fma_f32 v[28:29], v[58:59], v[86:87], v[28:29] op_sel_hi:[0,1,1]
	v_pk_fma_f32 v[30:31], v[62:63], v[66:67], v[30:31] op_sel_hi:[0,1,1]
	ds_write2_b64 v36, v[106:107], v[16:17] offset1:16
	ds_write2_b64 v36, v[8:9], v[24:25] offset0:33 offset1:49
	ds_write2_b64 v36, v[4:5], v[20:21] offset0:66 offset1:82
	ds_write2_b64 v36, v[12:13], v[28:29] offset0:99 offset1:115
	ds_write2_b64 v36, v[2:3], v[18:19] offset0:132 offset1:148
	ds_write2_b64 v36, v[10:11], v[26:27] offset0:165 offset1:181
	ds_write2_b64 v36, v[6:7], v[22:23] offset0:198 offset1:214
	ds_write2_b64 v36, v[14:15], v[30:31] offset0:231 offset1:247
	s_lshl_b64 s[6:7], s[6:7], 14
	v_lshl_add_u64 v[2:3], v[34:35], 0, s[82:83]
	s_waitcnt lgkmcnt(0)
	s_barrier
	global_load_dwordx4 v[10:13], v[2:3], off nt
	global_load_dwordx4 v[30:33], v[2:3], off offset:16 nt
	v_lshl_add_u64 v[2:3], v[34:35], 0, s[6:7]
	global_load_dwordx4 v[26:29], v[2:3], off nt
	global_load_dwordx4 v[22:25], v[2:3], off offset:16 nt
	v_mov_b32_e32 v38, 0
	s_and_saveexec_b64 s[6:7], s[0:1]
	s_cbranch_execz .LBB0_430
	global_load_ushort v38, v[2:3], off offset:32

.LBB0_434:
	s_andn2_saveexec_b64 s[6:7], s[6:7]
	s_cbranch_execz .LBB0_427
	v_pk_add_f32 v[110:111], v[84:85], v[114:115]
	v_pk_add_f32 v[84:85], v[84:85], v[114:115] neg_lo:[0,1] neg_hi:[0,1]
	v_mul_f32_e32 v112, 0.5, v110
	v_pk_fma_f32 v[114:115], v[66:67], 0, v[66:67] op_sel:[0,0,1] op_sel_hi:[1,0,0] neg_lo:[1,0,0]
	v_mov_b32_e32 v110, v84
	v_pk_mul_f32 v[110:111], v[110:111], s[78:79]
	s_mov_b32 s8, s45
	v_pk_mul_f32 v[116:117], v[114:115], v[110:111] op_sel:[0,1] op_sel_hi:[1,0]
	v_pk_mul_f32 v[110:111], v[114:115], v[110:111]
	s_mov_b32 s9, s42
	v_sub_f32_e32 v84, v110, v111
	v_fma_mixlo_f16 v93, v85, s79, v84
	v_fma_f32 v84, v85, 0.5, -v84
	v_cvt_f16_f32_sdwa v101, -v84 dst_sel:WORD_1 dst_unused:UNUSED_PAD src0_sel:DWORD
	v_pk_add_f32 v[84:85], v[116:117], v[116:117] op_sel:[0,1] op_sel_hi:[0,1]
	v_pk_add_f32 v[110:111], v[112:113], v[84:85]
	v_pk_add_f32 v[84:85], v[112:113], v[84:85] op_sel_hi:[0,1] neg_lo:[0,1] neg_hi:[0,1]
	v_cvt_pk_f16_f32 v84, v110, v85
	v_lshlrev_b32_e32 v93, 16, v93
	v_or_b32_sdwa v85, v101, v84 dst_sel:DWORD dst_unused:UNUSED_PAD src0_sel:DWORD src1_sel:WORD_1
	v_or_b32_sdwa v84, v93, v84 dst_sel:DWORD dst_unused:UNUSED_PAD src0_sel:DWORD src1_sel:WORD_0
	global_store_dwordx2 v[40:41], v[84:85], off
	v_pk_add_f32 v[84:85], v[86:87], v[108:109]
	v_pk_add_f32 v[86:87], v[86:87], v[108:109] neg_lo:[0,1] neg_hi:[0,1]
	v_mul_f32_e32 v110, 0.5, v84
	v_mov_b32_e32 v84, v67
	v_mov_b32_e32 v108, v67
	v_mov_b32_e32 v109, v66
	v_pk_fma_f32 v[112:113], v[66:67], 0, v[108:109] op_sel_hi:[1,0,1] neg_lo:[0,0,1] neg_hi:[0,0,1]
	v_pk_fma_f32 v[114:115], v[66:67], 0, v[84:85] op_sel_hi:[1,0,1]
	v_mov_b32_e32 v84, v86
	v_pk_mov_b32 v[112:113], v[112:113], v[114:115] op_sel:[1,0]
	v_pk_mul_f32 v[84:85], v[84:85], s[78:79]
	s_mov_b32 s43, s45
	v_pk_mul_f32 v[114:115], v[112:113], v[84:85] op_sel:[0,1] op_sel_hi:[1,0]
	v_pk_mul_f32 v[84:85], v[112:113], v[84:85]
	v_pk_fma_f32 v[112:113], v[108:109], s[68:69], v[36:37] op_sel_hi:[1,1,0]
	v_sub_f32_e32 v84, v84, v85
	v_fma_mixlo_f16 v93, v87, s79, v84
	v_fma_f32 v84, v87, 0.5, -v84
	v_cvt_f16_f32_sdwa v101, -v84 dst_sel:WORD_1 dst_unused:UNUSED_PAD src0_sel:DWORD
	v_pk_add_f32 v[84:85], v[114:115], v[114:115] op_sel:[0,1] op_sel_hi:[0,1]
	v_pk_add_f32 v[86:87], v[110:111], v[84:85]
	v_pk_add_f32 v[84:85], v[110:111], v[84:85] op_sel_hi:[0,1] neg_lo:[0,1] neg_hi:[0,1]
	v_cvt_pk_f16_f32 v84, v86, v85
	v_lshlrev_b32_e32 v86, 16, v93
	v_or_b32_sdwa v85, v101, v84 dst_sel:DWORD dst_unused:UNUSED_PAD src0_sel:DWORD src1_sel:WORD_1
	v_or_b32_sdwa v84, v86, v84 dst_sel:DWORD dst_unused:UNUSED_PAD src0_sel:DWORD src1_sel:WORD_0
	global_store_dwordx2 v[40:41], v[84:85], off offset:2048
	v_pk_mul_f32 v[84:85], v[108:109], s[68:69]
	v_pk_add_f32 v[86:87], v[78:79], v[106:107]
	v_pk_add_f32 v[78:79], v[78:79], v[106:107] neg_lo:[0,1] neg_hi:[0,1]
	v_mul_f32_e32 v110, 0.5, v86
	v_pk_add_f32 v[106:107], v[36:37], v[84:85] op_sel:[0,1] op_sel_hi:[0,1] neg_lo:[0,1] neg_hi:[0,1]
	v_mov_b32_e32 v86, v78
	v_mov_b32_e32 v107, v113
	v_pk_mul_f32 v[86:87], v[86:87], s[78:79]
	v_mov_b32_e32 v101, v76
	v_pk_mul_f32 v[112:113], v[106:107], v[86:87] op_sel:[0,1] op_sel_hi:[1,0]
	v_pk_mul_f32 v[86:87], v[106:107], v[86:87]
	s_mov_b32 s39, s27
	v_sub_f32_e32 v36, v86, v87
	v_fma_mixlo_f16 v93, v79, s79, v36
	v_fma_f32 v36, v79, 0.5, -v36
	v_cvt_f16_f32_sdwa v36, -v36 dst_sel:WORD_1 dst_unused:UNUSED_PAD src0_sel:DWORD
	v_pk_add_f32 v[78:79], v[112:113], v[112:113] op_sel:[0,1] op_sel_hi:[0,1]
	v_pk_add_f32 v[86:87], v[110:111], v[78:79]
	v_pk_add_f32 v[78:79], v[110:111], v[78:79] op_sel_hi:[0,1] neg_lo:[0,1] neg_hi:[0,1]
	v_cvt_pk_f16_f32 v78, v86, v79
	v_lshlrev_b32_e32 v86, 16, v93
	v_or_b32_sdwa v79, v36, v78 dst_sel:DWORD dst_unused:UNUSED_PAD src0_sel:DWORD src1_sel:WORD_1
	v_or_b32_sdwa v78, v86, v78 dst_sel:DWORD dst_unused:UNUSED_PAD src0_sel:DWORD src1_sel:WORD_0
	v_add_co_u32_e32 v86, vcc, s34, v40
	v_mov_b32_e32 v93, v80
	s_nop 0
	v_addc_co_u32_e32 v87, vcc, 0, v41, vcc
	v_add_co_u32_e32 v110, vcc, s3, v40
	s_mov_b32 s82, s27
	s_nop 0
	v_addc_co_u32_e32 v111, vcc, 0, v41, vcc
	global_store_dwordx2 v[110:111], v[78:79], off offset:-4096
	v_pk_fma_f32 v[78:79], v[108:109], s[68:69], v[84:85] op_sel:[0,0,1] op_sel_hi:[1,1,0] neg_lo:[0,0,1] neg_hi:[0,0,1]
	v_pk_add_f32 v[84:85], v[74:75], v[104:105]
	v_pk_add_f32 v[74:75], v[74:75], v[104:105] neg_lo:[0,1] neg_hi:[0,1]
	v_mul_f32_e32 v36, 0.5, v84
	v_mov_b32_e32 v84, v74
	v_pk_mul_f32 v[84:85], v[84:85], s[78:79]
	v_mov_b32_e32 v79, v106
	v_mov_b32_e32 v107, v78
	v_pk_mul_f32 v[78:79], v[78:79], v[84:85]
	v_pk_mul_f32 v[104:105], v[106:107], v[84:85]
	v_sub_f32_e32 v74, v78, v79
	v_fma_mixlo_f16 v84, v75, s79, v74
	v_fma_f32 v74, v75, 0.5, -v74
	v_cvt_f16_f32_sdwa v85, -v74 dst_sel:WORD_1 dst_unused:UNUSED_PAD src0_sel:DWORD
	v_pk_add_f32 v[74:75], v[104:105], v[104:105] op_sel:[1,0] op_sel_hi:[1,0]
	s_mov_b32 s83, s38
	v_pk_add_f32 v[78:79], v[36:37], v[74:75]
	v_pk_add_f32 v[74:75], v[36:37], v[74:75] op_sel_hi:[0,1] neg_lo:[0,1] neg_hi:[0,1]
	v_cvt_pk_f16_f32 v36, v78, v75
	v_lshlrev_b32_e32 v74, 16, v84
	v_or_b32_sdwa v75, v85, v36 dst_sel:DWORD dst_unused:UNUSED_PAD src0_sel:DWORD src1_sel:WORD_1
	v_or_b32_sdwa v74, v74, v36 dst_sel:DWORD dst_unused:UNUSED_PAD src0_sel:DWORD src1_sel:WORD_0
	global_store_dwordx2 v[86:87], v[74:75], off offset:2048
	v_mov_b32_e32 v36, v67
	v_pk_mul_f32 v[66:67], v[66:67], s[8:9] op_sel_hi:[0,1]
	v_pk_add_f32 v[74:75], v[72:73], v[102:103]
	v_pk_add_f32 v[72:73], v[72:73], v[102:103] neg_lo:[0,1] neg_hi:[0,1]
	v_mul_f32_e32 v78, 0.5, v74
	v_pk_fma_f32 v[84:85], v[36:37], s[42:43], v[66:67] op_sel_hi:[0,1,1] neg_lo:[0,0,1] neg_hi:[0,0,1]
	v_pk_fma_f32 v[86:87], v[36:37], s[42:43], v[66:67] op_sel_hi:[0,1,1]
	v_mov_b32_e32 v74, v72
	v_mov_b32_e32 v102, v84
	v_mov_b32_e32 v103, v87
	v_pk_mul_f32 v[74:75], v[74:75], s[78:79]
	s_nop 0
	v_pk_mul_f32 v[104:105], v[102:103], v[74:75] op_sel:[0,1] op_sel_hi:[1,0]
	v_pk_mul_f32 v[74:75], v[102:103], v[74:75]
	s_nop 0
	v_sub_f32_e32 v36, v74, v75
	v_fma_mixlo_f16 v79, v73, s79, v36
	v_fma_f32 v36, v73, 0.5, -v36
	v_cvt_f16_f32_sdwa v36, -v36 dst_sel:WORD_1 dst_unused:UNUSED_PAD src0_sel:DWORD
	v_pk_add_f32 v[72:73], v[104:105], v[104:105] op_sel:[0,1] op_sel_hi:[0,1]
	v_pk_add_f32 v[74:75], v[78:79], v[72:73]
	v_pk_add_f32 v[72:73], v[78:79], v[72:73] op_sel_hi:[0,1] neg_lo:[0,1] neg_hi:[0,1]
	v_cvt_pk_f16_f32 v72, v74, v73
	v_lshlrev_b32_e32 v74, 16, v79
	v_or_b32_sdwa v73, v36, v72 dst_sel:DWORD dst_unused:UNUSED_PAD src0_sel:DWORD src1_sel:WORD_1
	v_or_b32_sdwa v72, v74, v72 dst_sel:DWORD dst_unused:UNUSED_PAD src0_sel:DWORD src1_sel:WORD_0
	global_store_dwordx2 v[110:111], v[72:73], off
	v_pk_add_f32 v[72:73], v[76:77], v[98:99]
	v_sub_f32_e32 v75, v77, v99
	v_pk_mov_b32 v[76:77], v[66:67], v[98:99] op_sel:[1,0]
	v_mul_f32_e32 v36, 0.5, v73
	v_pk_add_f32 v[76:77], v[100:101], v[76:77] neg_lo:[0,1] neg_hi:[0,1]
	v_mul_f32_e32 v74, 0.5, v72
	v_pk_mul_f32 v[78:79], v[76:77], v[36:37]
	s_nop 0
	v_mul_f32_e32 v67, v76, v79
	v_fma_f32 v36, -v84, v36, v67
	v_fma_mixlo_f16 v67, v75, s79, v36
	v_fma_f32 v36, v75, 0.5, -v36
	v_cvt_f16_f32_sdwa v36, -v36 dst_sel:WORD_1 dst_unused:UNUSED_PAD src0_sel:DWORD
	v_pk_fma_f32 v[98:99], v[84:85], v[78:79], v[78:79] op_sel:[0,1,0] op_sel_hi:[1,0,1]
	v_lshlrev_b32_e32 v67, 16, v67
	v_pk_add_f32 v[74:75], v[74:75], v[98:99]
	v_fma_f32 v72, v72, 0.5, -v98
	v_cvt_pk_f16_f32 v72, v74, v72
	v_or_b32_sdwa v73, v36, v72 dst_sel:DWORD dst_unused:UNUSED_PAD src0_sel:DWORD src1_sel:WORD_1
	v_or_b32_sdwa v72, v67, v72 dst_sel:DWORD dst_unused:UNUSED_PAD src0_sel:DWORD src1_sel:WORD_0
	global_store_dwordx2 v[110:111], v[72:73], off offset:2048
	v_pk_add_f32 v[72:73], v[96:97], v[82:83]
	v_pk_add_f32 v[74:75], v[82:83], v[96:97] neg_lo:[0,1] neg_hi:[0,1]
	v_mul_f32_e32 v36, 0.5, v72
	v_mov_b32_e32 v72, v74
	v_pk_mov_b32 v[76:77], v[84:85], v[86:87] op_sel:[1,0]
	v_pk_mul_f32 v[72:73], v[72:73], s[78:79]
	v_sub_f32_e32 v83, v81, v89
	v_pk_mul_f32 v[78:79], v[76:77], v[72:73] op_sel:[0,1] op_sel_hi:[1,0]
	v_pk_mul_f32 v[72:73], v[76:77], v[72:73]
	s_nop 0
	v_sub_f32_e32 v67, v72, v73
	v_fma_mixlo_f16 v82, v75, s79, v67
	v_fma_f32 v67, v75, 0.5, -v67
	v_pk_add_f32 v[72:73], v[78:79], v[78:79] op_sel:[0,1] op_sel_hi:[0,1]
	v_cvt_f16_f32_sdwa v67, -v67 dst_sel:WORD_1 dst_unused:UNUSED_PAD src0_sel:DWORD
	v_pk_add_f32 v[74:75], v[36:37], v[72:73]
	v_pk_add_f32 v[72:73], v[36:37], v[72:73] op_sel_hi:[0,1] neg_lo:[0,1] neg_hi:[0,1]
	v_cvt_pk_f16_f32 v36, v74, v73
	v_add_co_u32_e32 v74, vcc, s35, v40
	v_lshlrev_b32_e32 v72, 16, v82
	s_nop 0
	v_addc_co_u32_e32 v75, vcc, 0, v41, vcc
	v_add_co_u32_e32 v78, vcc, s37, v40
	v_or_b32_sdwa v73, v67, v36 dst_sel:DWORD dst_unused:UNUSED_PAD src0_sel:DWORD src1_sel:WORD_1
	v_or_b32_sdwa v72, v72, v36 dst_sel:DWORD dst_unused:UNUSED_PAD src0_sel:DWORD src1_sel:WORD_0
	v_addc_co_u32_e32 v79, vcc, 0, v41, vcc
	global_store_dwordx2 v[78:79], v[72:73], off offset:-4096
	v_pk_add_f32 v[72:73], v[88:89], v[80:81]
	v_mov_b32_e32 v67, v88
	v_mul_f32_e32 v36, 0.5, v73
	v_pk_add_f32 v[66:67], v[92:93], v[66:67] neg_lo:[0,1] neg_hi:[0,1]
	v_mul_f32_e32 v82, 0.5, v72
	v_pk_mul_f32 v[80:81], v[66:67], v[36:37]
	s_nop 0
	v_mul_f32_e32 v66, v66, v81
	v_fma_f32 v36, -v85, v36, v66
	v_fma_mixlo_f16 v73, v83, s79, v36
	v_fma_f32 v36, v83, 0.5, -v36
	v_pk_fma_f32 v[76:77], v[76:77], v[80:81], v[80:81] op_sel:[0,1,0] op_sel_hi:[1,0,1]
	v_cvt_f16_f32_sdwa v36, -v36 dst_sel:WORD_1 dst_unused:UNUSED_PAD src0_sel:DWORD
	v_pk_add_f32 v[66:67], v[82:83], v[76:77]
	s_nop 0
	v_fma_f32 v67, v72, 0.5, -v76
	v_cvt_pk_f16_f32 v66, v66, v67
	v_lshlrev_b32_e32 v72, 16, v73
	v_or_b32_sdwa v67, v36, v66 dst_sel:DWORD dst_unused:UNUSED_PAD src0_sel:DWORD src1_sel:WORD_1
	v_sub_f32_e32 v36, v94, v95
	v_or_b32_sdwa v66, v72, v66 dst_sel:DWORD dst_unused:UNUSED_PAD src0_sel:DWORD src1_sel:WORD_0
	v_cvt_f16_f32_sdwa v72, -v91 dst_sel:WORD_1 dst_unused:UNUSED_PAD src0_sel:DWORD
	v_cvt_f16_f32_sdwa v36, v36 dst_sel:WORD_1 dst_unused:UNUSED_PAD src0_sel:DWORD
	global_store_dwordx2 v[74:75], v[66:67], off offset:2048
	v_pk_add_f32 v[66:67], v[94:95], v[94:95] op_sel:[0,1] op_sel_hi:[1,0]
	s_nop 0
	v_cvt_pk_f16_f32 v66, v66, v90
	v_or_b32_sdwa v67, v72, v66 dst_sel:DWORD dst_unused:UNUSED_PAD src0_sel:DWORD src1_sel:WORD_1
	v_or_b32_sdwa v66, v36, v66 dst_sel:DWORD dst_unused:UNUSED_PAD src0_sel:DWORD src1_sel:WORD_0
	global_store_dwordx2 v[78:79], v[66:67], off
	v_pk_add_f32 v[66:67], v[60:61], v[48:49]
	v_pk_add_f32 v[48:49], v[60:61], v[48:49] neg_lo:[0,1] neg_hi:[0,1]
	v_mul_f32_e32 v36, 0.5, v66
	v_mov_b32_e32 v66, v48
	v_pk_mul_f32 v[60:61], v[66:67], s[78:79]
	s_nop 0
	v_pk_mul_f32 v[66:67], v[60:61], s[38:39]
	v_pk_mul_f32 v[60:61], v[60:61], s[82:83]
	s_mov_b32 s82, s47
	v_sub_f32_e32 v48, v60, v61
	v_fma_mixlo_f16 v72, v49, s79, v48
	v_fma_f32 v48, v49, 0.5, -v48
	v_cvt_f16_f32_sdwa v73, -v48 dst_sel:WORD_1 dst_unused:UNUSED_PAD src0_sel:DWORD
	v_pk_add_f32 v[48:49], v[66:67], v[66:67] op_sel:[1,0] op_sel_hi:[1,0]
	s_mov_b32 s83, s46
	v_pk_add_f32 v[60:61], v[36:37], v[48:49]
	v_pk_add_f32 v[48:49], v[36:37], v[48:49] op_sel_hi:[0,1] neg_lo:[0,1] neg_hi:[0,1]
	v_cvt_pk_f16_f32 v36, v60, v49
	v_lshlrev_b32_e32 v48, 16, v72
	v_or_b32_sdwa v49, v73, v36 dst_sel:DWORD dst_unused:UNUSED_PAD src0_sel:DWORD src1_sel:WORD_1
	v_or_b32_sdwa v48, v48, v36 dst_sel:DWORD dst_unused:UNUSED_PAD src0_sel:DWORD src1_sel:WORD_0
	global_store_dwordx2 v[78:79], v[48:49], off offset:2048
	v_pk_add_f32 v[48:49], v[68:69], v[62:63]
	v_pk_add_f32 v[60:61], v[68:69], v[62:63] neg_lo:[0,1] neg_hi:[0,1]
	v_mul_f32_e32 v36, 0.5, v48
	v_mov_b32_e32 v48, v60
	v_pk_mul_f32 v[48:49], v[48:49], s[78:79]
	s_nop 0
	v_pk_mul_f32 v[62:63], v[48:49], s[8:9]
	v_pk_mul_f32 v[48:49], v[48:49], s[42:43]
	s_nop 0
	v_sub_f32_e32 v48, v48, v49
	v_fma_mixlo_f16 v66, v61, s79, v48
	v_fma_f32 v48, v61, 0.5, -v48
	v_cvt_f16_f32_sdwa v67, -v48 dst_sel:WORD_1 dst_unused:UNUSED_PAD src0_sel:DWORD
	v_pk_add_f32 v[48:49], v[62:63], v[62:63] op_sel:[1,0] op_sel_hi:[1,0]
	s_nop 0
	v_pk_add_f32 v[60:61], v[36:37], v[48:49]
	v_pk_add_f32 v[48:49], v[36:37], v[48:49] op_sel_hi:[0,1] neg_lo:[0,1] neg_hi:[0,1]
	v_cvt_pk_f16_f32 v36, v60, v49
	v_add_co_u32_e32 v60, vcc, s51, v40
	v_lshlrev_b32_e32 v48, 16, v66
	s_nop 0
	v_addc_co_u32_e32 v61, vcc, 0, v41, vcc
	v_add_co_u32_e32 v62, vcc, s60, v40
	v_or_b32_sdwa v49, v67, v36 dst_sel:DWORD dst_unused:UNUSED_PAD src0_sel:DWORD src1_sel:WORD_1
	v_or_b32_sdwa v48, v48, v36 dst_sel:DWORD dst_unused:UNUSED_PAD src0_sel:DWORD src1_sel:WORD_0
	v_addc_co_u32_e32 v63, vcc, 0, v41, vcc
	global_store_dwordx2 v[62:63], v[48:49], off offset:-4096
	v_pk_add_f32 v[48:49], v[50:51], v[54:55]
	v_pk_add_f32 v[50:51], v[50:51], v[54:55] neg_lo:[0,1] neg_hi:[0,1]
	v_mul_f32_e32 v36, 0.5, v48
	v_mov_b32_e32 v48, v50
	v_pk_mul_f32 v[48:49], v[48:49], s[78:79]
	s_nop 0
	v_pk_mul_f32 v[54:55], v[48:49], s[46:47]
	v_pk_mul_f32 v[48:49], v[48:49], s[82:83]
	s_nop 0
	v_sub_f32_e32 v48, v48, v49
	v_fma_mixlo_f16 v66, v51, s79, v48
	v_fma_f32 v48, v51, 0.5, -v48
	v_cvt_f16_f32_sdwa v67, -v48 dst_sel:WORD_1 dst_unused:UNUSED_PAD src0_sel:DWORD
	v_pk_add_f32 v[48:49], v[54:55], v[54:55] op_sel:[1,0] op_sel_hi:[1,0]
	s_nop 0
	v_pk_add_f32 v[50:51], v[36:37], v[48:49]
	v_pk_add_f32 v[48:49], v[36:37], v[48:49] op_sel_hi:[0,1] neg_lo:[0,1] neg_hi:[0,1]
	v_cvt_pk_f16_f32 v36, v50, v49
	v_lshlrev_b32_e32 v48, 16, v66
	v_or_b32_sdwa v49, v67, v36 dst_sel:DWORD dst_unused:UNUSED_PAD src0_sel:DWORD src1_sel:WORD_1
	v_or_b32_sdwa v48, v48, v36 dst_sel:DWORD dst_unused:UNUSED_PAD src0_sel:DWORD src1_sel:WORD_0
	global_store_dwordx2 v[60:61], v[48:49], off offset:2048
	v_pk_add_f32 v[48:49], v[70:71], v[64:65]
	v_pk_add_f32 v[50:51], v[70:71], v[64:65] neg_lo:[0,1] neg_hi:[0,1]
	v_mul_f32_e32 v36, 0.5, v48
	v_mov_b32_e32 v48, v50
	v_pk_mul_f32 v[48:49], v[48:49], s[78:79]
	s_nop 0
	v_pk_mul_f32 v[48:49], s[64:65], v[48:49] op_sel_hi:[0,1]
	v_sub_f32_e32 v50, v48, v49
	v_fma_mixlo_f16 v54, v51, s79, v50
	v_fma_f32 v50, v51, 0.5, -v50
	v_cvt_f16_f32_sdwa v55, -v50 dst_sel:WORD_1 dst_unused:UNUSED_PAD src0_sel:DWORD
	v_pk_add_f32 v[48:49], v[48:49], v[48:49] op_sel:[1,0] op_sel_hi:[1,0]
	s_nop 0
	v_pk_add_f32 v[50:51], v[36:37], v[48:49]
	v_pk_add_f32 v[48:49], v[36:37], v[48:49] op_sel_hi:[0,1] neg_lo:[0,1] neg_hi:[0,1]
	v_cvt_pk_f16_f32 v36, v50, v49
	v_lshlrev_b32_e32 v48, 16, v54
	v_or_b32_sdwa v49, v55, v36 dst_sel:DWORD dst_unused:UNUSED_PAD src0_sel:DWORD src1_sel:WORD_1
	v_or_b32_sdwa v48, v48, v36 dst_sel:DWORD dst_unused:UNUSED_PAD src0_sel:DWORD src1_sel:WORD_0
	global_store_dwordx2 v[62:63], v[48:49], off
	v_pk_add_f32 v[48:49], v[52:53], v[44:45]
	v_pk_add_f32 v[44:45], v[52:53], v[44:45] neg_lo:[0,1] neg_hi:[0,1]
	v_mul_f32_e32 v36, 0.5, v48
	v_mov_b32_e32 v48, v44
	v_pk_mul_f32 v[48:49], v[48:49], s[78:79]
	s_nop 0
	v_pk_mul_f32 v[50:51], v[48:49], s[82:83]
	v_pk_mul_f32 v[48:49], v[48:49], s[46:47]
	s_nop 0
	v_sub_f32_e32 v44, v48, v49
	v_fma_mixlo_f16 v52, v45, s79, v44
	v_fma_f32 v44, v45, 0.5, -v44
	v_cvt_f16_f32_sdwa v53, -v44 dst_sel:WORD_1 dst_unused:UNUSED_PAD src0_sel:DWORD
	v_pk_add_f32 v[44:45], v[50:51], v[50:51] op_sel:[1,0] op_sel_hi:[1,0]
	s_nop 0
	v_pk_add_f32 v[48:49], v[36:37], v[44:45]
	v_pk_add_f32 v[44:45], v[36:37], v[44:45] op_sel_hi:[0,1] neg_lo:[0,1] neg_hi:[0,1]
	v_cvt_pk_f16_f32 v36, v48, v45
	v_lshlrev_b32_e32 v44, 16, v52
	v_or_b32_sdwa v45, v53, v36 dst_sel:DWORD dst_unused:UNUSED_PAD src0_sel:DWORD src1_sel:WORD_1
	v_or_b32_sdwa v44, v44, v36 dst_sel:DWORD dst_unused:UNUSED_PAD src0_sel:DWORD src1_sel:WORD_0
	global_store_dwordx2 v[62:63], v[44:45], off offset:2048
	v_pk_add_f32 v[44:45], v[58:59], v[56:57]
	v_pk_add_f32 v[48:49], v[56:57], v[58:59] neg_lo:[0,1] neg_hi:[0,1]
	v_mul_f32_e32 v36, 0.5, v44
	v_mov_b32_e32 v44, v48
	v_pk_mul_f32 v[44:45], v[44:45], s[78:79]
	s_nop 0
	v_pk_mul_f32 v[50:51], v[44:45], s[42:43]
	v_pk_mul_f32 v[44:45], v[44:45], s[8:9]
	s_mov_b32 s8, s27
	v_sub_f32_e32 v44, v44, v45
	v_fma_mixlo_f16 v52, v49, s79, v44
	v_fma_f32 v44, v49, 0.5, -v44
	v_cvt_f16_f32_sdwa v53, -v44 dst_sel:WORD_1 dst_unused:UNUSED_PAD src0_sel:DWORD
	v_pk_add_f32 v[44:45], v[50:51], v[50:51] op_sel:[1,0] op_sel_hi:[1,0]
	s_nop 0
	v_pk_add_f32 v[48:49], v[36:37], v[44:45]
	v_pk_add_f32 v[44:45], v[36:37], v[44:45] op_sel_hi:[0,1] neg_lo:[0,1] neg_hi:[0,1]
	v_cvt_pk_f16_f32 v36, v48, v45
	v_pk_add_f32 v[48:49], v[42:43], v[46:47]
	v_pk_add_f32 v[42:43], v[42:43], v[46:47] neg_lo:[0,1] neg_hi:[0,1]
	v_mov_b32_e32 v46, v48
	v_mov_b32_e32 v47, v43
	v_mov_b32_e32 v43, v49
	v_pk_mul_f32 v[42:43], v[42:43], s[78:79]
	v_lshlrev_b32_e32 v44, 16, v52
	v_pk_mul_f32 v[48:49], v[42:43], s[38:39] op_sel_hi:[1,0]
	v_or_b32_sdwa v45, v53, v36 dst_sel:DWORD dst_unused:UNUSED_PAD src0_sel:DWORD src1_sel:WORD_1
	v_pk_fma_f32 v[50:51], v[42:43], s[8:9], v[48:49] op_sel:[0,0,1] op_sel_hi:[1,0,0] neg_hi:[1,0,0]
	s_nop 0
	v_or_b32_sdwa v44, v44, v36 dst_sel:DWORD dst_unused:UNUSED_PAD src0_sel:DWORD src1_sel:WORD_0
	s_nop 0
	v_pk_fma_f32 v[42:43], v[46:47], 0.5, v[50:51] op_sel_hi:[1,0,1]
	v_pk_fma_f32 v[112:113], v[46:47], 0.5, v[50:51] op_sel_hi:[1,0,1] neg_lo:[0,0,1] neg_hi:[0,0,1]
	v_cvt_f16_f32_e32 v36, v42
	v_cvt_f16_f32_sdwa v48, v43 dst_sel:WORD_1 dst_unused:UNUSED_PAD src0_sel:DWORD
	v_add_co_u32_e32 v42, vcc, s61, v40
	v_or_b32_e32 v110, v48, v36
	s_nop 0
	v_addc_co_u32_e32 v43, vcc, 0, v41, vcc
	global_store_dwordx2 v[42:43], v[44:45], off
	s_branch .LBB0_427

.LBB0_503:
	s_or_b64 exec, exec, s[0:1]
	v_pk_mul_f32 v[22:23], v[32:33], s[6:7] op_sel_hi:[1,0]
	v_pk_add_f32 v[26:27], v[24:25], v[30:31]
	v_pk_add_f32 v[24:25], v[24:25], v[30:31] neg_lo:[0,1] neg_hi:[0,1]
	v_pk_add_f32 v[30:31], v[64:65], v[68:69]
	v_pk_add_f32 v[32:33], v[64:65], v[68:69] neg_lo:[0,1] neg_hi:[0,1]
	v_pk_add_f32 v[34:35], v[62:63], v[90:91]
	v_pk_add_f32 v[38:39], v[94:95], v[80:81]
	v_pk_add_f32 v[40:41], v[94:95], v[80:81] neg_lo:[0,1] neg_hi:[0,1]
	v_pk_add_f32 v[68:69], v[26:27], v[30:31]
	v_pk_add_f32 v[26:27], v[26:27], v[30:31] neg_lo:[0,1] neg_hi:[0,1]
	v_xor_b32_e32 v30, 0x80000000, v33
	v_mov_b32_e32 v31, v32
	v_pk_mul_f32 v[20:21], v[50:51], s[6:7] op_sel_hi:[1,0]
	v_pk_add_f32 v[36:37], v[62:63], v[90:91] neg_lo:[0,1] neg_hi:[0,1]
	v_pk_add_f32 v[42:43], v[78:79], v[136:137]
	v_pk_add_f32 v[46:47], v[130:131], v[120:121]
	v_pk_add_f32 v[50:51], v[130:131], v[120:121] neg_lo:[0,1] neg_hi:[0,1]
	v_pk_add_f32 v[32:33], v[24:25], v[30:31]
	v_pk_add_f32 v[24:25], v[24:25], v[30:31] neg_lo:[0,1] neg_hi:[0,1]
	v_pk_add_f32 v[30:31], v[34:35], v[38:39]
	v_pk_add_f32 v[34:35], v[34:35], v[38:39] neg_lo:[0,1] neg_hi:[0,1]
	v_xor_b32_e32 v38, 0x80000000, v41
	v_mov_b32_e32 v39, v40
	v_pk_add_f32 v[44:45], v[78:79], v[136:137] neg_lo:[0,1] neg_hi:[0,1]
	v_pk_add_f32 v[60:61], v[128:129], v[150:151]
	v_pk_add_f32 v[64:65], v[168:169], v[144:145]
	v_pk_add_f32 v[66:67], v[168:169], v[144:145] neg_lo:[0,1] neg_hi:[0,1]
	v_pk_add_f32 v[40:41], v[36:37], v[38:39]
	v_pk_add_f32 v[36:37], v[36:37], v[38:39] neg_lo:[0,1] neg_hi:[0,1]
	v_pk_add_f32 v[38:39], v[42:43], v[46:47]
	v_pk_add_f32 v[42:43], v[42:43], v[46:47] neg_lo:[0,1] neg_hi:[0,1]
	v_xor_b32_e32 v46, 0x80000000, v51
	v_mov_b32_e32 v47, v50
	v_pk_add_f32 v[62:63], v[128:129], v[150:151] neg_lo:[0,1] neg_hi:[0,1]
	v_pk_add_f32 v[50:51], v[44:45], v[46:47]
	v_pk_add_f32 v[44:45], v[44:45], v[46:47] neg_lo:[0,1] neg_hi:[0,1]
	v_pk_add_f32 v[46:47], v[60:61], v[64:65]
	v_pk_add_f32 v[60:61], v[60:61], v[64:65] neg_lo:[0,1] neg_hi:[0,1]
	v_xor_b32_e32 v64, 0x80000000, v67
	v_mov_b32_e32 v65, v66
	s_mov_b32 s78, s37
	s_mov_b32 s79, s36
	v_pk_add_f32 v[66:67], v[62:63], v[64:65]
	v_pk_add_f32 v[62:63], v[62:63], v[64:65] neg_lo:[0,1] neg_hi:[0,1]
	v_pk_add_f32 v[64:65], v[68:69], v[30:31]
	v_pk_add_f32 v[30:31], v[68:69], v[30:31] neg_lo:[0,1] neg_hi:[0,1]
	s_mov_b32 s0, s37
	v_pk_mul_f32 v[68:69], v[40:41], s[78:79]
	s_mov_b32 s80, s19
	v_pk_fma_f32 v[40:41], v[40:41], s[0:1], v[68:69] op_sel:[0,0,1] op_sel_hi:[1,0,0]
	s_mov_b32 s81, s18
	v_pk_add_f32 v[68:69], v[32:33], v[40:41]
	v_pk_add_f32 v[32:33], v[32:33], v[40:41] neg_lo:[0,1] neg_hi:[0,1]
	v_xor_b32_e32 v40, 0x80000000, v35
	v_mov_b32_e32 v41, v34
	v_pk_add_f32 v[34:35], v[26:27], v[40:41]
	v_pk_add_f32 v[26:27], v[26:27], v[40:41] neg_lo:[0,1] neg_hi:[0,1]
	v_pk_mul_f32 v[40:41], v[36:37], s[78:79]
	s_mov_b32 s82, s19
	v_pk_fma_f32 v[36:37], v[36:37], s[0:1], v[40:41] op_sel:[0,0,1] op_sel_hi:[1,0,0] neg_lo:[1,0,0] neg_hi:[1,0,0]
	v_pk_mul_f32 v[2:3], v[72:73], s[6:7] op_sel_hi:[1,0]
	v_pk_add_f32 v[40:41], v[24:25], v[36:37]
	v_pk_add_f32 v[24:25], v[24:25], v[36:37] neg_lo:[0,1] neg_hi:[0,1]
	v_pk_add_f32 v[36:37], v[38:39], v[46:47]
	v_pk_add_f32 v[38:39], v[38:39], v[46:47] neg_lo:[0,1] neg_hi:[0,1]
	v_pk_mul_f32 v[46:47], v[66:67], s[78:79]
	v_pk_mul_f32 v[8:9], v[70:71], s[6:7] op_sel_hi:[1,0]
	v_pk_fma_f32 v[46:47], v[66:67], s[0:1], v[46:47] op_sel:[0,0,1] op_sel_hi:[1,0,0]
	v_pk_mul_f32 v[10:11], v[76:77], s[6:7] op_sel_hi:[1,0]
	v_pk_add_f32 v[66:67], v[50:51], v[46:47]
	v_pk_add_f32 v[46:47], v[50:51], v[46:47] neg_lo:[0,1] neg_hi:[0,1]
	v_xor_b32_e32 v50, 0x80000000, v61
	v_mov_b32_e32 v51, v60
	v_pk_add_f32 v[60:61], v[42:43], v[50:51]
	v_pk_add_f32 v[42:43], v[42:43], v[50:51] neg_lo:[0,1] neg_hi:[0,1]
	v_pk_mul_f32 v[50:51], v[62:63], s[78:79]
	v_pk_mul_f32 v[14:15], v[74:75], s[6:7] op_sel_hi:[1,0]
	v_pk_fma_f32 v[50:51], v[62:63], s[0:1], v[50:51] op_sel:[0,0,1] op_sel_hi:[1,0,0] neg_lo:[1,0,0] neg_hi:[1,0,0]
	v_pk_mul_f32 v[16:17], v[16:17], s[6:7] op_sel_hi:[1,0]
	v_pk_add_f32 v[62:63], v[44:45], v[50:51]
	v_pk_add_f32 v[44:45], v[44:45], v[50:51] neg_lo:[0,1] neg_hi:[0,1]
	v_pk_add_f32 v[50:51], v[64:65], v[36:37]
	v_pk_add_f32 v[36:37], v[64:65], v[36:37] neg_lo:[0,1] neg_hi:[0,1]
	v_pk_mul_f32 v[64:65], v[66:67], s[80:81]
	v_pk_mul_f32 v[6:7], v[6:7], s[6:7] op_sel_hi:[1,0]
	v_pk_fma_f32 v[64:65], v[66:67], s[16:17], v[64:65] op_sel:[0,0,1] op_sel_hi:[1,0,0]
	s_mov_b32 s17, s40
	v_pk_add_f32 v[66:67], v[68:69], v[64:65]
	v_pk_add_f32 v[64:65], v[68:69], v[64:65] neg_lo:[0,1] neg_hi:[0,1]
	v_pk_mul_f32 v[68:69], v[60:61], s[78:79]
	s_mov_b32 s88, s11
	v_pk_fma_f32 v[60:61], v[60:61], s[0:1], v[68:69] op_sel:[0,0,1] op_sel_hi:[1,0,0]
	s_mov_b32 s89, s10
	v_pk_add_f32 v[68:69], v[34:35], v[60:61]
	v_pk_add_f32 v[34:35], v[34:35], v[60:61] neg_lo:[0,1] neg_hi:[0,1]
	v_pk_mul_f32 v[60:61], v[62:63], s[16:17]
	s_mov_b32 s62, s27
	v_pk_fma_f32 v[60:61], v[62:63], s[82:83], v[60:61] op_sel:[0,0,1] op_sel_hi:[1,0,0]
	s_mov_b32 s63, s26
	v_pk_add_f32 v[62:63], v[40:41], v[60:61]
	v_pk_add_f32 v[40:41], v[40:41], v[60:61] neg_lo:[0,1] neg_hi:[0,1]
	v_xor_b32_e32 v60, 0x80000000, v39
	v_mov_b32_e32 v61, v38
	v_pk_add_f32 v[38:39], v[30:31], v[60:61]
	v_pk_add_f32 v[30:31], v[30:31], v[60:61] neg_lo:[0,1] neg_hi:[0,1]
	v_pk_mul_f32 v[60:61], v[46:47], s[16:17]
	s_mov_b32 s84, s27
	v_pk_fma_f32 v[46:47], v[46:47], s[82:83], v[60:61] op_sel:[0,0,1] op_sel_hi:[1,0,0] neg_lo:[1,0,0] neg_hi:[1,0,0]
	s_mov_b32 s86, s11
	v_pk_add_f32 v[60:61], v[32:33], v[46:47]
	v_pk_add_f32 v[32:33], v[32:33], v[46:47] neg_lo:[0,1] neg_hi:[0,1]
	v_pk_mul_f32 v[46:47], v[42:43], s[78:79]
	s_ashr_i32 s73, s72, 31
	v_pk_fma_f32 v[42:43], s[0:1], v[42:43], v[46:47] op_sel:[0,0,1] op_sel_hi:[0,1,0] neg_lo:[0,1,0] neg_hi:[0,1,0]
	v_pk_add_f32 v[46:47], v[26:27], v[42:43]
	v_pk_add_f32 v[26:27], v[26:27], v[42:43] neg_lo:[0,1] neg_hi:[0,1]
	v_pk_mul_f32 v[42:43], v[44:45], s[80:81]
	s_nop 0
	v_pk_fma_f32 v[42:43], s[16:17], v[44:45], v[42:43] op_sel:[0,0,1] op_sel_hi:[0,1,0] neg_lo:[0,1,0] neg_hi:[0,1,0]
	v_pk_add_f32 v[44:45], v[24:25], v[42:43]
	v_pk_add_f32 v[24:25], v[24:25], v[42:43] neg_lo:[0,1] neg_hi:[0,1]
	v_pk_fma_f32 v[42:43], v[58:59], s[6:7], v[2:3] op_sel_hi:[1,0,1]
	v_pk_fma_f32 v[2:3], v[58:59], s[6:7], v[2:3] op_sel_hi:[1,0,1] neg_lo:[0,0,1] neg_hi:[0,0,1]
	v_pk_fma_f32 v[58:59], v[54:55], s[6:7], v[8:9] op_sel_hi:[1,0,1]
	v_pk_fma_f32 v[8:9], v[54:55], s[6:7], v[8:9] op_sel_hi:[1,0,1] neg_lo:[0,0,1] neg_hi:[0,0,1]
	v_pk_fma_f32 v[54:55], v[56:57], s[6:7], v[10:11] op_sel_hi:[1,0,1]
	v_pk_fma_f32 v[10:11], v[56:57], s[6:7], v[10:11] op_sel_hi:[1,0,1] neg_lo:[0,0,1] neg_hi:[0,0,1]
	v_pk_fma_f32 v[56:57], v[52:53], s[6:7], v[14:15] op_sel_hi:[1,0,1]
	v_pk_fma_f32 v[14:15], v[52:53], s[6:7], v[14:15] op_sel_hi:[1,0,1] neg_lo:[0,0,1] neg_hi:[0,0,1]
	v_pk_fma_f32 v[52:53], v[48:49], s[6:7], v[20:21] op_sel_hi:[1,0,1]
	v_pk_fma_f32 v[20:21], v[48:49], s[6:7], v[20:21] op_sel_hi:[1,0,1] neg_lo:[0,0,1] neg_hi:[0,0,1]
	v_pk_fma_f32 v[48:49], v[28:29], s[6:7], v[22:23] op_sel_hi:[1,0,1]
	v_pk_fma_f32 v[22:23], v[28:29], s[6:7], v[22:23] op_sel_hi:[1,0,1] neg_lo:[0,0,1] neg_hi:[0,0,1]
	v_pk_fma_f32 v[28:29], v[12:13], s[6:7], v[16:17] op_sel_hi:[1,0,1]
	v_pk_fma_f32 v[12:13], v[12:13], s[6:7], v[16:17] op_sel_hi:[1,0,1] neg_lo:[0,0,1] neg_hi:[0,0,1]
	v_pk_fma_f32 v[16:17], v[4:5], s[6:7], v[6:7] op_sel_hi:[1,0,1]
	v_pk_fma_f32 v[4:5], v[4:5], s[6:7], v[6:7] op_sel_hi:[1,0,1] neg_lo:[0,0,1] neg_hi:[0,0,1]
	v_pk_add_f32 v[6:7], v[58:59], v[42:43]
	v_pk_add_f32 v[42:43], v[42:43], v[58:59] neg_lo:[0,1] neg_hi:[0,1]
	v_xor_b32_e32 v58, 0x80000000, v9
	v_mov_b32_e32 v59, v8
	v_pk_add_f32 v[8:9], v[2:3], v[58:59]
	v_pk_add_f32 v[2:3], v[2:3], v[58:59] neg_lo:[0,1] neg_hi:[0,1]
	v_pk_add_f32 v[58:59], v[56:57], v[54:55]
	v_pk_add_f32 v[54:55], v[54:55], v[56:57] neg_lo:[0,1] neg_hi:[0,1]
	v_xor_b32_e32 v56, 0x80000000, v15
	v_mov_b32_e32 v57, v14
	v_pk_add_f32 v[14:15], v[10:11], v[56:57]
	v_pk_add_f32 v[10:11], v[10:11], v[56:57] neg_lo:[0,1] neg_hi:[0,1]
	v_pk_add_f32 v[56:57], v[48:49], v[52:53]
	v_pk_add_f32 v[48:49], v[52:53], v[48:49] neg_lo:[0,1] neg_hi:[0,1]
	v_xor_b32_e32 v52, 0x80000000, v23
	v_mov_b32_e32 v53, v22
	v_pk_add_f32 v[22:23], v[20:21], v[52:53]
	v_pk_add_f32 v[20:21], v[20:21], v[52:53] neg_lo:[0,1] neg_hi:[0,1]
	v_pk_add_f32 v[52:53], v[16:17], v[28:29]
	v_pk_add_f32 v[16:17], v[28:29], v[16:17] neg_lo:[0,1] neg_hi:[0,1]
	v_xor_b32_e32 v28, 0x80000000, v5
	v_mov_b32_e32 v29, v4
	v_pk_add_f32 v[4:5], v[12:13], v[28:29]
	v_pk_add_f32 v[12:13], v[12:13], v[28:29] neg_lo:[0,1] neg_hi:[0,1]
	v_pk_add_f32 v[28:29], v[58:59], v[6:7]
	v_pk_add_f32 v[6:7], v[6:7], v[58:59] neg_lo:[0,1] neg_hi:[0,1]
	v_pk_mul_f32 v[58:59], v[14:15], s[78:79]
	s_nop 0
	v_pk_fma_f32 v[14:15], s[0:1], v[14:15], v[58:59] op_sel:[0,0,1] op_sel_hi:[0,1,0]
	v_pk_add_f32 v[58:59], v[14:15], v[8:9]
	v_pk_add_f32 v[8:9], v[8:9], v[14:15] neg_lo:[0,1] neg_hi:[0,1]
	v_xor_b32_e32 v14, 0x80000000, v55
	v_mov_b32_e32 v15, v54
	v_pk_add_f32 v[54:55], v[14:15], v[42:43]
	v_pk_add_f32 v[14:15], v[42:43], v[14:15] neg_lo:[0,1] neg_hi:[0,1]
	v_pk_mul_f32 v[42:43], v[10:11], s[78:79]
	s_nop 0
	v_pk_fma_f32 v[10:11], s[0:1], v[10:11], v[42:43] op_sel:[0,0,1] op_sel_hi:[0,1,0] neg_lo:[0,1,0] neg_hi:[0,1,0]
	v_pk_add_f32 v[42:43], v[10:11], v[2:3]
	v_pk_add_f32 v[2:3], v[2:3], v[10:11] neg_lo:[0,1] neg_hi:[0,1]
	v_pk_add_f32 v[10:11], v[52:53], v[56:57]
	v_pk_add_f32 v[52:53], v[56:57], v[52:53] neg_lo:[0,1] neg_hi:[0,1]
	v_pk_mul_f32 v[56:57], v[4:5], s[78:79]
	s_nop 0
	v_pk_fma_f32 v[4:5], s[0:1], v[4:5], v[56:57] op_sel:[0,0,1] op_sel_hi:[0,1,0]
	v_pk_add_f32 v[56:57], v[4:5], v[22:23]
	v_pk_add_f32 v[4:5], v[22:23], v[4:5] neg_lo:[0,1] neg_hi:[0,1]
	v_xor_b32_e32 v22, 0x80000000, v17
	v_mov_b32_e32 v23, v16
	v_pk_add_f32 v[16:17], v[22:23], v[48:49]
	v_pk_add_f32 v[22:23], v[48:49], v[22:23] neg_lo:[0,1] neg_hi:[0,1]
	v_pk_mul_f32 v[48:49], v[12:13], s[78:79]
	s_nop 0
	v_pk_fma_f32 v[12:13], s[0:1], v[12:13], v[48:49] op_sel:[0,0,1] op_sel_hi:[0,1,0] neg_lo:[0,1,0] neg_hi:[0,1,0]
	v_pk_add_f32 v[48:49], v[12:13], v[20:21]
	v_pk_add_f32 v[12:13], v[20:21], v[12:13] neg_lo:[0,1] neg_hi:[0,1]
	v_pk_add_f32 v[20:21], v[10:11], v[28:29]
	v_pk_add_f32 v[10:11], v[28:29], v[10:11] neg_lo:[0,1] neg_hi:[0,1]
	v_pk_mul_f32 v[28:29], v[56:57], s[80:81]
	s_nop 0
	v_pk_fma_f32 v[28:29], s[16:17], v[56:57], v[28:29] op_sel:[0,0,1] op_sel_hi:[0,1,0]
	v_pk_add_f32 v[56:57], v[28:29], v[58:59]
	v_pk_add_f32 v[28:29], v[58:59], v[28:29] neg_lo:[0,1] neg_hi:[0,1]
	v_pk_mul_f32 v[58:59], v[16:17], s[78:79]
	s_nop 0
	v_pk_fma_f32 v[16:17], s[0:1], v[16:17], v[58:59] op_sel:[0,0,1] op_sel_hi:[0,1,0]
	v_pk_add_f32 v[58:59], v[16:17], v[54:55]
	v_pk_add_f32 v[16:17], v[54:55], v[16:17] neg_lo:[0,1] neg_hi:[0,1]
	v_pk_mul_f32 v[54:55], v[48:49], s[16:17]
	s_nop 0
	v_pk_fma_f32 v[48:49], s[82:83], v[48:49], v[54:55] op_sel:[0,0,1] op_sel_hi:[0,1,0]
	v_pk_add_f32 v[54:55], v[48:49], v[42:43]
	v_pk_add_f32 v[42:43], v[42:43], v[48:49] neg_lo:[0,1] neg_hi:[0,1]
	v_xor_b32_e32 v48, 0x80000000, v53
	v_mov_b32_e32 v49, v52
	v_pk_add_f32 v[52:53], v[48:49], v[6:7]
	v_pk_add_f32 v[6:7], v[6:7], v[48:49] neg_lo:[0,1] neg_hi:[0,1]
	v_pk_mul_f32 v[48:49], v[4:5], s[16:17]
	s_nop 0
	v_pk_fma_f32 v[4:5], s[82:83], v[4:5], v[48:49] op_sel:[0,0,1] op_sel_hi:[0,1,0] neg_lo:[0,1,0] neg_hi:[0,1,0]
	v_pk_add_f32 v[48:49], v[4:5], v[8:9]
	v_pk_add_f32 v[4:5], v[8:9], v[4:5] neg_lo:[0,1] neg_hi:[0,1]
	v_pk_mul_f32 v[8:9], v[22:23], s[78:79]
	s_nop 0
	v_pk_fma_f32 v[8:9], s[0:1], v[22:23], v[8:9] op_sel:[0,0,1] op_sel_hi:[0,1,0] neg_lo:[0,1,0] neg_hi:[0,1,0]
	v_pk_add_f32 v[22:23], v[8:9], v[14:15]
	v_pk_add_f32 v[8:9], v[14:15], v[8:9] neg_lo:[0,1] neg_hi:[0,1]
	v_pk_mul_f32 v[14:15], v[12:13], s[80:81]
	s_nop 0
	v_pk_fma_f32 v[12:13], s[16:17], v[12:13], v[14:15] op_sel:[0,0,1] op_sel_hi:[0,1,0] neg_lo:[0,1,0] neg_hi:[0,1,0]
	v_pk_add_f32 v[14:15], v[12:13], v[2:3]
	v_pk_add_f32 v[2:3], v[2:3], v[12:13] neg_lo:[0,1] neg_hi:[0,1]
	ds_write_b64 v211, v[50:51]
	ds_write_b64 v212, v[20:21]
	ds_write_b64 v211, v[66:67] offset:8
	ds_write_b64 v212, v[56:57] offset:8
	ds_write_b64 v211, v[68:69] offset:16
	ds_write_b64 v212, v[58:59] offset:16
	ds_write_b64 v211, v[62:63] offset:24
	ds_write_b64 v212, v[54:55] offset:24
	ds_write_b64 v211, v[38:39] offset:32
	ds_write_b64 v212, v[52:53] offset:32
	ds_write_b64 v211, v[60:61] offset:40
	ds_write_b64 v212, v[48:49] offset:40
	ds_write_b64 v211, v[46:47] offset:48
	ds_write_b64 v212, v[22:23] offset:48
	ds_write_b64 v211, v[44:45] offset:56
	ds_write_b64 v212, v[14:15] offset:56
	ds_write_b64 v211, v[36:37] offset:64
	ds_write_b64 v212, v[10:11] offset:64
	ds_write_b64 v211, v[64:65] offset:72
	ds_write_b64 v212, v[28:29] offset:72
	ds_write_b64 v211, v[34:35] offset:80
	ds_write_b64 v212, v[16:17] offset:80
	ds_write_b64 v211, v[40:41] offset:88
	ds_write_b64 v212, v[42:43] offset:88
	ds_write_b64 v211, v[30:31] offset:96
	ds_write_b64 v212, v[6:7] offset:96
	ds_write_b64 v211, v[32:33] offset:104
	ds_write_b64 v212, v[4:5] offset:104
	ds_write_b64 v211, v[26:27] offset:112
	ds_write_b64 v212, v[8:9] offset:112
	ds_write_b64 v211, v[24:25] offset:120
	ds_write_b64 v212, v[2:3] offset:120
	v_mov_b32_e32 v2, v210
	s_waitcnt lgkmcnt(0)
	s_barrier
	s_nop 0
	v_and_b32_e32 v3, 15, v2
	v_lshlrev_b32_e32 v5, 3, v3
	v_cvt_f32_ubyte0_e32 v3, v3
	v_mul_f32_e32 v3, 0x3b000000, v3
	v_sin_f32_e32 v17, v3
	v_cos_f32_e32 v16, v3
	v_lshlrev_b32_e32 v2, 5, v2
	v_and_b32_e32 v2, 0xfffffe00, v2
	v_lshl_add_u32 v4, v2, 3, 0
	v_ashrrev_i32_e32 v2, 2, v2
	v_xor_b32_e32 v72, 0x80000000, v17
	v_mov_b32_e32 v73, v17
	v_add3_u32 v2, v4, v5, v2
	v_pk_mul_f32 v[4:5], v[16:17], v[72:73] op_sel:[1,0] op_sel_hi:[0,1]
	v_pk_fma_f32 v[74:75], v[16:17], v[16:17], v[4:5] op_sel_hi:[1,0,1]
	v_add_u32_e32 v3, 0x800, v2
	v_pk_mul_f32 v[4:5], v[72:73], v[74:75] op_sel:[0,1] op_sel_hi:[1,0]
	v_xor_b32_e32 v78, 0x80000000, v75
	v_mov_b32_e32 v79, v75
	v_pk_fma_f32 v[76:77], v[16:17], v[74:75], v[4:5] op_sel_hi:[0,1,1]
	v_pk_mul_f32 v[4:5], v[74:75], v[78:79] op_sel:[1,0] op_sel_hi:[0,1]
	v_pk_fma_f32 v[80:81], v[74:75], v[74:75], v[4:5] op_sel_hi:[1,0,1]
	v_xor_b32_e32 v84, 0x80000000, v77
	v_pk_mul_f32 v[4:5], v[72:73], v[80:81] op_sel:[0,1] op_sel_hi:[1,0]
	v_mov_b32_e32 v85, v77
	v_pk_fma_f32 v[86:87], v[16:17], v[80:81], v[4:5] op_sel_hi:[0,1,1]
	v_pk_mul_f32 v[4:5], v[78:79], v[80:81] op_sel:[0,1] op_sel_hi:[1,0]
	v_xor_b32_e32 v82, 0x80000000, v81
	v_mov_b32_e32 v83, v81
	v_pk_fma_f32 v[90:91], v[74:75], v[80:81], v[4:5] op_sel_hi:[0,1,1]
	v_pk_mul_f32 v[4:5], v[80:81], v[84:85] op_sel:[1,0] op_sel_hi:[0,1]
	v_pk_fma_f32 v[94:95], v[80:81], v[76:77], v[4:5] op_sel_hi:[1,0,1]
	v_pk_mul_f32 v[4:5], v[80:81], v[82:83] op_sel:[1,0] op_sel_hi:[0,1]
	v_pk_fma_f32 v[98:99], v[80:81], v[80:81], v[4:5] op_sel_hi:[1,0,1]
	v_xor_b32_e32 v88, 0x80000000, v87
	v_pk_mul_f32 v[4:5], v[72:73], v[98:99] op_sel:[0,1] op_sel_hi:[1,0]
	v_mov_b32_e32 v89, v87
	v_pk_fma_f32 v[102:103], v[16:17], v[98:99], v[4:5] op_sel_hi:[0,1,1]
	v_pk_mul_f32 v[4:5], v[78:79], v[98:99] op_sel:[0,1] op_sel_hi:[1,0]
	v_xor_b32_e32 v92, 0x80000000, v91
	v_pk_fma_f32 v[106:107], v[74:75], v[98:99], v[4:5] op_sel_hi:[0,1,1]
	v_pk_mul_f32 v[4:5], v[84:85], v[98:99] op_sel:[0,1] op_sel_hi:[1,0]
	v_mov_b32_e32 v93, v91
	v_pk_fma_f32 v[110:111], v[76:77], v[98:99], v[4:5] op_sel_hi:[0,1,1]
	v_pk_mul_f32 v[4:5], v[82:83], v[98:99] op_sel:[0,1] op_sel_hi:[1,0]
	v_xor_b32_e32 v96, 0x80000000, v95
	v_pk_fma_f32 v[114:115], v[80:81], v[98:99], v[4:5] op_sel_hi:[0,1,1]
	v_pk_mul_f32 v[4:5], v[72:73], v[114:115] op_sel:[0,1] op_sel_hi:[1,0]
	v_mov_b32_e32 v97, v95
	v_pk_fma_f32 v[118:119], v[16:17], v[114:115], v[4:5] op_sel_hi:[0,1,1]
	v_pk_mul_f32 v[4:5], v[78:79], v[114:115] op_sel:[0,1] op_sel_hi:[1,0]
	v_xor_b32_e32 v100, 0x80000000, v99
	v_pk_fma_f32 v[122:123], v[74:75], v[114:115], v[4:5] op_sel_hi:[0,1,1]
	v_pk_mul_f32 v[4:5], v[84:85], v[114:115] op_sel:[0,1] op_sel_hi:[1,0]
	v_mov_b32_e32 v101, v99
	v_pk_fma_f32 v[126:127], v[76:77], v[114:115], v[4:5] op_sel_hi:[0,1,1]
	v_pk_mul_f32 v[4:5], v[82:83], v[114:115] op_sel:[0,1] op_sel_hi:[1,0]
	v_xor_b32_e32 v104, 0x80000000, v103
	v_pk_fma_f32 v[130:131], v[80:81], v[114:115], v[4:5] op_sel_hi:[0,1,1]
	v_pk_mul_f32 v[4:5], v[72:73], v[130:131] op_sel:[0,1] op_sel_hi:[1,0]
	v_mov_b32_e32 v105, v103
	v_pk_fma_f32 v[134:135], v[16:17], v[130:131], v[4:5] op_sel_hi:[0,1,1]
	v_pk_mul_f32 v[4:5], v[78:79], v[130:131] op_sel:[0,1] op_sel_hi:[1,0]
	v_xor_b32_e32 v108, 0x80000000, v107
	v_pk_fma_f32 v[138:139], v[74:75], v[130:131], v[4:5] op_sel_hi:[0,1,1]
	v_pk_mul_f32 v[4:5], v[84:85], v[130:131] op_sel:[0,1] op_sel_hi:[1,0]
	v_mov_b32_e32 v109, v107
	v_pk_fma_f32 v[142:143], v[76:77], v[130:131], v[4:5] op_sel_hi:[0,1,1]
	v_pk_mul_f32 v[4:5], v[82:83], v[130:131] op_sel:[0,1] op_sel_hi:[1,0]
	v_xor_b32_e32 v112, 0x80000000, v111
	v_pk_fma_f32 v[148:149], v[80:81], v[130:131], v[4:5] op_sel_hi:[0,1,1]
	v_pk_mul_f32 v[4:5], v[72:73], v[148:149] op_sel:[0,1] op_sel_hi:[1,0]
	v_mov_b32_e32 v113, v111
	v_pk_fma_f32 v[152:153], v[16:17], v[148:149], v[4:5] op_sel_hi:[0,1,1]
	v_pk_mul_f32 v[4:5], v[78:79], v[148:149] op_sel:[0,1] op_sel_hi:[1,0]
	v_xor_b32_e32 v116, 0x80000000, v115
	v_pk_fma_f32 v[156:157], v[74:75], v[148:149], v[4:5] op_sel_hi:[0,1,1]
	v_pk_mul_f32 v[4:5], v[84:85], v[148:149] op_sel:[0,1] op_sel_hi:[1,0]
	v_mov_b32_e32 v117, v115
	v_pk_fma_f32 v[160:161], v[76:77], v[148:149], v[4:5] op_sel_hi:[0,1,1]
	v_pk_mul_f32 v[4:5], v[82:83], v[148:149] op_sel:[0,1] op_sel_hi:[1,0]
	v_xor_b32_e32 v120, 0x80000000, v119
	v_pk_fma_f32 v[164:165], v[80:81], v[148:149], v[4:5] op_sel_hi:[0,1,1]
	v_pk_mul_f32 v[4:5], v[72:73], v[164:165] op_sel:[0,1] op_sel_hi:[1,0]
	v_mov_b32_e32 v121, v119
	v_pk_fma_f32 v[168:169], v[16:17], v[164:165], v[4:5] op_sel_hi:[0,1,1]
	v_pk_mul_f32 v[4:5], v[78:79], v[164:165] op_sel:[0,1] op_sel_hi:[1,0]
	v_xor_b32_e32 v124, 0x80000000, v123
	v_pk_fma_f32 v[172:173], v[74:75], v[164:165], v[4:5] op_sel_hi:[0,1,1]
	v_pk_mul_f32 v[4:5], v[84:85], v[164:165] op_sel:[0,1] op_sel_hi:[1,0]
	v_mov_b32_e32 v125, v123
	v_pk_fma_f32 v[176:177], v[76:77], v[164:165], v[4:5] op_sel_hi:[0,1,1]
	v_pk_mul_f32 v[4:5], v[82:83], v[164:165] op_sel:[0,1] op_sel_hi:[1,0]
	v_xor_b32_e32 v128, 0x80000000, v127
	v_pk_fma_f32 v[180:181], v[80:81], v[164:165], v[4:5] op_sel_hi:[0,1,1]
	v_pk_mul_f32 v[4:5], v[72:73], v[180:181] op_sel:[0,1] op_sel_hi:[1,0]
	v_mov_b32_e32 v129, v127
	v_pk_fma_f32 v[184:185], v[16:17], v[180:181], v[4:5] op_sel_hi:[0,1,1]
	v_pk_mul_f32 v[4:5], v[78:79], v[180:181] op_sel:[0,1] op_sel_hi:[1,0]
	v_xor_b32_e32 v132, 0x80000000, v131
	v_pk_fma_f32 v[188:189], v[74:75], v[180:181], v[4:5] op_sel_hi:[0,1,1]
	v_pk_mul_f32 v[4:5], v[84:85], v[180:181] op_sel:[0,1] op_sel_hi:[1,0]
	v_mov_b32_e32 v133, v131
	v_pk_fma_f32 v[192:193], v[76:77], v[180:181], v[4:5] op_sel_hi:[0,1,1]
	ds_read2_b64 v[4:7], v2 offset1:16
	ds_read2_b64 v[8:11], v2 offset0:33 offset1:49
	ds_read2_b64 v[12:15], v2 offset0:66 offset1:82
	ds_read2_b64 v[20:23], v2 offset0:99 offset1:115
	ds_read2_b64 v[24:27], v2 offset0:132 offset1:148
	ds_read2_b64 v[28:31], v2 offset0:165 offset1:181
	ds_read2_b64 v[32:35], v2 offset0:198 offset1:214
	ds_read2_b64 v[36:39], v2 offset0:231 offset1:247
	ds_read2_b64 v[40:43], v3 offset0:8 offset1:24
	ds_read2_b64 v[44:47], v3 offset0:41 offset1:57
	ds_read2_b64 v[48:51], v3 offset0:74 offset1:90
	ds_read2_b64 v[52:55], v3 offset0:107 offset1:123
	ds_read2_b64 v[56:59], v3 offset0:140 offset1:156
	ds_read2_b64 v[60:63], v3 offset0:173 offset1:189
	ds_read2_b64 v[64:67], v3 offset0:206 offset1:222
	ds_read2_b64 v[68:71], v3 offset0:239 offset1:255
	s_waitcnt lgkmcnt(7)
	v_pk_mul_f32 v[72:73], v[72:73], v[40:41] op_sel:[0,1] op_sel_hi:[1,0]
	v_xor_b32_e32 v136, 0x80000000, v135
	v_pk_fma_f32 v[16:17], v[16:17], v[40:41], v[72:73] op_sel_hi:[0,1,1]
	v_pk_mul_f32 v[40:41], v[24:25], v[78:79] op_sel:[1,0] op_sel_hi:[0,1]
	v_pk_fma_f32 v[24:25], v[24:25], v[74:75], v[40:41] op_sel_hi:[1,0,1]
	s_waitcnt lgkmcnt(3)
	v_pk_mul_f32 v[40:41], v[84:85], v[56:57] op_sel:[0,1] op_sel_hi:[1,0]
	v_mov_b32_e32 v137, v135
	v_pk_fma_f32 v[40:41], v[76:77], v[56:57], v[40:41] op_sel_hi:[0,1,1]
	v_pk_mul_f32 v[56:57], v[12:13], v[82:83] op_sel:[1,0] op_sel_hi:[0,1]
	v_pk_fma_f32 v[12:13], v[12:13], v[80:81], v[56:57] op_sel_hi:[1,0,1]
	v_pk_mul_f32 v[56:57], v[88:89], v[48:49] op_sel:[0,1] op_sel_hi:[1,0]
	v_xor_b32_e32 v140, 0x80000000, v139
	v_pk_fma_f32 v[48:49], v[86:87], v[48:49], v[56:57] op_sel_hi:[0,1,1]
	v_pk_mul_f32 v[56:57], v[32:33], v[92:93] op_sel:[1,0] op_sel_hi:[0,1]
	v_pk_fma_f32 v[32:33], v[32:33], v[90:91], v[56:57] op_sel_hi:[1,0,1]
	s_waitcnt lgkmcnt(1)
	v_pk_mul_f32 v[56:57], v[96:97], v[64:65] op_sel:[0,1] op_sel_hi:[1,0]
	v_mov_b32_e32 v141, v139
	v_pk_fma_f32 v[56:57], v[94:95], v[64:65], v[56:57] op_sel_hi:[0,1,1]
	v_pk_mul_f32 v[64:65], v[8:9], v[100:101] op_sel:[1,0] op_sel_hi:[0,1]
	v_pk_fma_f32 v[8:9], v[8:9], v[98:99], v[64:65] op_sel_hi:[1,0,1]
	v_pk_mul_f32 v[64:65], v[44:45], v[104:105] op_sel:[1,0] op_sel_hi:[0,1]
	v_pk_fma_f32 v[44:45], v[44:45], v[102:103], v[64:65] op_sel_hi:[1,0,1]
	v_pk_mul_f32 v[64:65], v[28:29], v[108:109] op_sel:[1,0] op_sel_hi:[0,1]
	v_pk_fma_f32 v[28:29], v[28:29], v[106:107], v[64:65] op_sel_hi:[1,0,1]
	v_pk_mul_f32 v[64:65], v[112:113], v[60:61] op_sel:[0,1] op_sel_hi:[1,0]
	v_xor_b32_e32 v144, 0x80000000, v143
	v_pk_fma_f32 v[60:61], v[110:111], v[60:61], v[64:65] op_sel_hi:[0,1,1]
	v_pk_mul_f32 v[64:65], v[20:21], v[116:117] op_sel:[1,0] op_sel_hi:[0,1]
	v_pk_fma_f32 v[20:21], v[20:21], v[114:115], v[64:65] op_sel_hi:[1,0,1]
	v_pk_mul_f32 v[64:65], v[52:53], v[120:121] op_sel:[1,0] op_sel_hi:[0,1]
	v_pk_fma_f32 v[52:53], v[52:53], v[118:119], v[64:65] op_sel_hi:[1,0,1]
	v_pk_mul_f32 v[64:65], v[36:37], v[124:125] op_sel:[1,0] op_sel_hi:[0,1]
	v_pk_fma_f32 v[36:37], v[36:37], v[122:123], v[64:65] op_sel_hi:[1,0,1]
	s_waitcnt lgkmcnt(0)
	v_pk_mul_f32 v[64:65], v[128:129], v[68:69] op_sel:[0,1] op_sel_hi:[1,0]
	v_mov_b32_e32 v145, v143
	v_pk_fma_f32 v[64:65], v[126:127], v[68:69], v[64:65] op_sel_hi:[0,1,1]
	v_pk_mul_f32 v[68:69], v[6:7], v[132:133] op_sel:[1,0] op_sel_hi:[0,1]
	v_pk_fma_f32 v[6:7], v[6:7], v[130:131], v[68:69] op_sel_hi:[1,0,1]
	v_pk_mul_f32 v[68:69], v[42:43], v[136:137] op_sel:[1,0] op_sel_hi:[0,1]
	v_pk_fma_f32 v[42:43], v[42:43], v[134:135], v[68:69] op_sel_hi:[1,0,1]
	v_pk_mul_f32 v[68:69], v[26:27], v[140:141] op_sel:[1,0] op_sel_hi:[0,1]
	v_xor_b32_e32 v150, 0x80000000, v149
	v_mov_b32_e32 v151, v149
	v_pk_fma_f32 v[26:27], v[26:27], v[138:139], v[68:69] op_sel_hi:[1,0,1]
	v_pk_mul_f32 v[68:69], v[58:59], v[144:145] op_sel:[1,0] op_sel_hi:[0,1]
	v_xor_b32_e32 v154, 0x80000000, v153
	v_mov_b32_e32 v155, v153
	v_pk_fma_f32 v[58:59], v[58:59], v[142:143], v[68:69] op_sel_hi:[1,0,1]
	v_pk_mul_f32 v[68:69], v[14:15], v[150:151] op_sel:[1,0] op_sel_hi:[0,1]
	v_xor_b32_e32 v158, 0x80000000, v157
	v_mov_b32_e32 v159, v157
	v_pk_fma_f32 v[14:15], v[14:15], v[148:149], v[68:69] op_sel_hi:[1,0,1]
	v_pk_mul_f32 v[68:69], v[50:51], v[154:155] op_sel:[1,0] op_sel_hi:[0,1]
	v_xor_b32_e32 v162, 0x80000000, v161
	v_mov_b32_e32 v163, v161
	v_pk_fma_f32 v[50:51], v[50:51], v[152:153], v[68:69] op_sel_hi:[1,0,1]
	v_pk_mul_f32 v[68:69], v[34:35], v[158:159] op_sel:[1,0] op_sel_hi:[0,1]
	v_xor_b32_e32 v166, 0x80000000, v165
	v_mov_b32_e32 v167, v165
	v_pk_fma_f32 v[34:35], v[34:35], v[156:157], v[68:69] op_sel_hi:[1,0,1]
	v_pk_mul_f32 v[68:69], v[162:163], v[66:67] op_sel:[0,1] op_sel_hi:[1,0]
	v_xor_b32_e32 v170, 0x80000000, v169
	v_mov_b32_e32 v171, v169
	v_pk_fma_f32 v[66:67], v[160:161], v[66:67], v[68:69] op_sel_hi:[0,1,1]
	v_pk_mul_f32 v[68:69], v[10:11], v[166:167] op_sel:[1,0] op_sel_hi:[0,1]
	v_xor_b32_e32 v174, 0x80000000, v173
	v_mov_b32_e32 v175, v173
	v_pk_fma_f32 v[10:11], v[10:11], v[164:165], v[68:69] op_sel_hi:[1,0,1]
	v_pk_mul_f32 v[68:69], v[46:47], v[170:171] op_sel:[1,0] op_sel_hi:[0,1]
	v_xor_b32_e32 v178, 0x80000000, v177
	v_mov_b32_e32 v179, v177
	v_pk_fma_f32 v[46:47], v[46:47], v[168:169], v[68:69] op_sel_hi:[1,0,1]
	v_pk_mul_f32 v[68:69], v[30:31], v[174:175] op_sel:[1,0] op_sel_hi:[0,1]
	v_xor_b32_e32 v182, 0x80000000, v181
	v_mov_b32_e32 v183, v181
	v_pk_fma_f32 v[30:31], v[30:31], v[172:173], v[68:69] op_sel_hi:[1,0,1]
	v_pk_mul_f32 v[68:69], v[62:63], v[178:179] op_sel:[1,0] op_sel_hi:[0,1]
	v_xor_b32_e32 v186, 0x80000000, v185
	v_mov_b32_e32 v187, v185
	v_pk_fma_f32 v[62:63], v[62:63], v[176:177], v[68:69] op_sel_hi:[1,0,1]
	v_pk_mul_f32 v[68:69], v[22:23], v[182:183] op_sel:[1,0] op_sel_hi:[0,1]
	v_xor_b32_e32 v190, 0x80000000, v189
	v_mov_b32_e32 v191, v189
	v_pk_fma_f32 v[22:23], v[22:23], v[180:181], v[68:69] op_sel_hi:[1,0,1]
	v_pk_mul_f32 v[68:69], v[54:55], v[186:187] op_sel:[1,0] op_sel_hi:[0,1]
	v_xor_b32_e32 v194, 0x80000000, v193
	v_mov_b32_e32 v195, v193
	v_pk_fma_f32 v[54:55], v[54:55], v[184:185], v[68:69] op_sel_hi:[1,0,1]
	v_pk_mul_f32 v[68:69], v[38:39], v[190:191] op_sel:[1,0] op_sel_hi:[0,1]
	v_pk_fma_f32 v[38:39], v[38:39], v[188:189], v[68:69] op_sel_hi:[1,0,1]
	v_pk_mul_f32 v[68:69], v[70:71], v[194:195] op_sel:[1,0] op_sel_hi:[0,1]
	v_pk_fma_f32 v[68:69], v[70:71], v[192:193], v[68:69] op_sel_hi:[1,0,1]
	v_pk_add_f32 v[70:71], v[4:5], v[6:7]
	v_pk_add_f32 v[4:5], v[4:5], v[6:7] neg_lo:[0,1] neg_hi:[0,1]
	v_pk_add_f32 v[6:7], v[8:9], v[10:11]
	v_pk_add_f32 v[8:9], v[8:9], v[10:11] neg_lo:[0,1] neg_hi:[0,1]
	v_pk_add_f32 v[10:11], v[12:13], v[14:15]
	v_pk_add_f32 v[12:13], v[12:13], v[14:15] neg_lo:[0,1] neg_hi:[0,1]
	v_pk_add_f32 v[14:15], v[20:21], v[22:23]
	v_pk_add_f32 v[20:21], v[20:21], v[22:23] neg_lo:[0,1] neg_hi:[0,1]
	v_pk_add_f32 v[22:23], v[24:25], v[26:27]
	v_pk_add_f32 v[24:25], v[24:25], v[26:27] neg_lo:[0,1] neg_hi:[0,1]
	v_pk_add_f32 v[26:27], v[28:29], v[30:31]
	v_pk_add_f32 v[28:29], v[28:29], v[30:31] neg_lo:[0,1] neg_hi:[0,1]
	v_pk_add_f32 v[30:31], v[32:33], v[34:35]
	v_pk_add_f32 v[32:33], v[32:33], v[34:35] neg_lo:[0,1] neg_hi:[0,1]
	v_pk_add_f32 v[34:35], v[36:37], v[38:39]
	v_pk_add_f32 v[36:37], v[36:37], v[38:39] neg_lo:[0,1] neg_hi:[0,1]
	v_pk_add_f32 v[38:39], v[16:17], v[42:43]
	v_pk_add_f32 v[16:17], v[16:17], v[42:43] neg_lo:[0,1] neg_hi:[0,1]
	v_pk_add_f32 v[42:43], v[44:45], v[46:47]
	v_pk_add_f32 v[44:45], v[44:45], v[46:47] neg_lo:[0,1] neg_hi:[0,1]
	v_pk_add_f32 v[46:47], v[48:49], v[50:51]
	v_pk_add_f32 v[48:49], v[48:49], v[50:51] neg_lo:[0,1] neg_hi:[0,1]
	v_pk_add_f32 v[50:51], v[52:53], v[54:55]
	v_pk_add_f32 v[52:53], v[52:53], v[54:55] neg_lo:[0,1] neg_hi:[0,1]
	v_pk_add_f32 v[54:55], v[40:41], v[58:59]
	v_pk_add_f32 v[40:41], v[40:41], v[58:59] neg_lo:[0,1] neg_hi:[0,1]
	v_pk_add_f32 v[58:59], v[60:61], v[62:63]
	v_pk_add_f32 v[60:61], v[60:61], v[62:63] neg_lo:[0,1] neg_hi:[0,1]
	v_pk_add_f32 v[62:63], v[56:57], v[66:67]
	v_pk_add_f32 v[56:57], v[56:57], v[66:67] neg_lo:[0,1] neg_hi:[0,1]
	v_pk_add_f32 v[66:67], v[64:65], v[68:69]
	v_pk_add_f32 v[64:65], v[64:65], v[68:69] neg_lo:[0,1] neg_hi:[0,1]
	v_pk_add_f32 v[68:69], v[70:71], v[6:7]
	v_pk_add_f32 v[6:7], v[70:71], v[6:7] neg_lo:[0,1] neg_hi:[0,1]
	v_xor_b32_e32 v70, 0x80000000, v9
	v_mov_b32_e32 v71, v8
	v_pk_add_f32 v[8:9], v[4:5], v[70:71]
	v_pk_add_f32 v[4:5], v[4:5], v[70:71] neg_lo:[0,1] neg_hi:[0,1]
	v_pk_add_f32 v[70:71], v[10:11], v[14:15]
	v_pk_add_f32 v[10:11], v[10:11], v[14:15] neg_lo:[0,1] neg_hi:[0,1]
	v_xor_b32_e32 v14, 0x80000000, v21
	v_mov_b32_e32 v15, v20
	v_pk_add_f32 v[20:21], v[12:13], v[14:15]
	v_pk_add_f32 v[12:13], v[12:13], v[14:15] neg_lo:[0,1] neg_hi:[0,1]
	v_pk_add_f32 v[14:15], v[22:23], v[26:27]
	v_pk_add_f32 v[22:23], v[22:23], v[26:27] neg_lo:[0,1] neg_hi:[0,1]
	v_xor_b32_e32 v26, 0x80000000, v29
	v_mov_b32_e32 v27, v28
	v_pk_add_f32 v[28:29], v[24:25], v[26:27]
	v_pk_add_f32 v[24:25], v[24:25], v[26:27] neg_lo:[0,1] neg_hi:[0,1]
	v_pk_add_f32 v[26:27], v[30:31], v[34:35]
	v_pk_add_f32 v[30:31], v[30:31], v[34:35] neg_lo:[0,1] neg_hi:[0,1]
	v_xor_b32_e32 v34, 0x80000000, v37
	v_mov_b32_e32 v35, v36
	v_pk_add_f32 v[36:37], v[32:33], v[34:35]
	v_pk_add_f32 v[32:33], v[32:33], v[34:35] neg_lo:[0,1] neg_hi:[0,1]
	v_pk_add_f32 v[34:35], v[38:39], v[42:43]
	v_pk_add_f32 v[38:39], v[38:39], v[42:43] neg_lo:[0,1] neg_hi:[0,1]
	v_xor_b32_e32 v42, 0x80000000, v45
	v_mov_b32_e32 v43, v44
	v_pk_add_f32 v[44:45], v[16:17], v[42:43]
	v_pk_add_f32 v[16:17], v[16:17], v[42:43] neg_lo:[0,1] neg_hi:[0,1]
	v_pk_add_f32 v[42:43], v[46:47], v[50:51]
	v_pk_add_f32 v[46:47], v[46:47], v[50:51] neg_lo:[0,1] neg_hi:[0,1]
	v_xor_b32_e32 v50, 0x80000000, v53
	v_mov_b32_e32 v51, v52
	v_pk_add_f32 v[52:53], v[48:49], v[50:51]
	v_pk_add_f32 v[48:49], v[48:49], v[50:51] neg_lo:[0,1] neg_hi:[0,1]
	v_pk_add_f32 v[50:51], v[54:55], v[58:59]
	v_pk_add_f32 v[54:55], v[54:55], v[58:59] neg_lo:[0,1] neg_hi:[0,1]
	v_xor_b32_e32 v58, 0x80000000, v61
	v_mov_b32_e32 v59, v60
	v_pk_add_f32 v[60:61], v[40:41], v[58:59]
	v_pk_add_f32 v[40:41], v[40:41], v[58:59] neg_lo:[0,1] neg_hi:[0,1]
	v_pk_add_f32 v[58:59], v[62:63], v[66:67]
	v_pk_add_f32 v[62:63], v[62:63], v[66:67] neg_lo:[0,1] neg_hi:[0,1]
	v_xor_b32_e32 v66, 0x80000000, v65
	v_mov_b32_e32 v67, v64
	v_pk_add_f32 v[64:65], v[56:57], v[66:67]
	v_pk_add_f32 v[56:57], v[56:57], v[66:67] neg_lo:[0,1] neg_hi:[0,1]
	v_pk_add_f32 v[66:67], v[68:69], v[70:71]
	v_pk_add_f32 v[68:69], v[68:69], v[70:71] neg_lo:[0,1] neg_hi:[0,1]
	v_pk_mul_f32 v[70:71], v[20:21], s[78:79]
	s_nop 0
	v_pk_fma_f32 v[20:21], s[0:1], v[20:21], v[70:71] op_sel:[0,0,1] op_sel_hi:[0,1,0]
	v_pk_add_f32 v[70:71], v[8:9], v[20:21]
	v_pk_add_f32 v[8:9], v[8:9], v[20:21] neg_lo:[0,1] neg_hi:[0,1]
	v_xor_b32_e32 v20, 0x80000000, v11
	v_mov_b32_e32 v21, v10
	v_pk_add_f32 v[10:11], v[6:7], v[20:21]
	v_pk_add_f32 v[6:7], v[6:7], v[20:21] neg_lo:[0,1] neg_hi:[0,1]
	v_pk_mul_f32 v[20:21], v[12:13], s[78:79]
	s_nop 0
	v_pk_fma_f32 v[12:13], s[0:1], v[12:13], v[20:21] op_sel:[0,0,1] op_sel_hi:[0,1,0] neg_lo:[0,1,0] neg_hi:[0,1,0]
	v_pk_add_f32 v[20:21], v[4:5], v[12:13]
	v_pk_add_f32 v[4:5], v[4:5], v[12:13] neg_lo:[0,1] neg_hi:[0,1]
	v_pk_add_f32 v[12:13], v[14:15], v[26:27]
	v_pk_add_f32 v[14:15], v[14:15], v[26:27] neg_lo:[0,1] neg_hi:[0,1]
	v_pk_mul_f32 v[26:27], v[36:37], s[78:79]
	s_nop 0
	v_pk_fma_f32 v[26:27], s[0:1], v[36:37], v[26:27] op_sel:[0,0,1] op_sel_hi:[0,1,0]
	v_pk_add_f32 v[36:37], v[28:29], v[26:27]
	v_pk_add_f32 v[26:27], v[28:29], v[26:27] neg_lo:[0,1] neg_hi:[0,1]
	v_xor_b32_e32 v28, 0x80000000, v31
	v_mov_b32_e32 v29, v30
	v_pk_add_f32 v[30:31], v[22:23], v[28:29]
	v_pk_add_f32 v[22:23], v[22:23], v[28:29] neg_lo:[0,1] neg_hi:[0,1]
	v_pk_mul_f32 v[28:29], v[32:33], s[78:79]
	s_nop 0
	v_pk_fma_f32 v[28:29], s[0:1], v[32:33], v[28:29] op_sel:[0,0,1] op_sel_hi:[0,1,0] neg_lo:[0,1,0] neg_hi:[0,1,0]
	v_pk_add_f32 v[32:33], v[24:25], v[28:29]
	v_pk_add_f32 v[24:25], v[24:25], v[28:29] neg_lo:[0,1] neg_hi:[0,1]
	v_pk_add_f32 v[28:29], v[34:35], v[42:43]
	v_pk_add_f32 v[34:35], v[34:35], v[42:43] neg_lo:[0,1] neg_hi:[0,1]
	v_pk_mul_f32 v[42:43], v[52:53], s[78:79]
	s_nop 0
	v_pk_fma_f32 v[42:43], s[0:1], v[52:53], v[42:43] op_sel:[0,0,1] op_sel_hi:[0,1,0]
	v_pk_add_f32 v[52:53], v[44:45], v[42:43]
	v_pk_add_f32 v[42:43], v[44:45], v[42:43] neg_lo:[0,1] neg_hi:[0,1]
	v_xor_b32_e32 v44, 0x80000000, v47
	v_mov_b32_e32 v45, v46
	v_pk_add_f32 v[46:47], v[38:39], v[44:45]
	v_pk_add_f32 v[38:39], v[38:39], v[44:45] neg_lo:[0,1] neg_hi:[0,1]
	v_pk_mul_f32 v[44:45], v[48:49], s[78:79]
	s_nop 0
	v_pk_fma_f32 v[44:45], s[0:1], v[48:49], v[44:45] op_sel:[0,0,1] op_sel_hi:[0,1,0] neg_lo:[0,1,0] neg_hi:[0,1,0]
	v_pk_add_f32 v[48:49], v[16:17], v[44:45]
	v_pk_add_f32 v[16:17], v[16:17], v[44:45] neg_lo:[0,1] neg_hi:[0,1]
	v_pk_add_f32 v[44:45], v[50:51], v[58:59]
	v_pk_add_f32 v[50:51], v[50:51], v[58:59] neg_lo:[0,1] neg_hi:[0,1]
	v_pk_mul_f32 v[58:59], v[64:65], s[78:79]
	s_nop 0
	v_pk_fma_f32 v[58:59], s[0:1], v[64:65], v[58:59] op_sel:[0,0,1] op_sel_hi:[0,1,0]
	v_pk_add_f32 v[64:65], v[60:61], v[58:59]
	v_pk_add_f32 v[58:59], v[60:61], v[58:59] neg_lo:[0,1] neg_hi:[0,1]
	v_xor_b32_e32 v60, 0x80000000, v63
	v_mov_b32_e32 v61, v62
	v_pk_add_f32 v[62:63], v[54:55], v[60:61]
	v_pk_add_f32 v[54:55], v[54:55], v[60:61] neg_lo:[0,1] neg_hi:[0,1]
	v_pk_mul_f32 v[60:61], v[56:57], s[78:79]
	s_nop 0
	v_pk_fma_f32 v[56:57], s[0:1], v[56:57], v[60:61] op_sel:[0,0,1] op_sel_hi:[0,1,0] neg_lo:[0,1,0] neg_hi:[0,1,0]
	v_pk_add_f32 v[60:61], v[40:41], v[56:57]
	v_pk_add_f32 v[40:41], v[40:41], v[56:57] neg_lo:[0,1] neg_hi:[0,1]
	v_pk_add_f32 v[56:57], v[66:67], v[12:13]
	v_pk_add_f32 v[12:13], v[66:67], v[12:13] neg_lo:[0,1] neg_hi:[0,1]
	v_pk_mul_f32 v[66:67], v[36:37], s[80:81]
	s_nop 0
	v_pk_fma_f32 v[36:37], s[16:17], v[36:37], v[66:67] op_sel:[0,0,1] op_sel_hi:[0,1,0]
	v_pk_add_f32 v[66:67], v[70:71], v[36:37]
	v_pk_add_f32 v[36:37], v[70:71], v[36:37] neg_lo:[0,1] neg_hi:[0,1]
	v_pk_mul_f32 v[70:71], v[30:31], s[78:79]
	s_nop 0
	v_pk_fma_f32 v[30:31], s[0:1], v[30:31], v[70:71] op_sel:[0,0,1] op_sel_hi:[0,1,0]
	v_pk_add_f32 v[70:71], v[10:11], v[30:31]
	v_pk_add_f32 v[10:11], v[10:11], v[30:31] neg_lo:[0,1] neg_hi:[0,1]
	v_pk_mul_f32 v[30:31], v[32:33], s[16:17]
	s_nop 0
	v_pk_fma_f32 v[30:31], s[82:83], v[32:33], v[30:31] op_sel:[0,0,1] op_sel_hi:[0,1,0]
	v_pk_add_f32 v[32:33], v[20:21], v[30:31]
	v_pk_add_f32 v[20:21], v[20:21], v[30:31] neg_lo:[0,1] neg_hi:[0,1]
	v_xor_b32_e32 v30, 0x80000000, v15
	v_mov_b32_e32 v31, v14
	v_pk_add_f32 v[14:15], v[68:69], v[30:31]
	v_pk_add_f32 v[30:31], v[68:69], v[30:31] neg_lo:[0,1] neg_hi:[0,1]
	v_pk_mul_f32 v[68:69], v[26:27], s[16:17]
	s_nop 0
	v_pk_fma_f32 v[26:27], s[82:83], v[26:27], v[68:69] op_sel:[0,0,1] op_sel_hi:[0,1,0] neg_lo:[0,1,0] neg_hi:[0,1,0]
	v_pk_add_f32 v[68:69], v[8:9], v[26:27]
	v_pk_add_f32 v[8:9], v[8:9], v[26:27] neg_lo:[0,1] neg_hi:[0,1]
	v_pk_mul_f32 v[26:27], v[22:23], s[78:79]
	s_nop 0
	v_pk_fma_f32 v[22:23], s[0:1], v[22:23], v[26:27] op_sel:[0,0,1] op_sel_hi:[0,1,0] neg_lo:[0,1,0] neg_hi:[0,1,0]
	v_pk_add_f32 v[26:27], v[6:7], v[22:23]
	v_pk_add_f32 v[6:7], v[6:7], v[22:23] neg_lo:[0,1] neg_hi:[0,1]
	v_pk_mul_f32 v[22:23], v[24:25], s[80:81]
	s_nop 0
	v_pk_fma_f32 v[22:23], s[16:17], v[24:25], v[22:23] op_sel:[0,0,1] op_sel_hi:[0,1,0] neg_lo:[0,1,0] neg_hi:[0,1,0]
	v_pk_add_f32 v[24:25], v[4:5], v[22:23]
	v_pk_add_f32 v[4:5], v[4:5], v[22:23] neg_lo:[0,1] neg_hi:[0,1]
	v_pk_add_f32 v[22:23], v[28:29], v[44:45]
	v_pk_add_f32 v[28:29], v[28:29], v[44:45] neg_lo:[0,1] neg_hi:[0,1]
	v_pk_mul_f32 v[44:45], v[64:65], s[80:81]
	s_nop 0
	v_pk_fma_f32 v[44:45], s[16:17], v[64:65], v[44:45] op_sel:[0,0,1] op_sel_hi:[0,1,0]
	v_pk_add_f32 v[64:65], v[52:53], v[44:45]
	v_pk_add_f32 v[44:45], v[52:53], v[44:45] neg_lo:[0,1] neg_hi:[0,1]
	v_pk_mul_f32 v[52:53], v[62:63], s[78:79]
	s_nop 0
	v_pk_fma_f32 v[52:53], s[0:1], v[62:63], v[52:53] op_sel:[0,0,1] op_sel_hi:[0,1,0]
	v_pk_add_f32 v[62:63], v[46:47], v[52:53]
	v_pk_add_f32 v[46:47], v[46:47], v[52:53] neg_lo:[0,1] neg_hi:[0,1]
	v_pk_mul_f32 v[52:53], v[60:61], s[16:17]
	s_nop 0
	v_pk_fma_f32 v[52:53], s[82:83], v[60:61], v[52:53] op_sel:[0,0,1] op_sel_hi:[0,1,0]
	v_pk_add_f32 v[60:61], v[48:49], v[52:53]
	v_pk_add_f32 v[48:49], v[48:49], v[52:53] neg_lo:[0,1] neg_hi:[0,1]
	v_xor_b32_e32 v52, 0x80000000, v51
	v_mov_b32_e32 v53, v50
	v_pk_add_f32 v[50:51], v[34:35], v[52:53]
	v_pk_add_f32 v[34:35], v[34:35], v[52:53] neg_lo:[0,1] neg_hi:[0,1]
	v_pk_mul_f32 v[52:53], v[58:59], s[16:17]
	s_nop 0
	v_pk_fma_f32 v[52:53], s[82:83], v[58:59], v[52:53] op_sel:[0,0,1] op_sel_hi:[0,1,0] neg_lo:[0,1,0] neg_hi:[0,1,0]
	v_pk_add_f32 v[58:59], v[42:43], v[52:53]
	v_pk_add_f32 v[42:43], v[42:43], v[52:53] neg_lo:[0,1] neg_hi:[0,1]
	v_pk_mul_f32 v[52:53], v[54:55], s[78:79]
	s_nop 0
	v_pk_fma_f32 v[52:53], s[0:1], v[54:55], v[52:53] op_sel:[0,0,1] op_sel_hi:[0,1,0] neg_lo:[0,1,0] neg_hi:[0,1,0]
	v_pk_add_f32 v[54:55], v[38:39], v[52:53]
	v_pk_add_f32 v[38:39], v[38:39], v[52:53] neg_lo:[0,1] neg_hi:[0,1]
	v_pk_mul_f32 v[52:53], v[40:41], s[80:81]
	s_nop 0
	v_pk_fma_f32 v[40:41], s[16:17], v[40:41], v[52:53] op_sel:[0,0,1] op_sel_hi:[0,1,0] neg_lo:[0,1,0] neg_hi:[0,1,0]
	v_pk_add_f32 v[52:53], v[16:17], v[40:41]
	v_pk_add_f32 v[16:17], v[16:17], v[40:41] neg_lo:[0,1] neg_hi:[0,1]
	v_pk_add_f32 v[40:41], v[56:57], v[22:23]
	v_pk_add_f32 v[22:23], v[56:57], v[22:23] neg_lo:[0,1] neg_hi:[0,1]
	v_pk_mul_f32 v[56:57], v[64:65], s[88:89]
	s_nop 0
	v_pk_fma_f32 v[56:57], v[64:65], s[8:9], v[56:57] op_sel:[0,0,1] op_sel_hi:[1,0,0]
	s_mov_b32 s9, s42
	v_pk_add_f32 v[64:65], v[66:67], v[56:57]
	v_pk_add_f32 v[56:57], v[66:67], v[56:57] neg_lo:[0,1] neg_hi:[0,1]
	v_pk_mul_f32 v[66:67], v[62:63], s[80:81]
	s_nop 0
	v_pk_fma_f32 v[62:63], s[16:17], v[62:63], v[66:67] op_sel:[0,0,1] op_sel_hi:[0,1,0]
	v_pk_add_f32 v[66:67], v[70:71], v[62:63]
	v_pk_add_f32 v[62:63], v[70:71], v[62:63] neg_lo:[0,1] neg_hi:[0,1]
	v_pk_mul_f32 v[70:71], v[60:61], s[62:63]
	s_nop 0
	v_pk_fma_f32 v[60:61], v[60:61], s[24:25], v[70:71] op_sel:[0,0,1] op_sel_hi:[1,0,0]
	s_mov_b32 s25, s38
	v_pk_add_f32 v[70:71], v[32:33], v[60:61]
	v_pk_add_f32 v[32:33], v[32:33], v[60:61] neg_lo:[0,1] neg_hi:[0,1]
	v_pk_mul_f32 v[60:61], v[50:51], s[78:79]
	s_nop 0
	v_pk_fma_f32 v[50:51], s[0:1], v[50:51], v[60:61] op_sel:[0,0,1] op_sel_hi:[0,1,0]
	v_pk_add_f32 v[60:61], v[14:15], v[50:51]
	v_pk_add_f32 v[14:15], v[14:15], v[50:51] neg_lo:[0,1] neg_hi:[0,1]
	v_pk_mul_f32 v[50:51], v[58:59], s[24:25]
	s_nop 0
	v_pk_fma_f32 v[50:51], s[84:85], v[58:59], v[50:51] op_sel:[0,0,1] op_sel_hi:[0,1,0]
	v_pk_add_f32 v[58:59], v[68:69], v[50:51]
	v_pk_add_f32 v[50:51], v[68:69], v[50:51] neg_lo:[0,1] neg_hi:[0,1]
	v_pk_mul_f32 v[68:69], v[54:55], s[16:17]
	s_nop 0
	v_pk_fma_f32 v[54:55], s[82:83], v[54:55], v[68:69] op_sel:[0,0,1] op_sel_hi:[0,1,0]
	v_pk_add_f32 v[68:69], v[26:27], v[54:55]
	v_pk_add_f32 v[26:27], v[26:27], v[54:55] neg_lo:[0,1] neg_hi:[0,1]
	v_pk_mul_f32 v[54:55], v[52:53], s[8:9]
	s_nop 0
	v_pk_fma_f32 v[52:53], s[86:87], v[52:53], v[54:55] op_sel:[0,0,1] op_sel_hi:[0,1,0]
	v_pk_add_f32 v[54:55], v[24:25], v[52:53]
	v_pk_add_f32 v[24:25], v[24:25], v[52:53] neg_lo:[0,1] neg_hi:[0,1]
	v_xor_b32_e32 v52, 0x80000000, v29
	v_mov_b32_e32 v53, v28
	v_pk_add_f32 v[28:29], v[12:13], v[52:53]
	v_pk_add_f32 v[12:13], v[12:13], v[52:53] neg_lo:[0,1] neg_hi:[0,1]
	v_pk_mul_f32 v[52:53], v[44:45], s[8:9]
	s_nop 0
	v_pk_fma_f32 v[44:45], s[86:87], v[44:45], v[52:53] op_sel:[0,0,1] op_sel_hi:[0,1,0] neg_lo:[0,1,0] neg_hi:[0,1,0]
	v_pk_add_f32 v[52:53], v[36:37], v[44:45]
	v_pk_add_f32 v[36:37], v[36:37], v[44:45] neg_lo:[0,1] neg_hi:[0,1]
	v_pk_mul_f32 v[44:45], v[46:47], s[16:17]
	s_nop 0
	v_pk_fma_f32 v[44:45], s[82:83], v[46:47], v[44:45] op_sel:[0,0,1] op_sel_hi:[0,1,0] neg_lo:[0,1,0] neg_hi:[0,1,0]
	v_pk_add_f32 v[46:47], v[10:11], v[44:45]
	v_pk_add_f32 v[10:11], v[10:11], v[44:45] neg_lo:[0,1] neg_hi:[0,1]
	v_pk_mul_f32 v[44:45], v[48:49], s[24:25]
	s_nop 0
	v_pk_fma_f32 v[44:45], s[84:85], v[48:49], v[44:45] op_sel:[0,0,1] op_sel_hi:[0,1,0] neg_lo:[0,1,0] neg_hi:[0,1,0]
	v_pk_add_f32 v[48:49], v[20:21], v[44:45]
	v_pk_add_f32 v[20:21], v[20:21], v[44:45] neg_lo:[0,1] neg_hi:[0,1]
	v_pk_mul_f32 v[44:45], v[34:35], s[78:79]
	s_nop 0
	v_pk_fma_f32 v[34:35], v[34:35], s[0:1], v[44:45] op_sel:[0,0,1] op_sel_hi:[1,0,0] neg_lo:[1,0,0] neg_hi:[1,0,0]
	s_lshl_b64 s[0:1], s[72:73], 2
	v_pk_add_f32 v[44:45], v[30:31], v[34:35]
	v_pk_add_f32 v[30:31], v[30:31], v[34:35] neg_lo:[0,1] neg_hi:[0,1]
	v_pk_mul_f32 v[34:35], v[42:43], s[62:63]
	s_add_u32 s0, s49, s0
	v_pk_fma_f32 v[34:35], v[42:43], s[24:25], v[34:35] op_sel:[0,0,1] op_sel_hi:[1,0,0] neg_lo:[1,0,0] neg_hi:[1,0,0]
	s_addc_u32 s1, s60, s1
	v_pk_add_f32 v[42:43], v[8:9], v[34:35]
	v_pk_add_f32 v[8:9], v[8:9], v[34:35] neg_lo:[0,1] neg_hi:[0,1]
	v_pk_mul_f32 v[34:35], v[38:39], s[80:81]
	s_lshl_b64 s[62:63], s[76:77], 2
	v_pk_fma_f32 v[34:35], v[38:39], s[16:17], v[34:35] op_sel:[0,0,1] op_sel_hi:[1,0,0] neg_lo:[1,0,0] neg_hi:[1,0,0]
	s_add_u32 s62, s22, s62
	v_pk_add_f32 v[38:39], v[6:7], v[34:35]
	v_pk_add_f32 v[6:7], v[6:7], v[34:35] neg_lo:[0,1] neg_hi:[0,1]
	v_pk_mul_f32 v[34:35], v[16:17], s[88:89]
	s_addc_u32 s63, s23, s63
	v_pk_fma_f32 v[16:17], s[8:9], v[16:17], v[34:35] op_sel:[0,0,1] op_sel_hi:[0,1,0] neg_lo:[0,1,0] neg_hi:[0,1,0]
	v_pk_add_f32 v[34:35], v[4:5], v[16:17]
	v_pk_add_f32 v[4:5], v[4:5], v[16:17] neg_lo:[0,1] neg_hi:[0,1]
	ds_write2_b64 v2, v[40:41], v[64:65] offset1:16
	ds_write2_b64 v2, v[66:67], v[70:71] offset0:33 offset1:49
	ds_write2_b64 v2, v[60:61], v[58:59] offset0:66 offset1:82
	ds_write2_b64 v2, v[68:69], v[54:55] offset0:99 offset1:115
	ds_write2_b64 v2, v[28:29], v[52:53] offset0:132 offset1:148
	ds_write2_b64 v2, v[46:47], v[48:49] offset0:165 offset1:181
	ds_write2_b64 v2, v[44:45], v[42:43] offset0:198 offset1:214
	ds_write2_b64 v2, v[38:39], v[34:35] offset0:231 offset1:247
	ds_write2_b64 v3, v[22:23], v[56:57] offset0:8 offset1:24
	ds_write2_b64 v3, v[62:63], v[32:33] offset0:41 offset1:57
	ds_write2_b64 v3, v[14:15], v[50:51] offset0:74 offset1:90
	ds_write2_b64 v3, v[26:27], v[24:25] offset0:107 offset1:123
	ds_write2_b64 v3, v[12:13], v[36:37] offset0:140 offset1:156
	ds_write2_b64 v3, v[10:11], v[20:21] offset0:173 offset1:189
	ds_write2_b64 v3, v[30:31], v[8:9] offset0:206 offset1:222
	ds_write2_b64 v3, v[6:7], v[4:5] offset0:239 offset1:255
	s_waitcnt lgkmcnt(0)
	s_barrier
	global_load_dword v30, v206, s[0:1]
	global_load_dword v20, v207, s[0:1]
	v_ashrrev_i32_e32 v2, 31, v210
	v_lshrrev_b32_e32 v2, 22, v2
	v_add_u32_e32 v2, v210, v2
	v_ashrrev_i32_e32 v2, 10, v2
	v_mul_i32_i24_e32 v3, 0x400, v2
	global_load_dword v31, v205, s[0:1]
	global_load_dword v24, v205, s[62:63]
	s_add_u32 s0, s87, s74
	v_sub_u32_e32 v21, v210, v3
	v_lshlrev_b32_e32 v36, 14, v2
	s_addc_u32 s1, s90, s75
	v_ashrrev_i32_e32 v37, 31, v36
	v_lshlrev_b32_e32 v32, 4, v21
	v_lshl_add_u64 v[2:3], v[36:37], 1, s[0:1]
	v_ashrrev_i32_e32 v33, 31, v32
	v_lshl_add_u64 v[2:3], v[32:33], 1, v[2:3]
	global_load_dwordx4 v[10:13], v[2:3], off offset:16 nt
	global_load_dwordx4 v[14:17], v[2:3], off nt
	v_cmp_lt_i32_e32 vcc, 0, v21
	v_mov_b32_e32 v39, 0
	v_mov_b32_e32 v41, 0
	s_and_saveexec_b64 s[72:73], vcc
	s_cbranch_execz .LBB0_505
	global_load_ushort v41, v[2:3], off offset:-2

.LBB0_538:
	s_or_b64 exec, exec, s[0:1]
	v_pk_mul_f32 v[22:23], v[32:33], s[46:47] op_sel_hi:[1,0]
	v_pk_add_f32 v[26:27], v[24:25], v[30:31]
	v_pk_add_f32 v[24:25], v[24:25], v[30:31] neg_lo:[0,1] neg_hi:[0,1]
	v_pk_add_f32 v[30:31], v[64:65], v[68:69]
	v_pk_add_f32 v[32:33], v[64:65], v[68:69] neg_lo:[0,1] neg_hi:[0,1]
	v_pk_add_f32 v[34:35], v[62:63], v[90:91]
	v_pk_add_f32 v[38:39], v[94:95], v[80:81]
	v_pk_add_f32 v[40:41], v[94:95], v[80:81] neg_lo:[0,1] neg_hi:[0,1]
	v_pk_add_f32 v[68:69], v[26:27], v[30:31]
	v_pk_add_f32 v[26:27], v[26:27], v[30:31] neg_lo:[0,1] neg_hi:[0,1]
	v_xor_b32_e32 v30, 0x80000000, v33
	v_mov_b32_e32 v31, v32
	v_pk_mul_f32 v[20:21], v[50:51], s[46:47] op_sel_hi:[1,0]
	v_pk_add_f32 v[36:37], v[62:63], v[90:91] neg_lo:[0,1] neg_hi:[0,1]
	v_pk_add_f32 v[42:43], v[78:79], v[136:137]
	v_pk_add_f32 v[46:47], v[130:131], v[120:121]
	v_pk_add_f32 v[50:51], v[130:131], v[120:121] neg_lo:[0,1] neg_hi:[0,1]
	v_pk_add_f32 v[32:33], v[24:25], v[30:31]
	v_pk_add_f32 v[24:25], v[24:25], v[30:31] neg_lo:[0,1] neg_hi:[0,1]
	v_pk_add_f32 v[30:31], v[34:35], v[38:39]
	v_pk_add_f32 v[34:35], v[34:35], v[38:39] neg_lo:[0,1] neg_hi:[0,1]
	v_xor_b32_e32 v38, 0x80000000, v41
	v_mov_b32_e32 v39, v40
	v_pk_add_f32 v[44:45], v[78:79], v[136:137] neg_lo:[0,1] neg_hi:[0,1]
	v_pk_add_f32 v[60:61], v[128:129], v[150:151]
	v_pk_add_f32 v[64:65], v[168:169], v[144:145]
	v_pk_add_f32 v[66:67], v[168:169], v[144:145] neg_lo:[0,1] neg_hi:[0,1]
	v_pk_add_f32 v[40:41], v[36:37], v[38:39]
	v_pk_add_f32 v[36:37], v[36:37], v[38:39] neg_lo:[0,1] neg_hi:[0,1]
	v_pk_add_f32 v[38:39], v[42:43], v[46:47]
	v_pk_add_f32 v[42:43], v[42:43], v[46:47] neg_lo:[0,1] neg_hi:[0,1]
	v_xor_b32_e32 v46, 0x80000000, v51
	v_mov_b32_e32 v47, v50
	v_pk_add_f32 v[62:63], v[128:129], v[150:151] neg_lo:[0,1] neg_hi:[0,1]
	v_pk_add_f32 v[50:51], v[44:45], v[46:47]
	v_pk_add_f32 v[44:45], v[44:45], v[46:47] neg_lo:[0,1] neg_hi:[0,1]
	v_pk_add_f32 v[46:47], v[60:61], v[64:65]
	v_pk_add_f32 v[60:61], v[60:61], v[64:65] neg_lo:[0,1] neg_hi:[0,1]
	v_xor_b32_e32 v64, 0x80000000, v67
	v_mov_b32_e32 v65, v66
	s_mov_b32 s66, s37
	s_mov_b32 s67, s36
	v_pk_add_f32 v[66:67], v[62:63], v[64:65]
	v_pk_add_f32 v[62:63], v[62:63], v[64:65] neg_lo:[0,1] neg_hi:[0,1]
	v_pk_add_f32 v[64:65], v[68:69], v[30:31]
	v_pk_add_f32 v[30:31], v[68:69], v[30:31] neg_lo:[0,1] neg_hi:[0,1]
	s_mov_b32 s0, s37
	v_pk_mul_f32 v[68:69], v[40:41], s[66:67]
	s_mov_b32 s68, s19
	v_pk_fma_f32 v[40:41], v[40:41], s[0:1], v[68:69] op_sel:[0,0,1] op_sel_hi:[1,0,0]
	s_mov_b32 s69, s18
	v_pk_add_f32 v[68:69], v[32:33], v[40:41]
	v_pk_add_f32 v[32:33], v[32:33], v[40:41] neg_lo:[0,1] neg_hi:[0,1]
	v_xor_b32_e32 v40, 0x80000000, v35
	v_mov_b32_e32 v41, v34
	v_pk_add_f32 v[34:35], v[26:27], v[40:41]
	v_pk_add_f32 v[26:27], v[26:27], v[40:41] neg_lo:[0,1] neg_hi:[0,1]
	v_pk_mul_f32 v[40:41], v[36:37], s[66:67]
	s_mov_b32 s72, s19
	v_pk_fma_f32 v[36:37], v[36:37], s[0:1], v[40:41] op_sel:[0,0,1] op_sel_hi:[1,0,0] neg_lo:[1,0,0] neg_hi:[1,0,0]
	v_pk_mul_f32 v[2:3], v[72:73], s[46:47] op_sel_hi:[1,0]
	v_pk_add_f32 v[40:41], v[24:25], v[36:37]
	v_pk_add_f32 v[24:25], v[24:25], v[36:37] neg_lo:[0,1] neg_hi:[0,1]
	v_pk_add_f32 v[36:37], v[38:39], v[46:47]
	v_pk_add_f32 v[38:39], v[38:39], v[46:47] neg_lo:[0,1] neg_hi:[0,1]
	v_pk_mul_f32 v[46:47], v[66:67], s[66:67]
	v_pk_mul_f32 v[8:9], v[70:71], s[46:47] op_sel_hi:[1,0]
	v_pk_fma_f32 v[46:47], v[66:67], s[0:1], v[46:47] op_sel:[0,0,1] op_sel_hi:[1,0,0]
	v_pk_mul_f32 v[10:11], v[76:77], s[46:47] op_sel_hi:[1,0]
	v_pk_add_f32 v[66:67], v[50:51], v[46:47]
	v_pk_add_f32 v[46:47], v[50:51], v[46:47] neg_lo:[0,1] neg_hi:[0,1]
	v_xor_b32_e32 v50, 0x80000000, v61
	v_mov_b32_e32 v51, v60
	v_pk_add_f32 v[60:61], v[42:43], v[50:51]
	v_pk_add_f32 v[42:43], v[42:43], v[50:51] neg_lo:[0,1] neg_hi:[0,1]
	v_pk_mul_f32 v[50:51], v[62:63], s[66:67]
	v_pk_mul_f32 v[14:15], v[74:75], s[46:47] op_sel_hi:[1,0]
	v_pk_fma_f32 v[50:51], v[62:63], s[0:1], v[50:51] op_sel:[0,0,1] op_sel_hi:[1,0,0] neg_lo:[1,0,0] neg_hi:[1,0,0]
	v_pk_mul_f32 v[16:17], v[16:17], s[46:47] op_sel_hi:[1,0]
	v_pk_add_f32 v[62:63], v[44:45], v[50:51]
	v_pk_add_f32 v[44:45], v[44:45], v[50:51] neg_lo:[0,1] neg_hi:[0,1]
	v_pk_add_f32 v[50:51], v[64:65], v[36:37]
	v_pk_add_f32 v[36:37], v[64:65], v[36:37] neg_lo:[0,1] neg_hi:[0,1]
	v_pk_mul_f32 v[64:65], v[66:67], s[68:69]
	v_pk_mul_f32 v[6:7], v[6:7], s[46:47] op_sel_hi:[1,0]
	v_pk_fma_f32 v[64:65], v[66:67], s[16:17], v[64:65] op_sel:[0,0,1] op_sel_hi:[1,0,0]
	s_mov_b32 s17, s40
	v_pk_add_f32 v[66:67], v[68:69], v[64:65]
	v_pk_add_f32 v[64:65], v[68:69], v[64:65] neg_lo:[0,1] neg_hi:[0,1]
	v_pk_mul_f32 v[68:69], v[60:61], s[66:67]
	s_ashr_i32 s63, s62, 31
	v_pk_fma_f32 v[60:61], s[0:1], v[60:61], v[68:69] op_sel:[0,0,1] op_sel_hi:[0,1,0]
	v_pk_add_f32 v[68:69], v[34:35], v[60:61]
	v_pk_add_f32 v[34:35], v[34:35], v[60:61] neg_lo:[0,1] neg_hi:[0,1]
	v_pk_mul_f32 v[60:61], v[62:63], s[16:17]
	s_nop 0
	v_pk_fma_f32 v[60:61], s[72:73], v[62:63], v[60:61] op_sel:[0,0,1] op_sel_hi:[0,1,0]
	v_pk_add_f32 v[62:63], v[40:41], v[60:61]
	v_pk_add_f32 v[40:41], v[40:41], v[60:61] neg_lo:[0,1] neg_hi:[0,1]
	v_xor_b32_e32 v60, 0x80000000, v39
	v_mov_b32_e32 v61, v38
	v_pk_add_f32 v[38:39], v[30:31], v[60:61]
	v_pk_add_f32 v[30:31], v[30:31], v[60:61] neg_lo:[0,1] neg_hi:[0,1]
	v_pk_mul_f32 v[60:61], v[46:47], s[16:17]
	s_nop 0
	v_pk_fma_f32 v[46:47], s[72:73], v[46:47], v[60:61] op_sel:[0,0,1] op_sel_hi:[0,1,0] neg_lo:[0,1,0] neg_hi:[0,1,0]
	v_pk_add_f32 v[60:61], v[32:33], v[46:47]
	v_pk_add_f32 v[32:33], v[32:33], v[46:47] neg_lo:[0,1] neg_hi:[0,1]
	v_pk_mul_f32 v[46:47], v[42:43], s[66:67]
	s_nop 0
	v_pk_fma_f32 v[42:43], s[0:1], v[42:43], v[46:47] op_sel:[0,0,1] op_sel_hi:[0,1,0] neg_lo:[0,1,0] neg_hi:[0,1,0]
	v_pk_add_f32 v[46:47], v[26:27], v[42:43]
	v_pk_add_f32 v[26:27], v[26:27], v[42:43] neg_lo:[0,1] neg_hi:[0,1]
	v_pk_mul_f32 v[42:43], v[44:45], s[68:69]
	s_nop 0
	v_pk_fma_f32 v[42:43], s[16:17], v[44:45], v[42:43] op_sel:[0,0,1] op_sel_hi:[0,1,0] neg_lo:[0,1,0] neg_hi:[0,1,0]
	v_pk_add_f32 v[44:45], v[24:25], v[42:43]
	v_pk_add_f32 v[24:25], v[24:25], v[42:43] neg_lo:[0,1] neg_hi:[0,1]
	v_pk_fma_f32 v[42:43], v[58:59], s[46:47], v[2:3] op_sel_hi:[1,0,1]
	v_pk_fma_f32 v[2:3], v[58:59], s[46:47], v[2:3] op_sel_hi:[1,0,1] neg_lo:[0,0,1] neg_hi:[0,0,1]
	v_pk_fma_f32 v[58:59], v[54:55], s[46:47], v[8:9] op_sel_hi:[1,0,1]
	v_pk_fma_f32 v[8:9], v[54:55], s[46:47], v[8:9] op_sel_hi:[1,0,1] neg_lo:[0,0,1] neg_hi:[0,0,1]
	v_pk_fma_f32 v[54:55], v[56:57], s[46:47], v[10:11] op_sel_hi:[1,0,1]
	v_pk_fma_f32 v[10:11], v[56:57], s[46:47], v[10:11] op_sel_hi:[1,0,1] neg_lo:[0,0,1] neg_hi:[0,0,1]
	v_pk_fma_f32 v[56:57], v[52:53], s[46:47], v[14:15] op_sel_hi:[1,0,1]
	v_pk_fma_f32 v[14:15], v[52:53], s[46:47], v[14:15] op_sel_hi:[1,0,1] neg_lo:[0,0,1] neg_hi:[0,0,1]
	v_pk_fma_f32 v[52:53], v[48:49], s[46:47], v[20:21] op_sel_hi:[1,0,1]
	v_pk_fma_f32 v[20:21], v[48:49], s[46:47], v[20:21] op_sel_hi:[1,0,1] neg_lo:[0,0,1] neg_hi:[0,0,1]
	v_pk_fma_f32 v[48:49], v[28:29], s[46:47], v[22:23] op_sel_hi:[1,0,1]
	v_pk_fma_f32 v[22:23], v[28:29], s[46:47], v[22:23] op_sel_hi:[1,0,1] neg_lo:[0,0,1] neg_hi:[0,0,1]
	v_pk_fma_f32 v[28:29], v[12:13], s[46:47], v[16:17] op_sel_hi:[1,0,1]
	v_pk_fma_f32 v[12:13], v[12:13], s[46:47], v[16:17] op_sel_hi:[1,0,1] neg_lo:[0,0,1] neg_hi:[0,0,1]
	v_pk_fma_f32 v[16:17], v[4:5], s[46:47], v[6:7] op_sel_hi:[1,0,1]
	v_pk_fma_f32 v[4:5], v[4:5], s[46:47], v[6:7] op_sel_hi:[1,0,1] neg_lo:[0,0,1] neg_hi:[0,0,1]
	v_pk_add_f32 v[6:7], v[58:59], v[42:43]
	v_pk_add_f32 v[42:43], v[42:43], v[58:59] neg_lo:[0,1] neg_hi:[0,1]
	v_xor_b32_e32 v58, 0x80000000, v9
	v_mov_b32_e32 v59, v8
	v_pk_add_f32 v[8:9], v[2:3], v[58:59]
	v_pk_add_f32 v[2:3], v[2:3], v[58:59] neg_lo:[0,1] neg_hi:[0,1]
	v_pk_add_f32 v[58:59], v[56:57], v[54:55]
	v_pk_add_f32 v[54:55], v[54:55], v[56:57] neg_lo:[0,1] neg_hi:[0,1]
	v_xor_b32_e32 v56, 0x80000000, v15
	v_mov_b32_e32 v57, v14
	v_pk_add_f32 v[14:15], v[10:11], v[56:57]
	v_pk_add_f32 v[10:11], v[10:11], v[56:57] neg_lo:[0,1] neg_hi:[0,1]
	v_pk_add_f32 v[56:57], v[48:49], v[52:53]
	v_pk_add_f32 v[48:49], v[52:53], v[48:49] neg_lo:[0,1] neg_hi:[0,1]
	v_xor_b32_e32 v52, 0x80000000, v23
	v_mov_b32_e32 v53, v22
	v_pk_add_f32 v[22:23], v[20:21], v[52:53]
	v_pk_add_f32 v[20:21], v[20:21], v[52:53] neg_lo:[0,1] neg_hi:[0,1]
	v_pk_add_f32 v[52:53], v[16:17], v[28:29]
	v_pk_add_f32 v[16:17], v[28:29], v[16:17] neg_lo:[0,1] neg_hi:[0,1]
	v_xor_b32_e32 v28, 0x80000000, v5
	v_mov_b32_e32 v29, v4
	v_pk_add_f32 v[4:5], v[12:13], v[28:29]
	v_pk_add_f32 v[12:13], v[12:13], v[28:29] neg_lo:[0,1] neg_hi:[0,1]
	v_pk_add_f32 v[28:29], v[58:59], v[6:7]
	v_pk_add_f32 v[6:7], v[6:7], v[58:59] neg_lo:[0,1] neg_hi:[0,1]
	v_pk_mul_f32 v[58:59], v[14:15], s[66:67]
	s_nop 0
	v_pk_fma_f32 v[14:15], s[0:1], v[14:15], v[58:59] op_sel:[0,0,1] op_sel_hi:[0,1,0]
	v_pk_add_f32 v[58:59], v[14:15], v[8:9]
	v_pk_add_f32 v[8:9], v[8:9], v[14:15] neg_lo:[0,1] neg_hi:[0,1]
	v_xor_b32_e32 v14, 0x80000000, v55
	v_mov_b32_e32 v15, v54
	v_pk_add_f32 v[54:55], v[14:15], v[42:43]
	v_pk_add_f32 v[14:15], v[42:43], v[14:15] neg_lo:[0,1] neg_hi:[0,1]
	v_pk_mul_f32 v[42:43], v[10:11], s[66:67]
	s_nop 0
	v_pk_fma_f32 v[10:11], s[0:1], v[10:11], v[42:43] op_sel:[0,0,1] op_sel_hi:[0,1,0] neg_lo:[0,1,0] neg_hi:[0,1,0]
	v_pk_add_f32 v[42:43], v[10:11], v[2:3]
	v_pk_add_f32 v[2:3], v[2:3], v[10:11] neg_lo:[0,1] neg_hi:[0,1]
	v_pk_add_f32 v[10:11], v[52:53], v[56:57]
	v_pk_add_f32 v[52:53], v[56:57], v[52:53] neg_lo:[0,1] neg_hi:[0,1]
	v_pk_mul_f32 v[56:57], v[4:5], s[66:67]
	s_nop 0
	v_pk_fma_f32 v[4:5], s[0:1], v[4:5], v[56:57] op_sel:[0,0,1] op_sel_hi:[0,1,0]
	v_pk_add_f32 v[56:57], v[4:5], v[22:23]
	v_pk_add_f32 v[4:5], v[22:23], v[4:5] neg_lo:[0,1] neg_hi:[0,1]
	v_xor_b32_e32 v22, 0x80000000, v17
	v_mov_b32_e32 v23, v16
	v_pk_add_f32 v[16:17], v[22:23], v[48:49]
	v_pk_add_f32 v[22:23], v[48:49], v[22:23] neg_lo:[0,1] neg_hi:[0,1]
	v_pk_mul_f32 v[48:49], v[12:13], s[66:67]
	s_nop 0
	v_pk_fma_f32 v[12:13], s[0:1], v[12:13], v[48:49] op_sel:[0,0,1] op_sel_hi:[0,1,0] neg_lo:[0,1,0] neg_hi:[0,1,0]
	v_pk_add_f32 v[48:49], v[12:13], v[20:21]
	v_pk_add_f32 v[12:13], v[20:21], v[12:13] neg_lo:[0,1] neg_hi:[0,1]
	v_pk_add_f32 v[20:21], v[10:11], v[28:29]
	v_pk_add_f32 v[10:11], v[28:29], v[10:11] neg_lo:[0,1] neg_hi:[0,1]
	v_pk_mul_f32 v[28:29], v[56:57], s[68:69]
	s_nop 0
	v_pk_fma_f32 v[28:29], s[16:17], v[56:57], v[28:29] op_sel:[0,0,1] op_sel_hi:[0,1,0]
	v_pk_add_f32 v[56:57], v[28:29], v[58:59]
	v_pk_add_f32 v[28:29], v[58:59], v[28:29] neg_lo:[0,1] neg_hi:[0,1]
	v_pk_mul_f32 v[58:59], v[16:17], s[66:67]
	s_nop 0
	v_pk_fma_f32 v[16:17], s[0:1], v[16:17], v[58:59] op_sel:[0,0,1] op_sel_hi:[0,1,0]
	v_pk_add_f32 v[58:59], v[16:17], v[54:55]
	v_pk_add_f32 v[16:17], v[54:55], v[16:17] neg_lo:[0,1] neg_hi:[0,1]
	v_pk_mul_f32 v[54:55], v[48:49], s[16:17]
	s_nop 0
	v_pk_fma_f32 v[48:49], s[72:73], v[48:49], v[54:55] op_sel:[0,0,1] op_sel_hi:[0,1,0]
	v_pk_add_f32 v[54:55], v[48:49], v[42:43]
	v_pk_add_f32 v[42:43], v[42:43], v[48:49] neg_lo:[0,1] neg_hi:[0,1]
	v_xor_b32_e32 v48, 0x80000000, v53
	v_mov_b32_e32 v49, v52
	v_pk_add_f32 v[52:53], v[48:49], v[6:7]
	v_pk_add_f32 v[6:7], v[6:7], v[48:49] neg_lo:[0,1] neg_hi:[0,1]
	v_pk_mul_f32 v[48:49], v[4:5], s[16:17]
	s_nop 0
	v_pk_fma_f32 v[4:5], s[72:73], v[4:5], v[48:49] op_sel:[0,0,1] op_sel_hi:[0,1,0] neg_lo:[0,1,0] neg_hi:[0,1,0]
	v_pk_add_f32 v[48:49], v[4:5], v[8:9]
	v_pk_add_f32 v[4:5], v[8:9], v[4:5] neg_lo:[0,1] neg_hi:[0,1]
	v_pk_mul_f32 v[8:9], v[22:23], s[66:67]
	s_nop 0
	v_pk_fma_f32 v[8:9], s[0:1], v[22:23], v[8:9] op_sel:[0,0,1] op_sel_hi:[0,1,0] neg_lo:[0,1,0] neg_hi:[0,1,0]
	v_pk_add_f32 v[22:23], v[8:9], v[14:15]
	v_pk_add_f32 v[8:9], v[14:15], v[8:9] neg_lo:[0,1] neg_hi:[0,1]
	v_pk_mul_f32 v[14:15], v[12:13], s[68:69]
	s_nop 0
	v_pk_fma_f32 v[12:13], s[16:17], v[12:13], v[14:15] op_sel:[0,0,1] op_sel_hi:[0,1,0] neg_lo:[0,1,0] neg_hi:[0,1,0]
	v_pk_add_f32 v[14:15], v[12:13], v[2:3]
	v_pk_add_f32 v[2:3], v[2:3], v[12:13] neg_lo:[0,1] neg_hi:[0,1]
	ds_write_b64 v211, v[50:51]
	ds_write_b64 v212, v[20:21]
	ds_write_b64 v211, v[66:67] offset:8
	ds_write_b64 v212, v[56:57] offset:8
	ds_write_b64 v211, v[68:69] offset:16
	ds_write_b64 v212, v[58:59] offset:16
	ds_write_b64 v211, v[62:63] offset:24
	ds_write_b64 v212, v[54:55] offset:24
	ds_write_b64 v211, v[38:39] offset:32
	ds_write_b64 v212, v[52:53] offset:32
	ds_write_b64 v211, v[60:61] offset:40
	ds_write_b64 v212, v[48:49] offset:40
	ds_write_b64 v211, v[46:47] offset:48
	ds_write_b64 v212, v[22:23] offset:48
	ds_write_b64 v211, v[44:45] offset:56
	ds_write_b64 v212, v[14:15] offset:56
	ds_write_b64 v211, v[36:37] offset:64
	ds_write_b64 v212, v[10:11] offset:64
	ds_write_b64 v211, v[64:65] offset:72
	ds_write_b64 v212, v[28:29] offset:72
	ds_write_b64 v211, v[34:35] offset:80
	ds_write_b64 v212, v[16:17] offset:80
	ds_write_b64 v211, v[40:41] offset:88
	ds_write_b64 v212, v[42:43] offset:88
	ds_write_b64 v211, v[30:31] offset:96
	ds_write_b64 v212, v[6:7] offset:96
	ds_write_b64 v211, v[32:33] offset:104
	ds_write_b64 v212, v[4:5] offset:104
	ds_write_b64 v211, v[26:27] offset:112
	ds_write_b64 v212, v[8:9] offset:112
	ds_write_b64 v211, v[24:25] offset:120
	ds_write_b64 v212, v[2:3] offset:120
	v_mov_b32_e32 v2, v210
	s_waitcnt lgkmcnt(0)
	s_barrier
	s_nop 0
	v_and_b32_e32 v4, 15, v2
	v_cvt_f32_ubyte0_e32 v3, v4
	v_mul_f32_e32 v5, 0x3b800000, v3
	v_sin_f32_e32 v3, v5
	v_lshlrev_b32_e32 v6, 4, v2
	v_cos_f32_e32 v2, v5
	v_lshlrev_b32_e32 v7, 3, v4
	v_xor_b32_e32 v16, 0x80000000, v3
	v_mov_b32_e32 v17, v3
	v_pk_mul_f32 v[4:5], v[2:3], v[16:17] op_sel:[1,0] op_sel_hi:[0,1]
	v_pk_fma_f32 v[40:41], v[2:3], v[2:3], v[4:5] op_sel_hi:[0,1,1]
	v_pk_mul_f32 v[4:5], v[16:17], v[40:41] op_sel:[0,1] op_sel_hi:[1,0]
	v_xor_b32_e32 v44, 0x80000000, v41
	v_mov_b32_e32 v45, v41
	v_pk_fma_f32 v[42:43], v[2:3], v[40:41], v[4:5] op_sel_hi:[0,1,1]
	v_pk_mul_f32 v[4:5], v[40:41], v[44:45] op_sel:[1,0] op_sel_hi:[0,1]
	v_pk_fma_f32 v[46:47], v[40:41], v[40:41], v[4:5] op_sel_hi:[1,0,1]
	v_xor_b32_e32 v50, 0x80000000, v43
	v_pk_mul_f32 v[4:5], v[16:17], v[46:47] op_sel:[0,1] op_sel_hi:[1,0]
	v_mov_b32_e32 v51, v43
	v_pk_fma_f32 v[52:53], v[2:3], v[46:47], v[4:5] op_sel_hi:[0,1,1]
	v_pk_mul_f32 v[4:5], v[44:45], v[46:47] op_sel:[0,1] op_sel_hi:[1,0]
	v_xor_b32_e32 v48, 0x80000000, v47
	v_mov_b32_e32 v49, v47
	v_pk_fma_f32 v[56:57], v[40:41], v[46:47], v[4:5] op_sel_hi:[0,1,1]
	v_pk_mul_f32 v[4:5], v[46:47], v[50:51] op_sel:[1,0] op_sel_hi:[0,1]
	v_pk_fma_f32 v[60:61], v[46:47], v[42:43], v[4:5] op_sel_hi:[1,0,1]
	v_pk_mul_f32 v[4:5], v[46:47], v[48:49] op_sel:[1,0] op_sel_hi:[0,1]
	v_pk_fma_f32 v[64:65], v[46:47], v[46:47], v[4:5] op_sel_hi:[1,0,1]
	v_xor_b32_e32 v54, 0x80000000, v53
	v_pk_mul_f32 v[4:5], v[16:17], v[64:65] op_sel:[0,1] op_sel_hi:[1,0]
	v_mov_b32_e32 v55, v53
	v_pk_fma_f32 v[68:69], v[2:3], v[64:65], v[4:5] op_sel_hi:[0,1,1]
	v_pk_mul_f32 v[4:5], v[44:45], v[64:65] op_sel:[0,1] op_sel_hi:[1,0]
	v_xor_b32_e32 v58, 0x80000000, v57
	v_pk_fma_f32 v[72:73], v[40:41], v[64:65], v[4:5] op_sel_hi:[0,1,1]
	v_pk_mul_f32 v[4:5], v[50:51], v[64:65] op_sel:[0,1] op_sel_hi:[1,0]
	v_mov_b32_e32 v59, v57
	v_pk_fma_f32 v[76:77], v[42:43], v[64:65], v[4:5] op_sel_hi:[0,1,1]
	v_pk_mul_f32 v[4:5], v[48:49], v[64:65] op_sel:[0,1] op_sel_hi:[1,0]
	v_xor_b32_e32 v62, 0x80000000, v61
	v_pk_fma_f32 v[80:81], v[46:47], v[64:65], v[4:5] op_sel_hi:[0,1,1]
	v_pk_mul_f32 v[4:5], v[16:17], v[80:81] op_sel:[0,1] op_sel_hi:[1,0]
	v_mov_b32_e32 v63, v61
	v_pk_fma_f32 v[84:85], v[2:3], v[80:81], v[4:5] op_sel_hi:[0,1,1]
	v_pk_mul_f32 v[4:5], v[44:45], v[80:81] op_sel:[0,1] op_sel_hi:[1,0]
	v_and_b32_e32 v3, 0xffffff00, v6
	v_pk_fma_f32 v[88:89], v[40:41], v[80:81], v[4:5] op_sel_hi:[0,1,1]
	v_pk_mul_f32 v[4:5], v[50:51], v[80:81] op_sel:[0,1] op_sel_hi:[1,0]
	v_xor_b32_e32 v66, 0x80000000, v65
	v_pk_fma_f32 v[92:93], v[42:43], v[80:81], v[4:5] op_sel_hi:[0,1,1]
	v_lshlrev_b32_e32 v4, 3, v3
	v_add3_u32 v18, 0, v7, v4
	v_ashrrev_i32_e32 v4, 2, v3
	v_add_u32_e32 v98, v18, v4
	ds_read2_b64 v[4:7], v98 offset1:16
	ds_read2_b64 v[8:11], v98 offset0:33 offset1:49
	ds_read2_b64 v[12:15], v98 offset0:66 offset1:82
	ds_read2_b64 v[20:23], v98 offset0:132 offset1:148
	ds_read2_b64 v[24:27], v98 offset0:99 offset1:115
	ds_read2_b64 v[28:31], v98 offset0:165 offset1:181
	ds_read2_b64 v[32:35], v98 offset0:198 offset1:214
	ds_read2_b64 v[36:39], v98 offset0:231 offset1:247
	s_waitcnt lgkmcnt(4)
	v_pk_mul_f32 v[96:97], v[16:17], v[20:21] op_sel:[0,1] op_sel_hi:[1,0]
	v_mov_b32_e32 v67, v65
	v_pk_fma_f32 v[20:21], v[2:3], v[20:21], v[96:97] op_sel_hi:[0,1,1]
	v_pk_mul_f32 v[96:97], v[12:13], v[44:45] op_sel:[1,0] op_sel_hi:[0,1]
	v_pk_fma_f32 v[12:13], v[12:13], v[40:41], v[96:97] op_sel_hi:[1,0,1]
	s_waitcnt lgkmcnt(1)
	v_pk_mul_f32 v[96:97], v[50:51], v[32:33] op_sel:[0,1] op_sel_hi:[1,0]
	v_xor_b32_e32 v70, 0x80000000, v69
	v_pk_fma_f32 v[32:33], v[42:43], v[32:33], v[96:97] op_sel_hi:[0,1,1]
	v_pk_mul_f32 v[96:97], v[8:9], v[48:49] op_sel:[1,0] op_sel_hi:[0,1]
	v_pk_fma_f32 v[8:9], v[8:9], v[46:47], v[96:97] op_sel_hi:[1,0,1]
	v_pk_mul_f32 v[96:97], v[28:29], v[54:55] op_sel:[1,0] op_sel_hi:[0,1]
	v_pk_fma_f32 v[28:29], v[28:29], v[52:53], v[96:97] op_sel_hi:[1,0,1]
	v_pk_mul_f32 v[96:97], v[24:25], v[58:59] op_sel:[1,0] op_sel_hi:[0,1]
	v_pk_fma_f32 v[24:25], v[24:25], v[56:57], v[96:97] op_sel_hi:[1,0,1]
	s_waitcnt lgkmcnt(0)
	v_pk_mul_f32 v[96:97], v[36:37], v[62:63] op_sel:[1,0] op_sel_hi:[0,1]
	v_mov_b32_e32 v71, v69
	v_pk_fma_f32 v[36:37], v[36:37], v[60:61], v[96:97] op_sel_hi:[1,0,1]
	v_pk_mul_f32 v[96:97], v[6:7], v[66:67] op_sel:[1,0] op_sel_hi:[0,1]
	v_xor_b32_e32 v74, 0x80000000, v73
	v_mov_b32_e32 v75, v73
	v_pk_fma_f32 v[6:7], v[6:7], v[64:65], v[96:97] op_sel_hi:[1,0,1]
	v_pk_mul_f32 v[96:97], v[22:23], v[70:71] op_sel:[1,0] op_sel_hi:[0,1]
	v_xor_b32_e32 v78, 0x80000000, v77
	v_mov_b32_e32 v79, v77
	v_pk_fma_f32 v[22:23], v[22:23], v[68:69], v[96:97] op_sel_hi:[1,0,1]
	v_pk_mul_f32 v[96:97], v[14:15], v[74:75] op_sel:[1,0] op_sel_hi:[0,1]
	v_xor_b32_e32 v82, 0x80000000, v81
	v_mov_b32_e32 v83, v81
	v_pk_fma_f32 v[14:15], v[14:15], v[72:73], v[96:97] op_sel_hi:[1,0,1]
	v_pk_mul_f32 v[96:97], v[34:35], v[78:79] op_sel:[1,0] op_sel_hi:[0,1]
	v_xor_b32_e32 v86, 0x80000000, v85
	v_mov_b32_e32 v87, v85
	v_pk_fma_f32 v[34:35], v[34:35], v[76:77], v[96:97] op_sel_hi:[1,0,1]
	v_pk_mul_f32 v[96:97], v[10:11], v[82:83] op_sel:[1,0] op_sel_hi:[0,1]
	v_xor_b32_e32 v90, 0x80000000, v89
	v_mov_b32_e32 v91, v89
	v_pk_fma_f32 v[10:11], v[10:11], v[80:81], v[96:97] op_sel_hi:[1,0,1]
	v_pk_mul_f32 v[96:97], v[30:31], v[86:87] op_sel:[1,0] op_sel_hi:[0,1]
	v_xor_b32_e32 v94, 0x80000000, v93
	v_mov_b32_e32 v95, v93
	v_pk_fma_f32 v[30:31], v[30:31], v[84:85], v[96:97] op_sel_hi:[1,0,1]
	v_pk_mul_f32 v[96:97], v[26:27], v[90:91] op_sel:[1,0] op_sel_hi:[0,1]
	v_pk_fma_f32 v[26:27], v[26:27], v[88:89], v[96:97] op_sel_hi:[1,0,1]
	v_pk_mul_f32 v[96:97], v[38:39], v[94:95] op_sel:[1,0] op_sel_hi:[0,1]
	v_pk_fma_f32 v[38:39], v[38:39], v[92:93], v[96:97] op_sel_hi:[1,0,1]
	v_pk_add_f32 v[96:97], v[4:5], v[6:7]
	v_pk_add_f32 v[4:5], v[4:5], v[6:7] neg_lo:[0,1] neg_hi:[0,1]
	v_pk_add_f32 v[6:7], v[8:9], v[10:11]
	v_pk_add_f32 v[8:9], v[8:9], v[10:11] neg_lo:[0,1] neg_hi:[0,1]
	v_pk_add_f32 v[10:11], v[12:13], v[14:15]
	v_pk_add_f32 v[12:13], v[12:13], v[14:15] neg_lo:[0,1] neg_hi:[0,1]
	v_pk_add_f32 v[14:15], v[24:25], v[26:27]
	v_pk_add_f32 v[24:25], v[24:25], v[26:27] neg_lo:[0,1] neg_hi:[0,1]
	v_pk_add_f32 v[26:27], v[20:21], v[22:23]
	v_pk_add_f32 v[20:21], v[20:21], v[22:23] neg_lo:[0,1] neg_hi:[0,1]
	v_pk_add_f32 v[22:23], v[28:29], v[30:31]
	v_pk_add_f32 v[28:29], v[28:29], v[30:31] neg_lo:[0,1] neg_hi:[0,1]
	v_pk_add_f32 v[30:31], v[32:33], v[34:35]
	v_pk_add_f32 v[32:33], v[32:33], v[34:35] neg_lo:[0,1] neg_hi:[0,1]
	v_pk_add_f32 v[34:35], v[36:37], v[38:39]
	v_pk_add_f32 v[36:37], v[36:37], v[38:39] neg_lo:[0,1] neg_hi:[0,1]
	v_pk_add_f32 v[38:39], v[96:97], v[6:7]
	v_pk_add_f32 v[6:7], v[96:97], v[6:7] neg_lo:[0,1] neg_hi:[0,1]
	v_xor_b32_e32 v96, 0x80000000, v9
	v_mov_b32_e32 v97, v8
	v_pk_add_f32 v[8:9], v[4:5], v[96:97]
	v_pk_add_f32 v[4:5], v[4:5], v[96:97] neg_lo:[0,1] neg_hi:[0,1]
	v_pk_add_f32 v[96:97], v[10:11], v[14:15]
	v_pk_add_f32 v[10:11], v[10:11], v[14:15] neg_lo:[0,1] neg_hi:[0,1]
	v_xor_b32_e32 v14, 0x80000000, v25
	v_mov_b32_e32 v15, v24
	v_pk_add_f32 v[24:25], v[12:13], v[14:15]
	v_pk_add_f32 v[12:13], v[12:13], v[14:15] neg_lo:[0,1] neg_hi:[0,1]
	v_pk_add_f32 v[14:15], v[26:27], v[22:23]
	v_pk_add_f32 v[22:23], v[26:27], v[22:23] neg_lo:[0,1] neg_hi:[0,1]
	v_xor_b32_e32 v26, 0x80000000, v29
	v_mov_b32_e32 v27, v28
	v_pk_add_f32 v[28:29], v[20:21], v[26:27]
	v_pk_add_f32 v[20:21], v[20:21], v[26:27] neg_lo:[0,1] neg_hi:[0,1]
	v_pk_add_f32 v[26:27], v[30:31], v[34:35]
	v_pk_add_f32 v[30:31], v[30:31], v[34:35] neg_lo:[0,1] neg_hi:[0,1]
	v_xor_b32_e32 v34, 0x80000000, v37
	v_mov_b32_e32 v35, v36
	v_pk_add_f32 v[36:37], v[32:33], v[34:35]
	v_pk_add_f32 v[32:33], v[32:33], v[34:35] neg_lo:[0,1] neg_hi:[0,1]
	v_pk_add_f32 v[34:35], v[38:39], v[96:97]
	v_pk_add_f32 v[38:39], v[38:39], v[96:97] neg_lo:[0,1] neg_hi:[0,1]
	v_pk_mul_f32 v[96:97], v[24:25], s[66:67]
	v_add_u32_e32 v3, 0x2000, v3
	v_pk_fma_f32 v[24:25], v[24:25], s[0:1], v[96:97] op_sel:[0,0,1] op_sel_hi:[1,0,0]
	v_ashrrev_i32_e32 v3, 2, v3
	v_pk_add_f32 v[96:97], v[8:9], v[24:25]
	v_pk_add_f32 v[8:9], v[8:9], v[24:25] neg_lo:[0,1] neg_hi:[0,1]
	v_xor_b32_e32 v24, 0x80000000, v11
	v_mov_b32_e32 v25, v10
	v_pk_add_f32 v[10:11], v[6:7], v[24:25]
	v_pk_add_f32 v[6:7], v[6:7], v[24:25] neg_lo:[0,1] neg_hi:[0,1]
	v_pk_mul_f32 v[24:25], v[12:13], s[66:67]
	v_add3_u32 v18, v18, v3, s5
	v_pk_fma_f32 v[12:13], s[0:1], v[12:13], v[24:25] op_sel:[0,0,1] op_sel_hi:[0,1,0] neg_lo:[0,1,0] neg_hi:[0,1,0]
	v_pk_add_f32 v[24:25], v[4:5], v[12:13]
	v_pk_add_f32 v[4:5], v[4:5], v[12:13] neg_lo:[0,1] neg_hi:[0,1]
	v_pk_add_f32 v[12:13], v[14:15], v[26:27]
	v_pk_add_f32 v[14:15], v[14:15], v[26:27] neg_lo:[0,1] neg_hi:[0,1]
	v_pk_mul_f32 v[26:27], v[36:37], s[66:67]
	s_nop 0
	v_pk_fma_f32 v[26:27], s[0:1], v[36:37], v[26:27] op_sel:[0,0,1] op_sel_hi:[0,1,0]
	v_pk_add_f32 v[36:37], v[28:29], v[26:27]
	v_pk_add_f32 v[26:27], v[28:29], v[26:27] neg_lo:[0,1] neg_hi:[0,1]
	v_xor_b32_e32 v28, 0x80000000, v31
	v_mov_b32_e32 v29, v30
	v_pk_add_f32 v[30:31], v[22:23], v[28:29]
	v_pk_add_f32 v[22:23], v[22:23], v[28:29] neg_lo:[0,1] neg_hi:[0,1]
	v_pk_mul_f32 v[28:29], v[32:33], s[66:67]
	s_nop 0
	v_pk_fma_f32 v[28:29], s[0:1], v[32:33], v[28:29] op_sel:[0,0,1] op_sel_hi:[0,1,0] neg_lo:[0,1,0] neg_hi:[0,1,0]
	v_pk_add_f32 v[32:33], v[20:21], v[28:29]
	v_pk_add_f32 v[20:21], v[20:21], v[28:29] neg_lo:[0,1] neg_hi:[0,1]
	v_pk_add_f32 v[28:29], v[34:35], v[12:13]
	v_pk_add_f32 v[12:13], v[34:35], v[12:13] neg_lo:[0,1] neg_hi:[0,1]
	v_pk_mul_f32 v[34:35], v[36:37], s[68:69]
	s_nop 0
	v_pk_fma_f32 v[34:35], s[16:17], v[36:37], v[34:35] op_sel:[0,0,1] op_sel_hi:[0,1,0]
	v_pk_add_f32 v[36:37], v[96:97], v[34:35]
	v_pk_add_f32 v[34:35], v[96:97], v[34:35] neg_lo:[0,1] neg_hi:[0,1]
	v_pk_mul_f32 v[96:97], v[30:31], s[66:67]
	s_nop 0
	v_pk_fma_f32 v[30:31], s[0:1], v[30:31], v[96:97] op_sel:[0,0,1] op_sel_hi:[0,1,0]
	v_pk_add_f32 v[96:97], v[10:11], v[30:31]
	v_pk_add_f32 v[10:11], v[10:11], v[30:31] neg_lo:[0,1] neg_hi:[0,1]
	v_pk_mul_f32 v[30:31], v[32:33], s[16:17]
	s_nop 0
	v_pk_fma_f32 v[30:31], s[72:73], v[32:33], v[30:31] op_sel:[0,0,1] op_sel_hi:[0,1,0]
	v_pk_add_f32 v[32:33], v[24:25], v[30:31]
	v_pk_add_f32 v[24:25], v[24:25], v[30:31] neg_lo:[0,1] neg_hi:[0,1]
	v_xor_b32_e32 v30, 0x80000000, v15
	v_mov_b32_e32 v31, v14
	v_pk_add_f32 v[14:15], v[38:39], v[30:31]
	v_pk_add_f32 v[30:31], v[38:39], v[30:31] neg_lo:[0,1] neg_hi:[0,1]
	v_pk_mul_f32 v[38:39], v[26:27], s[16:17]
	s_nop 0
	v_pk_fma_f32 v[26:27], s[72:73], v[26:27], v[38:39] op_sel:[0,0,1] op_sel_hi:[0,1,0] neg_lo:[0,1,0] neg_hi:[0,1,0]
	v_pk_add_f32 v[38:39], v[8:9], v[26:27]
	v_pk_add_f32 v[8:9], v[8:9], v[26:27] neg_lo:[0,1] neg_hi:[0,1]
	v_pk_mul_f32 v[26:27], v[22:23], s[66:67]
	s_nop 0
	v_pk_fma_f32 v[22:23], s[0:1], v[22:23], v[26:27] op_sel:[0,0,1] op_sel_hi:[0,1,0] neg_lo:[0,1,0] neg_hi:[0,1,0]
	v_pk_add_f32 v[26:27], v[6:7], v[22:23]
	v_pk_add_f32 v[6:7], v[6:7], v[22:23] neg_lo:[0,1] neg_hi:[0,1]
	v_pk_mul_f32 v[22:23], v[20:21], s[68:69]
	s_nop 0
	v_pk_fma_f32 v[20:21], s[16:17], v[20:21], v[22:23] op_sel:[0,0,1] op_sel_hi:[0,1,0] neg_lo:[0,1,0] neg_hi:[0,1,0]
	v_pk_add_f32 v[22:23], v[4:5], v[20:21]
	v_pk_add_f32 v[4:5], v[4:5], v[20:21] neg_lo:[0,1] neg_hi:[0,1]
	ds_write2_b64 v98, v[28:29], v[36:37] offset1:16
	ds_write2_b64 v98, v[96:97], v[32:33] offset0:33 offset1:49
	ds_write2_b64 v98, v[14:15], v[38:39] offset0:66 offset1:82
	ds_write2_b64 v98, v[26:27], v[22:23] offset0:99 offset1:115
	ds_write2_b64 v98, v[12:13], v[34:35] offset0:132 offset1:148
	ds_write2_b64 v98, v[10:11], v[24:25] offset0:165 offset1:181
	ds_write2_b64 v98, v[30:31], v[8:9] offset0:198 offset1:214
	ds_write2_b64 v98, v[6:7], v[4:5] offset0:231 offset1:247
	ds_read2_b64 v[4:7], v18 offset1:16
	ds_read2_b64 v[8:11], v18 offset0:33 offset1:49
	ds_read2_b64 v[12:15], v18 offset0:66 offset1:82
	ds_read2_b64 v[20:23], v18 offset0:132 offset1:148
	ds_read2_b64 v[24:27], v18 offset0:99 offset1:115
	ds_read2_b64 v[28:31], v18 offset0:165 offset1:181
	ds_read2_b64 v[32:35], v18 offset0:198 offset1:214
	ds_read2_b64 v[36:39], v18 offset0:231 offset1:247
	s_waitcnt lgkmcnt(4)
	v_pk_mul_f32 v[16:17], v[20:21], v[16:17] op_sel:[1,0] op_sel_hi:[0,1]
	v_pk_fma_f32 v[2:3], v[2:3], v[20:21], v[16:17] op_sel_hi:[0,1,1]
	v_pk_mul_f32 v[16:17], v[44:45], v[12:13] op_sel:[0,1] op_sel_hi:[1,0]
	v_pk_mul_f32 v[20:21], v[48:49], v[8:9] op_sel:[0,1] op_sel_hi:[1,0]
	v_pk_fma_f32 v[12:13], v[40:41], v[12:13], v[16:17] op_sel_hi:[0,1,1]
	s_waitcnt lgkmcnt(1)
	v_pk_mul_f32 v[16:17], v[50:51], v[32:33] op_sel:[0,1] op_sel_hi:[1,0]
	v_pk_fma_f32 v[8:9], v[46:47], v[8:9], v[20:21] op_sel_hi:[0,1,1]
	v_pk_fma_f32 v[16:17], v[42:43], v[32:33], v[16:17] op_sel_hi:[0,1,1]
	v_pk_mul_f32 v[32:33], v[66:67], v[6:7] op_sel:[0,1] op_sel_hi:[1,0]
	v_pk_mul_f32 v[20:21], v[54:55], v[28:29] op_sel:[0,1] op_sel_hi:[1,0]
	v_pk_fma_f32 v[6:7], v[64:65], v[6:7], v[32:33] op_sel_hi:[0,1,1]
	v_pk_mul_f32 v[32:33], v[70:71], v[22:23] op_sel:[0,1] op_sel_hi:[1,0]
	v_pk_fma_f32 v[20:21], v[52:53], v[28:29], v[20:21] op_sel_hi:[0,1,1]
	v_pk_fma_f32 v[22:23], v[68:69], v[22:23], v[32:33] op_sel_hi:[0,1,1]
	v_pk_mul_f32 v[32:33], v[74:75], v[14:15] op_sel:[0,1] op_sel_hi:[1,0]
	v_pk_mul_f32 v[28:29], v[58:59], v[24:25] op_sel:[0,1] op_sel_hi:[1,0]
	v_pk_fma_f32 v[14:15], v[72:73], v[14:15], v[32:33] op_sel_hi:[0,1,1]
	v_pk_mul_f32 v[32:33], v[78:79], v[34:35] op_sel:[0,1] op_sel_hi:[1,0]
	v_pk_fma_f32 v[24:25], v[56:57], v[24:25], v[28:29] op_sel_hi:[0,1,1]
	v_pk_fma_f32 v[32:33], v[76:77], v[34:35], v[32:33] op_sel_hi:[0,1,1]
	v_pk_mul_f32 v[34:35], v[82:83], v[10:11] op_sel:[0,1] op_sel_hi:[1,0]
	s_waitcnt lgkmcnt(0)
	v_pk_mul_f32 v[28:29], v[62:63], v[36:37] op_sel:[0,1] op_sel_hi:[1,0]
	v_pk_fma_f32 v[10:11], v[80:81], v[10:11], v[34:35] op_sel_hi:[0,1,1]
	v_pk_mul_f32 v[34:35], v[86:87], v[30:31] op_sel:[0,1] op_sel_hi:[1,0]
	v_pk_fma_f32 v[28:29], v[60:61], v[36:37], v[28:29] op_sel_hi:[0,1,1]
	v_pk_fma_f32 v[30:31], v[84:85], v[30:31], v[34:35] op_sel_hi:[0,1,1]
	v_pk_mul_f32 v[34:35], v[90:91], v[26:27] op_sel:[0,1] op_sel_hi:[1,0]
	v_pk_add_f32 v[36:37], v[4:5], v[6:7]
	v_pk_fma_f32 v[26:27], v[88:89], v[26:27], v[34:35] op_sel_hi:[0,1,1]
	v_pk_mul_f32 v[34:35], v[94:95], v[38:39] op_sel:[0,1] op_sel_hi:[1,0]
	v_pk_add_f32 v[4:5], v[4:5], v[6:7] neg_lo:[0,1] neg_hi:[0,1]
	v_pk_fma_f32 v[34:35], v[92:93], v[38:39], v[34:35] op_sel_hi:[0,1,1]
	v_pk_add_f32 v[6:7], v[8:9], v[10:11]
	v_pk_add_f32 v[8:9], v[8:9], v[10:11] neg_lo:[0,1] neg_hi:[0,1]
	v_pk_add_f32 v[10:11], v[12:13], v[14:15]
	v_pk_add_f32 v[12:13], v[12:13], v[14:15] neg_lo:[0,1] neg_hi:[0,1]
	v_pk_add_f32 v[14:15], v[24:25], v[26:27]
	v_pk_add_f32 v[24:25], v[24:25], v[26:27] neg_lo:[0,1] neg_hi:[0,1]
	v_pk_add_f32 v[26:27], v[2:3], v[22:23]
	v_pk_add_f32 v[2:3], v[2:3], v[22:23] neg_lo:[0,1] neg_hi:[0,1]
	v_pk_add_f32 v[22:23], v[20:21], v[30:31]
	v_pk_add_f32 v[20:21], v[20:21], v[30:31] neg_lo:[0,1] neg_hi:[0,1]
	v_pk_add_f32 v[30:31], v[16:17], v[32:33]
	v_pk_add_f32 v[16:17], v[16:17], v[32:33] neg_lo:[0,1] neg_hi:[0,1]
	v_pk_add_f32 v[32:33], v[28:29], v[34:35]
	v_pk_add_f32 v[28:29], v[28:29], v[34:35] neg_lo:[0,1] neg_hi:[0,1]
	v_pk_add_f32 v[34:35], v[36:37], v[6:7]
	v_pk_add_f32 v[6:7], v[36:37], v[6:7] neg_lo:[0,1] neg_hi:[0,1]
	v_xor_b32_e32 v36, 0x80000000, v9
	v_mov_b32_e32 v37, v8
	v_pk_add_f32 v[8:9], v[4:5], v[36:37]
	v_pk_add_f32 v[4:5], v[4:5], v[36:37] neg_lo:[0,1] neg_hi:[0,1]
	v_pk_add_f32 v[36:37], v[10:11], v[14:15]
	v_pk_add_f32 v[10:11], v[10:11], v[14:15] neg_lo:[0,1] neg_hi:[0,1]
	v_xor_b32_e32 v14, 0x80000000, v25
	v_mov_b32_e32 v15, v24
	v_pk_add_f32 v[24:25], v[12:13], v[14:15]
	v_pk_add_f32 v[12:13], v[12:13], v[14:15] neg_lo:[0,1] neg_hi:[0,1]
	v_pk_add_f32 v[14:15], v[26:27], v[22:23]
	v_pk_add_f32 v[22:23], v[26:27], v[22:23] neg_lo:[0,1] neg_hi:[0,1]
	v_xor_b32_e32 v26, 0x80000000, v21
	v_mov_b32_e32 v27, v20
	v_pk_add_f32 v[20:21], v[2:3], v[26:27]
	v_pk_add_f32 v[2:3], v[2:3], v[26:27] neg_lo:[0,1] neg_hi:[0,1]
	v_pk_add_f32 v[26:27], v[30:31], v[32:33]
	v_pk_add_f32 v[30:31], v[30:31], v[32:33] neg_lo:[0,1] neg_hi:[0,1]
	v_xor_b32_e32 v32, 0x80000000, v29
	v_mov_b32_e32 v33, v28
	v_pk_add_f32 v[28:29], v[16:17], v[32:33]
	v_pk_add_f32 v[16:17], v[16:17], v[32:33] neg_lo:[0,1] neg_hi:[0,1]
	v_pk_add_f32 v[32:33], v[34:35], v[36:37]
	v_pk_add_f32 v[34:35], v[34:35], v[36:37] neg_lo:[0,1] neg_hi:[0,1]
	v_pk_mul_f32 v[36:37], v[24:25], s[66:67]
	v_mov_b32_e32 v39, 0
	v_pk_fma_f32 v[24:25], v[24:25], s[0:1], v[36:37] op_sel:[0,0,1] op_sel_hi:[1,0,0]
	v_mov_b32_e32 v41, 0
	v_pk_add_f32 v[36:37], v[8:9], v[24:25]
	v_pk_add_f32 v[8:9], v[8:9], v[24:25] neg_lo:[0,1] neg_hi:[0,1]
	v_xor_b32_e32 v24, 0x80000000, v11
	v_mov_b32_e32 v25, v10
	v_pk_add_f32 v[10:11], v[6:7], v[24:25]
	v_pk_add_f32 v[6:7], v[6:7], v[24:25] neg_lo:[0,1] neg_hi:[0,1]
	v_pk_mul_f32 v[24:25], v[12:13], s[66:67]
	s_nop 0
	v_pk_fma_f32 v[12:13], s[0:1], v[12:13], v[24:25] op_sel:[0,0,1] op_sel_hi:[0,1,0] neg_lo:[0,1,0] neg_hi:[0,1,0]
	v_pk_add_f32 v[24:25], v[4:5], v[12:13]
	v_pk_add_f32 v[4:5], v[4:5], v[12:13] neg_lo:[0,1] neg_hi:[0,1]
	v_pk_add_f32 v[12:13], v[14:15], v[26:27]
	v_pk_add_f32 v[14:15], v[14:15], v[26:27] neg_lo:[0,1] neg_hi:[0,1]
	v_pk_mul_f32 v[26:27], v[28:29], s[66:67]
	s_nop 0
	v_pk_fma_f32 v[26:27], s[0:1], v[28:29], v[26:27] op_sel:[0,0,1] op_sel_hi:[0,1,0]
	v_pk_add_f32 v[28:29], v[20:21], v[26:27]
	v_pk_add_f32 v[20:21], v[20:21], v[26:27] neg_lo:[0,1] neg_hi:[0,1]
	v_xor_b32_e32 v26, 0x80000000, v31
	v_mov_b32_e32 v27, v30
	v_pk_add_f32 v[30:31], v[22:23], v[26:27]
	v_pk_add_f32 v[22:23], v[22:23], v[26:27] neg_lo:[0,1] neg_hi:[0,1]
	v_pk_mul_f32 v[26:27], v[16:17], s[66:67]
	s_nop 0
	v_pk_fma_f32 v[16:17], s[0:1], v[16:17], v[26:27] op_sel:[0,0,1] op_sel_hi:[0,1,0] neg_lo:[0,1,0] neg_hi:[0,1,0]
	v_pk_add_f32 v[26:27], v[2:3], v[16:17]
	v_pk_add_f32 v[2:3], v[2:3], v[16:17] neg_lo:[0,1] neg_hi:[0,1]
	v_pk_add_f32 v[16:17], v[32:33], v[12:13]
	v_pk_add_f32 v[12:13], v[32:33], v[12:13] neg_lo:[0,1] neg_hi:[0,1]
	v_pk_mul_f32 v[32:33], v[28:29], s[68:69]
	s_nop 0
	v_pk_fma_f32 v[28:29], s[16:17], v[28:29], v[32:33] op_sel:[0,0,1] op_sel_hi:[0,1,0]
	v_pk_add_f32 v[32:33], v[36:37], v[28:29]
	v_pk_add_f32 v[28:29], v[36:37], v[28:29] neg_lo:[0,1] neg_hi:[0,1]
	v_pk_mul_f32 v[36:37], v[30:31], s[66:67]
	s_nop 0
	v_pk_fma_f32 v[30:31], s[0:1], v[30:31], v[36:37] op_sel:[0,0,1] op_sel_hi:[0,1,0]
	v_pk_add_f32 v[36:37], v[10:11], v[30:31]
	v_pk_add_f32 v[10:11], v[10:11], v[30:31] neg_lo:[0,1] neg_hi:[0,1]
	v_pk_mul_f32 v[30:31], v[26:27], s[16:17]
	s_nop 0
	v_pk_fma_f32 v[26:27], s[72:73], v[26:27], v[30:31] op_sel:[0,0,1] op_sel_hi:[0,1,0]
	v_pk_add_f32 v[30:31], v[24:25], v[26:27]
	v_pk_add_f32 v[24:25], v[24:25], v[26:27] neg_lo:[0,1] neg_hi:[0,1]
	v_xor_b32_e32 v26, 0x80000000, v15
	v_mov_b32_e32 v27, v14
	v_pk_add_f32 v[14:15], v[34:35], v[26:27]
	v_pk_add_f32 v[26:27], v[34:35], v[26:27] neg_lo:[0,1] neg_hi:[0,1]
	v_pk_mul_f32 v[34:35], v[20:21], s[16:17]
	s_nop 0
	v_pk_fma_f32 v[20:21], s[72:73], v[20:21], v[34:35] op_sel:[0,0,1] op_sel_hi:[0,1,0] neg_lo:[0,1,0] neg_hi:[0,1,0]
	v_pk_add_f32 v[34:35], v[8:9], v[20:21]
	v_pk_add_f32 v[8:9], v[8:9], v[20:21] neg_lo:[0,1] neg_hi:[0,1]
	v_pk_mul_f32 v[20:21], v[22:23], s[66:67]
	s_nop 0
	v_pk_fma_f32 v[20:21], v[22:23], s[0:1], v[20:21] op_sel:[0,0,1] op_sel_hi:[1,0,0] neg_lo:[1,0,0] neg_hi:[1,0,0]
	s_lshl_b64 s[0:1], s[62:63], 2
	v_pk_add_f32 v[22:23], v[6:7], v[20:21]
	v_pk_add_f32 v[6:7], v[6:7], v[20:21] neg_lo:[0,1] neg_hi:[0,1]
	v_pk_mul_f32 v[20:21], v[2:3], s[68:69]
	s_add_u32 s0, s49, s0
	v_pk_fma_f32 v[2:3], v[2:3], s[16:17], v[20:21] op_sel:[0,0,1] op_sel_hi:[1,0,0] neg_lo:[1,0,0] neg_hi:[1,0,0]
	s_addc_u32 s1, s60, s1
	v_pk_add_f32 v[20:21], v[4:5], v[2:3]
	v_pk_add_f32 v[2:3], v[4:5], v[2:3] neg_lo:[0,1] neg_hi:[0,1]
	ds_write2_b64 v18, v[16:17], v[32:33] offset1:16
	ds_write2_b64 v18, v[36:37], v[30:31] offset0:33 offset1:49
	ds_write2_b64 v18, v[14:15], v[34:35] offset0:66 offset1:82
	ds_write2_b64 v18, v[22:23], v[20:21] offset0:99 offset1:115
	ds_write2_b64 v18, v[12:13], v[28:29] offset0:132 offset1:148
	ds_write2_b64 v18, v[10:11], v[24:25] offset0:165 offset1:181
	ds_write2_b64 v18, v[26:27], v[8:9] offset0:198 offset1:214
	ds_write2_b64 v18, v[6:7], v[2:3] offset0:231 offset1:247
	s_waitcnt lgkmcnt(0)
	s_barrier
	s_lshl_b64 s[62:63], s[64:65], 2
	v_ashrrev_i32_e32 v2, 31, v210
	s_add_u32 s62, s22, s62
	v_lshrrev_b32_e32 v2, 23, v2
	global_load_dword v30, v206, s[0:1]
	global_load_dword v20, v207, s[0:1]
	s_addc_u32 s63, s23, s63
	global_load_dword v31, v205, s[0:1]
	global_load_dword v24, v205, s[62:63]
	s_lshl_b64 s[0:1], s[64:65], 16
	v_add_u32_e32 v2, v210, v2
	s_add_u32 s0, s87, s0
	v_ashrrev_i32_e32 v2, 9, v2
	s_addc_u32 s1, s90, s1
	v_mul_i32_i24_e32 v3, 0x200, v2
	s_add_u32 s0, s0, 0x8000
	v_sub_u32_e32 v21, v210, v3
	v_lshlrev_b32_e32 v36, 13, v2
	s_addc_u32 s1, s1, 0
	v_ashrrev_i32_e32 v37, 31, v36
	v_lshlrev_b32_e32 v32, 4, v21
	v_lshl_add_u64 v[2:3], v[36:37], 1, s[0:1]
	v_ashrrev_i32_e32 v33, 31, v32
	v_lshl_add_u64 v[2:3], v[32:33], 1, v[2:3]
	global_load_dwordx4 v[10:13], v[2:3], off offset:16 nt
	global_load_dwordx4 v[14:17], v[2:3], off nt
	v_cmp_lt_i32_e32 vcc, 0, v21
	s_and_saveexec_b64 s[62:63], vcc
	s_cbranch_execz .LBB0_540
	global_load_ushort v41, v[2:3], off offset:-2
